# residual epilogues: both halves of the (1+sc) parameter row loaded together (one parameter round trip instead of two)
# baseline (speedup 1.0000x reference)
.LBB0_1191:
	s_ashr_i32 s12, s55, 31
	s_lshr_b32 s12, s12, 29
	s_add_i32 s12, s55, s12
	s_ashr_i32 s12, s12, 3
	s_mul_i32 s27, s12, 0x6000
	s_mul_hi_i32 s25, s12, 0x6000
	s_add_u32 s80, s40, s27
	s_addc_u32 s81, s41, s25
	s_add_u32 s82, s47, s27
	s_addc_u32 s83, s48, s25
	s_mov_b32 s62, 0xaaaaaaaa
	s_mov_b32 s63, 0xaaaaaaaa
	s_mov_b32 s66, 0x55555555
	s_mov_b32 s67, 0x55555555
	s_mov_b32 s32, 0x0504000c
	s_mov_b32 s61, 0x0504020c
	s_mov_b32 s98, 0x0706030c
	v_mbcnt_lo_u32_b32 v150, -1, 0
	v_mbcnt_hi_u32_b32 v150, -1, v150
	v_and_b32_e32 v150, 1, v150
	v_and_b32_e32 v149, 0x60, v194
	v_add_u32_e32 v149, v149, v194
	v_lshl_or_b32 v149, s4, 8, v149
	v_lshlrev_b32_e32 v28, 2, v149
	v_lshl_add_u32 v149, v150, 5, v149
	v_lshl_add_u32 v148, s55, 8, v192
	v_sub_u32_e32 v148, v148, v150
	v_lshl_add_u32 v148, v148, 10, v149
	v_lshlrev_b32_e32 v149, 1, v148
	global_load_dwordx4 v[176:179], v28, s[80:81] offset:0
	global_load_dwordx4 v[180:183], v28, s[80:81] offset:16
	global_load_dwordx4 v[210:213], v28, s[20:21] offset:0
	global_load_dwordx4 v[214:217], v28, s[20:21] offset:16
	global_load_dwordx4 v[184:187], v28, s[80:81] offset:128
	global_load_dwordx4 v[188:191], v28, s[80:81] offset:144
	global_load_dwordx4 v[218:221], v28, s[20:21] offset:128
	global_load_dwordx4 v[222:225], v28, s[20:21] offset:144
	global_load_dwordx4 v[226:229], v28, s[82:83] offset:0
	global_load_dwordx4 v[230:233], v28, s[82:83] offset:16
	global_load_dwordx4 v[234:237], v28, s[82:83] offset:128
	global_load_dwordx4 v[238:241], v28, s[82:83] offset:144
	s_waitcnt vmcnt(0)
	v_pk_add_f32 v[226:227], v[226:227], 1.0 op_sel_hi:[1,0]
	v_pk_add_f32 v[228:229], v[228:229], 1.0 op_sel_hi:[1,0]
	v_pk_add_f32 v[230:231], v[230:231], 1.0 op_sel_hi:[1,0]
	v_pk_add_f32 v[232:233], v[232:233], 1.0 op_sel_hi:[1,0]
	v_pk_mul_f32 v[210:211], v[210:211], v[226:227]
	v_pk_mul_f32 v[212:213], v[212:213], v[228:229]
	v_pk_mul_f32 v[214:215], v[214:215], v[230:231]
	v_pk_mul_f32 v[216:217], v[216:217], v[232:233]
	v_pk_add_f32 v[234:235], v[234:235], 1.0 op_sel_hi:[1,0]
	v_pk_add_f32 v[236:237], v[236:237], 1.0 op_sel_hi:[1,0]
	v_pk_add_f32 v[238:239], v[238:239], 1.0 op_sel_hi:[1,0]
	v_pk_add_f32 v[240:241], v[240:241], 1.0 op_sel_hi:[1,0]
	v_pk_mul_f32 v[218:219], v[218:219], v[234:235]
	v_pk_mul_f32 v[220:221], v[220:221], v[236:237]
	v_pk_mul_f32 v[222:223], v[222:223], v[238:239]
	v_pk_mul_f32 v[224:225], v[224:225], v[240:241]
	s_add_u32 s84, s58, 0x0
	s_addc_u32 s85, s59, 0
	s_add_u32 s86, s74, 0x0
	s_addc_u32 s87, s75, 0
	global_load_dwordx4 v[226:229], v149, s[84:85]
	global_load_dwordx2 v[152:153], v148, s[86:87]
	global_load_dwordx4 v[230:233], v149, s[84:85] offset:2048
	global_load_dwordx2 v[196:197], v148, s[86:87] offset:1024
	s_waitcnt vmcnt(0)
	s_mov_b64 vcc, s[66:67]
	v_cndmask_b32_dpp v32, v230, v226, vcc quad_perm:[1,0,3,2] row_mask:0xf bank_mask:0xf
	v_cndmask_b32_dpp v33, v231, v227, vcc quad_perm:[1,0,3,2] row_mask:0xf bank_mask:0xf
	v_cndmask_b32_dpp v34, v232, v228, vcc quad_perm:[1,0,3,2] row_mask:0xf bank_mask:0xf
	v_cndmask_b32_dpp v35, v233, v229, vcc quad_perm:[1,0,3,2] row_mask:0xf bank_mask:0xf
	s_mov_b64 vcc, s[62:63]
	v_cndmask_b32_dpp v230, v226, v230, vcc quad_perm:[1,0,3,2] row_mask:0xf bank_mask:0xf
	v_cndmask_b32_dpp v231, v227, v231, vcc quad_perm:[1,0,3,2] row_mask:0xf bank_mask:0xf
	v_cndmask_b32_dpp v232, v228, v232, vcc quad_perm:[1,0,3,2] row_mask:0xf bank_mask:0xf
	v_cndmask_b32_dpp v233, v229, v233, vcc quad_perm:[1,0,3,2] row_mask:0xf bank_mask:0xf
	s_mov_b64 vcc, s[66:67]
	v_cndmask_b32_dpp v36, v196, v152, vcc quad_perm:[1,0,3,2] row_mask:0xf bank_mask:0xf
	v_cndmask_b32_dpp v37, v197, v153, vcc quad_perm:[1,0,3,2] row_mask:0xf bank_mask:0xf
	s_mov_b64 vcc, s[62:63]
	v_cndmask_b32_dpp v196, v152, v196, vcc quad_perm:[1,0,3,2] row_mask:0xf bank_mask:0xf
	v_cndmask_b32_dpp v197, v153, v197, vcc quad_perm:[1,0,3,2] row_mask:0xf bank_mask:0xf
	v_perm_b32 v28, v32, v36, s32
	v_perm_b32 v29, v32, v36, s8
	v_perm_b32 v30, v33, v36, s61
	v_perm_b32 v31, v33, v36, s98
	v_pk_fma_f32 v[142:143], v[142:143], v[176:177], v[28:29]
	v_pk_fma_f32 v[144:145], v[144:145], v[178:179], v[30:31]
	v_perm_b32 v28, v34, v37, s32
	v_perm_b32 v29, v34, v37, s8
	v_perm_b32 v30, v35, v37, s61
	v_perm_b32 v31, v35, v37, s98
	v_pk_fma_f32 v[138:139], v[138:139], v[180:181], v[28:29]
	v_pk_fma_f32 v[140:141], v[140:141], v[182:183], v[30:31]
	v_perm_b32 v28, v230, v196, s32
	v_perm_b32 v29, v230, v196, s8
	v_perm_b32 v30, v231, v196, s61
	v_perm_b32 v31, v231, v196, s98
	v_pk_fma_f32 v[134:135], v[134:135], v[184:185], v[28:29]
	v_pk_fma_f32 v[136:137], v[136:137], v[186:187], v[30:31]
	v_perm_b32 v28, v232, v197, s32
	v_perm_b32 v29, v232, v197, s8
	v_perm_b32 v30, v233, v197, s61
	v_perm_b32 v31, v233, v197, s98
	v_pk_fma_f32 v[130:131], v[130:131], v[188:189], v[28:29]
	v_pk_fma_f32 v[132:133], v[132:133], v[190:191], v[30:31]
	v_mul_f32_e32 v28, v143, v143
	v_mul_f32_e32 v29, v145, v145
	v_mul_f32_e32 v30, v139, v139
	v_mul_f32_e32 v31, v141, v141
	v_fmac_f32_e32 v28, v142, v142
	v_fmac_f32_e32 v29, v144, v144
	v_fmac_f32_e32 v30, v138, v138
	v_fmac_f32_e32 v31, v140, v140
	v_add_f32_e32 v28, v28, v29
	v_add_f32_e32 v30, v30, v31
	v_add_f32_e32 v151, v28, v30
	v_add_u32_e32 v28, 0x80, v142
	v_add_u32_e32 v29, 0x80, v143
	v_add_u32_e32 v30, 0x80, v144
	v_add_u32_e32 v31, 0x80, v145
	v_perm_b32 v32, v29, v28, s78
	v_perm_b32 v33, v31, v30, s78
	v_perm_b32 v26, v29, v28, s79
	v_perm_b32 v27, v31, v30, s79
	v_perm_b32 v40, v27, v26, s60
	v_add_u32_e32 v28, 0x80, v138
	v_add_u32_e32 v29, 0x80, v139
	v_add_u32_e32 v30, 0x80, v140
	v_add_u32_e32 v31, 0x80, v141
	v_perm_b32 v34, v29, v28, s78
	v_perm_b32 v35, v31, v30, s78
	v_perm_b32 v26, v29, v28, s79
	v_perm_b32 v27, v31, v30, s79
	v_perm_b32 v41, v27, v26, s60
	v_mul_f32_e32 v28, v135, v135
	v_mul_f32_e32 v29, v137, v137
	v_mul_f32_e32 v30, v131, v131
	v_mul_f32_e32 v31, v133, v133
	v_fmac_f32_e32 v28, v134, v134
	v_fmac_f32_e32 v29, v136, v136
	v_fmac_f32_e32 v30, v130, v130
	v_fmac_f32_e32 v31, v132, v132
	v_add_f32_e32 v28, v28, v29
	v_add_f32_e32 v30, v30, v31
	v_add_f32_e32 v28, v28, v30
	v_add_f32_e32 v151, v151, v28
	v_add_u32_e32 v28, 0x80, v134
	v_add_u32_e32 v29, 0x80, v135
	v_add_u32_e32 v30, 0x80, v136
	v_add_u32_e32 v31, 0x80, v137
	v_perm_b32 v36, v29, v28, s78
	v_perm_b32 v37, v31, v30, s78
	v_perm_b32 v26, v29, v28, s79
	v_perm_b32 v27, v31, v30, s79
	v_perm_b32 v146, v27, v26, s60
	v_add_u32_e32 v28, 0x80, v130
	v_add_u32_e32 v29, 0x80, v131
	v_add_u32_e32 v30, 0x80, v132
	v_add_u32_e32 v31, 0x80, v133
	v_perm_b32 v38, v29, v28, s78
	v_perm_b32 v39, v31, v30, s78
	v_perm_b32 v26, v29, v28, s79
	v_perm_b32 v27, v31, v30, s79
	v_perm_b32 v147, v27, v26, s60
	s_mov_b64 vcc, s[66:67]
	v_cndmask_b32_dpp v226, v36, v32, vcc quad_perm:[1,0,3,2] row_mask:0xf bank_mask:0xf
	v_cndmask_b32_dpp v227, v37, v33, vcc quad_perm:[1,0,3,2] row_mask:0xf bank_mask:0xf
	v_cndmask_b32_dpp v228, v38, v34, vcc quad_perm:[1,0,3,2] row_mask:0xf bank_mask:0xf
	v_cndmask_b32_dpp v229, v39, v35, vcc quad_perm:[1,0,3,2] row_mask:0xf bank_mask:0xf
	s_mov_b64 vcc, s[62:63]
	v_cndmask_b32_dpp v36, v32, v36, vcc quad_perm:[1,0,3,2] row_mask:0xf bank_mask:0xf
	v_cndmask_b32_dpp v37, v33, v37, vcc quad_perm:[1,0,3,2] row_mask:0xf bank_mask:0xf
	v_cndmask_b32_dpp v38, v34, v38, vcc quad_perm:[1,0,3,2] row_mask:0xf bank_mask:0xf
	v_cndmask_b32_dpp v39, v35, v39, vcc quad_perm:[1,0,3,2] row_mask:0xf bank_mask:0xf
	s_mov_b64 vcc, s[66:67]
	v_cndmask_b32_dpp v230, v146, v40, vcc quad_perm:[1,0,3,2] row_mask:0xf bank_mask:0xf
	v_cndmask_b32_dpp v231, v147, v41, vcc quad_perm:[1,0,3,2] row_mask:0xf bank_mask:0xf
	s_mov_b64 vcc, s[62:63]
	v_cndmask_b32_dpp v146, v40, v146, vcc quad_perm:[1,0,3,2] row_mask:0xf bank_mask:0xf
	v_cndmask_b32_dpp v147, v41, v147, vcc quad_perm:[1,0,3,2] row_mask:0xf bank_mask:0xf
	s_add_u32 s88, s58, 0x0
	s_addc_u32 s89, s59, 0
	s_add_u32 s90, s74, 0x0
	s_addc_u32 s91, s75, 0
	global_store_dwordx4 v149, v[226:229], s[88:89]
	global_store_dwordx4 v149, v[36:39], s[88:89] offset:2048
	global_store_dwordx2 v148, v[230:231], s[90:91]
	global_store_dwordx2 v148, v[146:147], s[90:91] offset:1024
	s_add_u32 s92, s96, 0x0
	s_addc_u32 s93, s97, 0
	v_pk_mul_f32 v[142:143], v[210:211], v[142:143]
	v_pk_mul_f32 v[144:145], v[212:213], v[144:145]
	v_pk_mul_f32 v[138:139], v[214:215], v[138:139]
	v_pk_mul_f32 v[140:141], v[216:217], v[140:141]
	v_cvt_pk_bf16_f32 v32, v142, v143
	v_cvt_pk_bf16_f32 v33, v144, v145
	v_cvt_pk_bf16_f32 v34, v138, v139
	v_cvt_pk_bf16_f32 v35, v140, v141
	v_pk_mul_f32 v[134:135], v[218:219], v[134:135]
	v_pk_mul_f32 v[136:137], v[220:221], v[136:137]
	v_pk_mul_f32 v[130:131], v[222:223], v[130:131]
	v_pk_mul_f32 v[132:133], v[224:225], v[132:133]
	v_cvt_pk_bf16_f32 v36, v134, v135
	v_cvt_pk_bf16_f32 v37, v136, v137
	v_cvt_pk_bf16_f32 v38, v130, v131
	v_cvt_pk_bf16_f32 v39, v132, v133
	s_mov_b64 vcc, s[66:67]
	v_cndmask_b32_dpp v226, v36, v32, vcc quad_perm:[1,0,3,2] row_mask:0xf bank_mask:0xf
	v_cndmask_b32_dpp v227, v37, v33, vcc quad_perm:[1,0,3,2] row_mask:0xf bank_mask:0xf
	v_cndmask_b32_dpp v228, v38, v34, vcc quad_perm:[1,0,3,2] row_mask:0xf bank_mask:0xf
	v_cndmask_b32_dpp v229, v39, v35, vcc quad_perm:[1,0,3,2] row_mask:0xf bank_mask:0xf
	s_mov_b64 vcc, s[62:63]
	v_cndmask_b32_dpp v36, v32, v36, vcc quad_perm:[1,0,3,2] row_mask:0xf bank_mask:0xf
	v_cndmask_b32_dpp v37, v33, v37, vcc quad_perm:[1,0,3,2] row_mask:0xf bank_mask:0xf
	v_cndmask_b32_dpp v38, v34, v38, vcc quad_perm:[1,0,3,2] row_mask:0xf bank_mask:0xf
	v_cndmask_b32_dpp v39, v35, v39, vcc quad_perm:[1,0,3,2] row_mask:0xf bank_mask:0xf
	global_store_dwordx4 v149, v[226:229], s[92:93]
	global_store_dwordx4 v149, v[36:39], s[92:93] offset:2048
	v_mov_b32_e32 v130, v151
	s_add_u32 s84, s58, 0x8000
	s_addc_u32 s85, s59, 0
	s_add_u32 s86, s74, 0x4000
	s_addc_u32 s87, s75, 0
	global_load_dwordx4 v[132:135], v149, s[84:85]
	global_load_dwordx2 v[136:137], v148, s[86:87]
	global_load_dwordx4 v[138:141], v149, s[84:85] offset:2048
	global_load_dwordx2 v[142:143], v148, s[86:87] offset:1024
	s_add_u32 s84, s58, 0x10000
	s_addc_u32 s85, s59, 0
	s_add_u32 s86, s74, 0x8000
	s_addc_u32 s87, s75, 0
	global_load_dwordx4 v[226:229], v149, s[84:85]
	global_load_dwordx2 v[144:145], v148, s[86:87]
	global_load_dwordx4 v[230:233], v149, s[84:85] offset:2048
	global_load_dwordx2 v[152:153], v148, s[86:87] offset:1024
	s_waitcnt vmcnt(4)
	s_mov_b64 vcc, s[66:67]
	v_cndmask_b32_dpp v32, v138, v132, vcc quad_perm:[1,0,3,2] row_mask:0xf bank_mask:0xf
	v_cndmask_b32_dpp v33, v139, v133, vcc quad_perm:[1,0,3,2] row_mask:0xf bank_mask:0xf
	v_cndmask_b32_dpp v34, v140, v134, vcc quad_perm:[1,0,3,2] row_mask:0xf bank_mask:0xf
	v_cndmask_b32_dpp v35, v141, v135, vcc quad_perm:[1,0,3,2] row_mask:0xf bank_mask:0xf
	s_mov_b64 vcc, s[62:63]
	v_cndmask_b32_dpp v138, v132, v138, vcc quad_perm:[1,0,3,2] row_mask:0xf bank_mask:0xf
	v_cndmask_b32_dpp v139, v133, v139, vcc quad_perm:[1,0,3,2] row_mask:0xf bank_mask:0xf
	v_cndmask_b32_dpp v140, v134, v140, vcc quad_perm:[1,0,3,2] row_mask:0xf bank_mask:0xf
	v_cndmask_b32_dpp v141, v135, v141, vcc quad_perm:[1,0,3,2] row_mask:0xf bank_mask:0xf
	s_mov_b64 vcc, s[66:67]
	v_cndmask_b32_dpp v36, v142, v136, vcc quad_perm:[1,0,3,2] row_mask:0xf bank_mask:0xf
	v_cndmask_b32_dpp v37, v143, v137, vcc quad_perm:[1,0,3,2] row_mask:0xf bank_mask:0xf
	s_mov_b64 vcc, s[62:63]
	v_cndmask_b32_dpp v142, v136, v142, vcc quad_perm:[1,0,3,2] row_mask:0xf bank_mask:0xf
	v_cndmask_b32_dpp v143, v137, v143, vcc quad_perm:[1,0,3,2] row_mask:0xf bank_mask:0xf
	v_perm_b32 v28, v32, v36, s32
	v_perm_b32 v29, v32, v36, s8
	v_perm_b32 v30, v33, v36, s61
	v_perm_b32 v31, v33, v36, s98
	v_pk_fma_f32 v[126:127], v[126:127], v[176:177], v[28:29]
	v_pk_fma_f32 v[128:129], v[128:129], v[178:179], v[30:31]
	v_perm_b32 v28, v34, v37, s32
	v_perm_b32 v29, v34, v37, s8
	v_perm_b32 v30, v35, v37, s61
	v_perm_b32 v31, v35, v37, s98
	v_pk_fma_f32 v[122:123], v[122:123], v[180:181], v[28:29]
	v_pk_fma_f32 v[124:125], v[124:125], v[182:183], v[30:31]
	v_perm_b32 v28, v138, v142, s32
	v_perm_b32 v29, v138, v142, s8
	v_perm_b32 v30, v139, v142, s61
	v_perm_b32 v31, v139, v142, s98
	v_pk_fma_f32 v[118:119], v[118:119], v[184:185], v[28:29]
	v_pk_fma_f32 v[120:121], v[120:121], v[186:187], v[30:31]
	v_perm_b32 v28, v140, v143, s32
	v_perm_b32 v29, v140, v143, s8
	v_perm_b32 v30, v141, v143, s61
	v_perm_b32 v31, v141, v143, s98
	v_pk_fma_f32 v[114:115], v[114:115], v[188:189], v[28:29]
	v_pk_fma_f32 v[116:117], v[116:117], v[190:191], v[30:31]
	v_mul_f32_e32 v28, v127, v127
	v_mul_f32_e32 v29, v129, v129
	v_mul_f32_e32 v30, v123, v123
	v_mul_f32_e32 v31, v125, v125
	v_fmac_f32_e32 v28, v126, v126
	v_fmac_f32_e32 v29, v128, v128
	v_fmac_f32_e32 v30, v122, v122
	v_fmac_f32_e32 v31, v124, v124
	v_add_f32_e32 v28, v28, v29
	v_add_f32_e32 v30, v30, v31
	v_add_f32_e32 v151, v28, v30
	v_add_u32_e32 v28, 0x80, v126
	v_add_u32_e32 v29, 0x80, v127
	v_add_u32_e32 v30, 0x80, v128
	v_add_u32_e32 v31, 0x80, v129
	v_perm_b32 v32, v29, v28, s78
	v_perm_b32 v33, v31, v30, s78
	v_perm_b32 v26, v29, v28, s79
	v_perm_b32 v27, v31, v30, s79
	v_perm_b32 v40, v27, v26, s60
	v_add_u32_e32 v28, 0x80, v122
	v_add_u32_e32 v29, 0x80, v123
	v_add_u32_e32 v30, 0x80, v124
	v_add_u32_e32 v31, 0x80, v125
	v_perm_b32 v34, v29, v28, s78
	v_perm_b32 v35, v31, v30, s78
	v_perm_b32 v26, v29, v28, s79
	v_perm_b32 v27, v31, v30, s79
	v_perm_b32 v41, v27, v26, s60
	v_mul_f32_e32 v28, v119, v119
	v_mul_f32_e32 v29, v121, v121
	v_mul_f32_e32 v30, v115, v115
	v_mul_f32_e32 v31, v117, v117
	v_fmac_f32_e32 v28, v118, v118
	v_fmac_f32_e32 v29, v120, v120
	v_fmac_f32_e32 v30, v114, v114
	v_fmac_f32_e32 v31, v116, v116
	v_add_f32_e32 v28, v28, v29
	v_add_f32_e32 v30, v30, v31
	v_add_f32_e32 v28, v28, v30
	v_add_f32_e32 v151, v151, v28
	v_add_u32_e32 v28, 0x80, v118
	v_add_u32_e32 v29, 0x80, v119
	v_add_u32_e32 v30, 0x80, v120
	v_add_u32_e32 v31, 0x80, v121
	v_perm_b32 v36, v29, v28, s78
	v_perm_b32 v37, v31, v30, s78
	v_perm_b32 v26, v29, v28, s79
	v_perm_b32 v27, v31, v30, s79
	v_perm_b32 v146, v27, v26, s60
	v_add_u32_e32 v28, 0x80, v114
	v_add_u32_e32 v29, 0x80, v115
	v_add_u32_e32 v30, 0x80, v116
	v_add_u32_e32 v31, 0x80, v117
	v_perm_b32 v38, v29, v28, s78
	v_perm_b32 v39, v31, v30, s78
	v_perm_b32 v26, v29, v28, s79
	v_perm_b32 v27, v31, v30, s79
	v_perm_b32 v147, v27, v26, s60
	s_mov_b64 vcc, s[66:67]
	v_cndmask_b32_dpp v132, v36, v32, vcc quad_perm:[1,0,3,2] row_mask:0xf bank_mask:0xf
	v_cndmask_b32_dpp v133, v37, v33, vcc quad_perm:[1,0,3,2] row_mask:0xf bank_mask:0xf
	v_cndmask_b32_dpp v134, v38, v34, vcc quad_perm:[1,0,3,2] row_mask:0xf bank_mask:0xf
	v_cndmask_b32_dpp v135, v39, v35, vcc quad_perm:[1,0,3,2] row_mask:0xf bank_mask:0xf
	s_mov_b64 vcc, s[62:63]
	v_cndmask_b32_dpp v36, v32, v36, vcc quad_perm:[1,0,3,2] row_mask:0xf bank_mask:0xf
	v_cndmask_b32_dpp v37, v33, v37, vcc quad_perm:[1,0,3,2] row_mask:0xf bank_mask:0xf
	v_cndmask_b32_dpp v38, v34, v38, vcc quad_perm:[1,0,3,2] row_mask:0xf bank_mask:0xf
	v_cndmask_b32_dpp v39, v35, v39, vcc quad_perm:[1,0,3,2] row_mask:0xf bank_mask:0xf
	s_mov_b64 vcc, s[66:67]
	v_cndmask_b32_dpp v138, v146, v40, vcc quad_perm:[1,0,3,2] row_mask:0xf bank_mask:0xf
	v_cndmask_b32_dpp v139, v147, v41, vcc quad_perm:[1,0,3,2] row_mask:0xf bank_mask:0xf
	s_mov_b64 vcc, s[62:63]
	v_cndmask_b32_dpp v146, v40, v146, vcc quad_perm:[1,0,3,2] row_mask:0xf bank_mask:0xf
	v_cndmask_b32_dpp v147, v41, v147, vcc quad_perm:[1,0,3,2] row_mask:0xf bank_mask:0xf
	s_add_u32 s88, s58, 0x8000
	s_addc_u32 s89, s59, 0
	s_add_u32 s90, s74, 0x4000
	s_addc_u32 s91, s75, 0
	global_store_dwordx4 v149, v[132:135], s[88:89]
	global_store_dwordx4 v149, v[36:39], s[88:89] offset:2048
	global_store_dwordx2 v148, v[138:139], s[90:91]
	global_store_dwordx2 v148, v[146:147], s[90:91] offset:1024
	s_add_u32 s92, s96, 0x8000
	s_addc_u32 s93, s97, 0
	v_pk_mul_f32 v[126:127], v[210:211], v[126:127]
	v_pk_mul_f32 v[128:129], v[212:213], v[128:129]
	v_pk_mul_f32 v[122:123], v[214:215], v[122:123]
	v_pk_mul_f32 v[124:125], v[216:217], v[124:125]
	v_cvt_pk_bf16_f32 v32, v126, v127
	v_cvt_pk_bf16_f32 v33, v128, v129
	v_cvt_pk_bf16_f32 v34, v122, v123
	v_cvt_pk_bf16_f32 v35, v124, v125
	v_pk_mul_f32 v[118:119], v[218:219], v[118:119]
	v_pk_mul_f32 v[120:121], v[220:221], v[120:121]
	v_pk_mul_f32 v[114:115], v[222:223], v[114:115]
	v_pk_mul_f32 v[116:117], v[224:225], v[116:117]
	v_cvt_pk_bf16_f32 v36, v118, v119
	v_cvt_pk_bf16_f32 v37, v120, v121
	v_cvt_pk_bf16_f32 v38, v114, v115
	v_cvt_pk_bf16_f32 v39, v116, v117
	s_mov_b64 vcc, s[66:67]
	v_cndmask_b32_dpp v132, v36, v32, vcc quad_perm:[1,0,3,2] row_mask:0xf bank_mask:0xf
	v_cndmask_b32_dpp v133, v37, v33, vcc quad_perm:[1,0,3,2] row_mask:0xf bank_mask:0xf
	v_cndmask_b32_dpp v134, v38, v34, vcc quad_perm:[1,0,3,2] row_mask:0xf bank_mask:0xf
	v_cndmask_b32_dpp v135, v39, v35, vcc quad_perm:[1,0,3,2] row_mask:0xf bank_mask:0xf
	s_mov_b64 vcc, s[62:63]
	v_cndmask_b32_dpp v36, v32, v36, vcc quad_perm:[1,0,3,2] row_mask:0xf bank_mask:0xf
	v_cndmask_b32_dpp v37, v33, v37, vcc quad_perm:[1,0,3,2] row_mask:0xf bank_mask:0xf
	v_cndmask_b32_dpp v38, v34, v38, vcc quad_perm:[1,0,3,2] row_mask:0xf bank_mask:0xf
	v_cndmask_b32_dpp v39, v35, v39, vcc quad_perm:[1,0,3,2] row_mask:0xf bank_mask:0xf
	global_store_dwordx4 v149, v[132:135], s[92:93]
	global_store_dwordx4 v149, v[36:39], s[92:93] offset:2048
	v_mov_b32_e32 v114, v151
	s_add_u32 s84, s58, 0x18000
	s_addc_u32 s85, s59, 0
	s_add_u32 s86, s74, 0xc000
	s_addc_u32 s87, s75, 0
	global_load_dwordx4 v[116:119], v149, s[84:85]
	global_load_dwordx2 v[120:121], v148, s[86:87]
	global_load_dwordx4 v[122:125], v149, s[84:85] offset:2048
	global_load_dwordx2 v[126:127], v148, s[86:87] offset:1024
	s_waitcnt vmcnt(10)
	s_mov_b64 vcc, s[66:67]
	v_cndmask_b32_dpp v32, v230, v226, vcc quad_perm:[1,0,3,2] row_mask:0xf bank_mask:0xf
	v_cndmask_b32_dpp v33, v231, v227, vcc quad_perm:[1,0,3,2] row_mask:0xf bank_mask:0xf
	v_cndmask_b32_dpp v34, v232, v228, vcc quad_perm:[1,0,3,2] row_mask:0xf bank_mask:0xf
	v_cndmask_b32_dpp v35, v233, v229, vcc quad_perm:[1,0,3,2] row_mask:0xf bank_mask:0xf
	s_mov_b64 vcc, s[62:63]
	v_cndmask_b32_dpp v230, v226, v230, vcc quad_perm:[1,0,3,2] row_mask:0xf bank_mask:0xf
	v_cndmask_b32_dpp v231, v227, v231, vcc quad_perm:[1,0,3,2] row_mask:0xf bank_mask:0xf
	v_cndmask_b32_dpp v232, v228, v232, vcc quad_perm:[1,0,3,2] row_mask:0xf bank_mask:0xf
	v_cndmask_b32_dpp v233, v229, v233, vcc quad_perm:[1,0,3,2] row_mask:0xf bank_mask:0xf
	s_mov_b64 vcc, s[66:67]
	v_cndmask_b32_dpp v36, v152, v144, vcc quad_perm:[1,0,3,2] row_mask:0xf bank_mask:0xf
	v_cndmask_b32_dpp v37, v153, v145, vcc quad_perm:[1,0,3,2] row_mask:0xf bank_mask:0xf
	s_mov_b64 vcc, s[62:63]
	v_cndmask_b32_dpp v152, v144, v152, vcc quad_perm:[1,0,3,2] row_mask:0xf bank_mask:0xf
	v_cndmask_b32_dpp v153, v145, v153, vcc quad_perm:[1,0,3,2] row_mask:0xf bank_mask:0xf
	v_perm_b32 v28, v32, v36, s32
	v_perm_b32 v29, v32, v36, s8
	v_perm_b32 v30, v33, v36, s61
	v_perm_b32 v31, v33, v36, s98
	v_pk_fma_f32 v[110:111], v[110:111], v[176:177], v[28:29]
	v_pk_fma_f32 v[112:113], v[112:113], v[178:179], v[30:31]
	v_perm_b32 v28, v34, v37, s32
	v_perm_b32 v29, v34, v37, s8
	v_perm_b32 v30, v35, v37, s61
	v_perm_b32 v31, v35, v37, s98
	v_pk_fma_f32 v[106:107], v[106:107], v[180:181], v[28:29]
	v_pk_fma_f32 v[108:109], v[108:109], v[182:183], v[30:31]
	v_perm_b32 v28, v230, v152, s32
	v_perm_b32 v29, v230, v152, s8
	v_perm_b32 v30, v231, v152, s61
	v_perm_b32 v31, v231, v152, s98
	v_pk_fma_f32 v[102:103], v[102:103], v[184:185], v[28:29]
	v_pk_fma_f32 v[104:105], v[104:105], v[186:187], v[30:31]
	v_perm_b32 v28, v232, v153, s32
	v_perm_b32 v29, v232, v153, s8
	v_perm_b32 v30, v233, v153, s61
	v_perm_b32 v31, v233, v153, s98
	v_pk_fma_f32 v[98:99], v[98:99], v[188:189], v[28:29]
	v_pk_fma_f32 v[100:101], v[100:101], v[190:191], v[30:31]
	v_mul_f32_e32 v28, v111, v111
	v_mul_f32_e32 v29, v113, v113
	v_mul_f32_e32 v30, v107, v107
	v_mul_f32_e32 v31, v109, v109
	v_fmac_f32_e32 v28, v110, v110
	v_fmac_f32_e32 v29, v112, v112
	v_fmac_f32_e32 v30, v106, v106
	v_fmac_f32_e32 v31, v108, v108
	v_add_f32_e32 v28, v28, v29
	v_add_f32_e32 v30, v30, v31
	v_add_f32_e32 v151, v28, v30
	v_add_u32_e32 v28, 0x80, v110
	v_add_u32_e32 v29, 0x80, v111
	v_add_u32_e32 v30, 0x80, v112
	v_add_u32_e32 v31, 0x80, v113
	v_perm_b32 v32, v29, v28, s78
	v_perm_b32 v33, v31, v30, s78
	v_perm_b32 v26, v29, v28, s79
	v_perm_b32 v27, v31, v30, s79
	v_perm_b32 v40, v27, v26, s60
	v_add_u32_e32 v28, 0x80, v106
	v_add_u32_e32 v29, 0x80, v107
	v_add_u32_e32 v30, 0x80, v108
	v_add_u32_e32 v31, 0x80, v109
	v_perm_b32 v34, v29, v28, s78
	v_perm_b32 v35, v31, v30, s78
	v_perm_b32 v26, v29, v28, s79
	v_perm_b32 v27, v31, v30, s79
	v_perm_b32 v41, v27, v26, s60
	v_mul_f32_e32 v28, v103, v103
	v_mul_f32_e32 v29, v105, v105
	v_mul_f32_e32 v30, v99, v99
	v_mul_f32_e32 v31, v101, v101
	v_fmac_f32_e32 v28, v102, v102
	v_fmac_f32_e32 v29, v104, v104
	v_fmac_f32_e32 v30, v98, v98
	v_fmac_f32_e32 v31, v100, v100
	v_add_f32_e32 v28, v28, v29
	v_add_f32_e32 v30, v30, v31
	v_add_f32_e32 v28, v28, v30
	v_add_f32_e32 v151, v151, v28
	v_add_u32_e32 v28, 0x80, v102
	v_add_u32_e32 v29, 0x80, v103
	v_add_u32_e32 v30, 0x80, v104
	v_add_u32_e32 v31, 0x80, v105
	v_perm_b32 v36, v29, v28, s78
	v_perm_b32 v37, v31, v30, s78
	v_perm_b32 v26, v29, v28, s79
	v_perm_b32 v27, v31, v30, s79
	v_perm_b32 v146, v27, v26, s60
	v_add_u32_e32 v28, 0x80, v98
	v_add_u32_e32 v29, 0x80, v99
	v_add_u32_e32 v30, 0x80, v100
	v_add_u32_e32 v31, 0x80, v101
	v_perm_b32 v38, v29, v28, s78
	v_perm_b32 v39, v31, v30, s78
	v_perm_b32 v26, v29, v28, s79
	v_perm_b32 v27, v31, v30, s79
	v_perm_b32 v147, v27, v26, s60
	s_mov_b64 vcc, s[66:67]
	v_cndmask_b32_dpp v226, v36, v32, vcc quad_perm:[1,0,3,2] row_mask:0xf bank_mask:0xf
	v_cndmask_b32_dpp v227, v37, v33, vcc quad_perm:[1,0,3,2] row_mask:0xf bank_mask:0xf
	v_cndmask_b32_dpp v228, v38, v34, vcc quad_perm:[1,0,3,2] row_mask:0xf bank_mask:0xf
	v_cndmask_b32_dpp v229, v39, v35, vcc quad_perm:[1,0,3,2] row_mask:0xf bank_mask:0xf
	s_mov_b64 vcc, s[62:63]
	v_cndmask_b32_dpp v36, v32, v36, vcc quad_perm:[1,0,3,2] row_mask:0xf bank_mask:0xf
	v_cndmask_b32_dpp v37, v33, v37, vcc quad_perm:[1,0,3,2] row_mask:0xf bank_mask:0xf
	v_cndmask_b32_dpp v38, v34, v38, vcc quad_perm:[1,0,3,2] row_mask:0xf bank_mask:0xf
	v_cndmask_b32_dpp v39, v35, v39, vcc quad_perm:[1,0,3,2] row_mask:0xf bank_mask:0xf
	s_mov_b64 vcc, s[66:67]
	v_cndmask_b32_dpp v230, v146, v40, vcc quad_perm:[1,0,3,2] row_mask:0xf bank_mask:0xf
	v_cndmask_b32_dpp v231, v147, v41, vcc quad_perm:[1,0,3,2] row_mask:0xf bank_mask:0xf
	s_mov_b64 vcc, s[62:63]
	v_cndmask_b32_dpp v146, v40, v146, vcc quad_perm:[1,0,3,2] row_mask:0xf bank_mask:0xf
	v_cndmask_b32_dpp v147, v41, v147, vcc quad_perm:[1,0,3,2] row_mask:0xf bank_mask:0xf
	s_add_u32 s88, s58, 0x10000
	s_addc_u32 s89, s59, 0
	s_add_u32 s90, s74, 0x8000
	s_addc_u32 s91, s75, 0
	global_store_dwordx4 v149, v[226:229], s[88:89]
	global_store_dwordx4 v149, v[36:39], s[88:89] offset:2048
	global_store_dwordx2 v148, v[230:231], s[90:91]
	global_store_dwordx2 v148, v[146:147], s[90:91] offset:1024
	s_add_u32 s92, s96, 0x10000
	s_addc_u32 s93, s97, 0
	v_pk_mul_f32 v[110:111], v[210:211], v[110:111]
	v_pk_mul_f32 v[112:113], v[212:213], v[112:113]
	v_pk_mul_f32 v[106:107], v[214:215], v[106:107]
	v_pk_mul_f32 v[108:109], v[216:217], v[108:109]
	v_cvt_pk_bf16_f32 v32, v110, v111
	v_cvt_pk_bf16_f32 v33, v112, v113
	v_cvt_pk_bf16_f32 v34, v106, v107
	v_cvt_pk_bf16_f32 v35, v108, v109
	v_pk_mul_f32 v[102:103], v[218:219], v[102:103]
	v_pk_mul_f32 v[104:105], v[220:221], v[104:105]
	v_pk_mul_f32 v[98:99], v[222:223], v[98:99]
	v_pk_mul_f32 v[100:101], v[224:225], v[100:101]
	v_cvt_pk_bf16_f32 v36, v102, v103
	v_cvt_pk_bf16_f32 v37, v104, v105
	v_cvt_pk_bf16_f32 v38, v98, v99
	v_cvt_pk_bf16_f32 v39, v100, v101
	s_mov_b64 vcc, s[66:67]
	v_cndmask_b32_dpp v226, v36, v32, vcc quad_perm:[1,0,3,2] row_mask:0xf bank_mask:0xf
	v_cndmask_b32_dpp v227, v37, v33, vcc quad_perm:[1,0,3,2] row_mask:0xf bank_mask:0xf
	v_cndmask_b32_dpp v228, v38, v34, vcc quad_perm:[1,0,3,2] row_mask:0xf bank_mask:0xf
	v_cndmask_b32_dpp v229, v39, v35, vcc quad_perm:[1,0,3,2] row_mask:0xf bank_mask:0xf
	s_mov_b64 vcc, s[62:63]
	v_cndmask_b32_dpp v36, v32, v36, vcc quad_perm:[1,0,3,2] row_mask:0xf bank_mask:0xf
	v_cndmask_b32_dpp v37, v33, v37, vcc quad_perm:[1,0,3,2] row_mask:0xf bank_mask:0xf
	v_cndmask_b32_dpp v38, v34, v38, vcc quad_perm:[1,0,3,2] row_mask:0xf bank_mask:0xf
	v_cndmask_b32_dpp v39, v35, v39, vcc quad_perm:[1,0,3,2] row_mask:0xf bank_mask:0xf
	global_store_dwordx4 v149, v[226:229], s[92:93]
	global_store_dwordx4 v149, v[36:39], s[92:93] offset:2048
	v_mov_b32_e32 v98, v151
	s_add_u32 s84, s58, 0x40000
	s_addc_u32 s85, s59, 0
	s_add_u32 s86, s74, 0x20000
	s_addc_u32 s87, s75, 0
	global_load_dwordx4 v[100:103], v149, s[84:85]
	global_load_dwordx2 v[104:105], v148, s[86:87]
	global_load_dwordx4 v[106:109], v149, s[84:85] offset:2048
	global_load_dwordx2 v[110:111], v148, s[86:87] offset:1024
	s_waitcnt vmcnt(10)
	s_mov_b64 vcc, s[66:67]
	v_cndmask_b32_dpp v32, v122, v116, vcc quad_perm:[1,0,3,2] row_mask:0xf bank_mask:0xf
	v_cndmask_b32_dpp v33, v123, v117, vcc quad_perm:[1,0,3,2] row_mask:0xf bank_mask:0xf
	v_cndmask_b32_dpp v34, v124, v118, vcc quad_perm:[1,0,3,2] row_mask:0xf bank_mask:0xf
	v_cndmask_b32_dpp v35, v125, v119, vcc quad_perm:[1,0,3,2] row_mask:0xf bank_mask:0xf
	s_mov_b64 vcc, s[62:63]
	v_cndmask_b32_dpp v122, v116, v122, vcc quad_perm:[1,0,3,2] row_mask:0xf bank_mask:0xf
	v_cndmask_b32_dpp v123, v117, v123, vcc quad_perm:[1,0,3,2] row_mask:0xf bank_mask:0xf
	v_cndmask_b32_dpp v124, v118, v124, vcc quad_perm:[1,0,3,2] row_mask:0xf bank_mask:0xf
	v_cndmask_b32_dpp v125, v119, v125, vcc quad_perm:[1,0,3,2] row_mask:0xf bank_mask:0xf
	s_mov_b64 vcc, s[66:67]
	v_cndmask_b32_dpp v36, v126, v120, vcc quad_perm:[1,0,3,2] row_mask:0xf bank_mask:0xf
	v_cndmask_b32_dpp v37, v127, v121, vcc quad_perm:[1,0,3,2] row_mask:0xf bank_mask:0xf
	s_mov_b64 vcc, s[62:63]
	v_cndmask_b32_dpp v126, v120, v126, vcc quad_perm:[1,0,3,2] row_mask:0xf bank_mask:0xf
	v_cndmask_b32_dpp v127, v121, v127, vcc quad_perm:[1,0,3,2] row_mask:0xf bank_mask:0xf
	v_perm_b32 v28, v32, v36, s32
	v_perm_b32 v29, v32, v36, s8
	v_perm_b32 v30, v33, v36, s61
	v_perm_b32 v31, v33, v36, s98
	v_pk_fma_f32 v[94:95], v[94:95], v[176:177], v[28:29]
	v_pk_fma_f32 v[96:97], v[96:97], v[178:179], v[30:31]
	v_perm_b32 v28, v34, v37, s32
	v_perm_b32 v29, v34, v37, s8
	v_perm_b32 v30, v35, v37, s61
	v_perm_b32 v31, v35, v37, s98
	v_pk_fma_f32 v[90:91], v[90:91], v[180:181], v[28:29]
	v_pk_fma_f32 v[92:93], v[92:93], v[182:183], v[30:31]
	v_perm_b32 v28, v122, v126, s32
	v_perm_b32 v29, v122, v126, s8
	v_perm_b32 v30, v123, v126, s61
	v_perm_b32 v31, v123, v126, s98
	v_pk_fma_f32 v[86:87], v[86:87], v[184:185], v[28:29]
	v_pk_fma_f32 v[88:89], v[88:89], v[186:187], v[30:31]
	v_perm_b32 v28, v124, v127, s32
	v_perm_b32 v29, v124, v127, s8
	v_perm_b32 v30, v125, v127, s61
	v_perm_b32 v31, v125, v127, s98
	v_pk_fma_f32 v[82:83], v[82:83], v[188:189], v[28:29]
	v_pk_fma_f32 v[84:85], v[84:85], v[190:191], v[30:31]
	v_mul_f32_e32 v28, v95, v95
	v_mul_f32_e32 v29, v97, v97
	v_mul_f32_e32 v30, v91, v91
	v_mul_f32_e32 v31, v93, v93
	v_fmac_f32_e32 v28, v94, v94
	v_fmac_f32_e32 v29, v96, v96
	v_fmac_f32_e32 v30, v90, v90
	v_fmac_f32_e32 v31, v92, v92
	v_add_f32_e32 v28, v28, v29
	v_add_f32_e32 v30, v30, v31
	v_add_f32_e32 v151, v28, v30
	v_add_u32_e32 v28, 0x80, v94
	v_add_u32_e32 v29, 0x80, v95
	v_add_u32_e32 v30, 0x80, v96
	v_add_u32_e32 v31, 0x80, v97
	v_perm_b32 v32, v29, v28, s78
	v_perm_b32 v33, v31, v30, s78
	v_perm_b32 v26, v29, v28, s79
	v_perm_b32 v27, v31, v30, s79
	v_perm_b32 v40, v27, v26, s60
	v_add_u32_e32 v28, 0x80, v90
	v_add_u32_e32 v29, 0x80, v91
	v_add_u32_e32 v30, 0x80, v92
	v_add_u32_e32 v31, 0x80, v93
	v_perm_b32 v34, v29, v28, s78
	v_perm_b32 v35, v31, v30, s78
	v_perm_b32 v26, v29, v28, s79
	v_perm_b32 v27, v31, v30, s79
	v_perm_b32 v41, v27, v26, s60
	v_mul_f32_e32 v28, v87, v87
	v_mul_f32_e32 v29, v89, v89
	v_mul_f32_e32 v30, v83, v83
	v_mul_f32_e32 v31, v85, v85
	v_fmac_f32_e32 v28, v86, v86
	v_fmac_f32_e32 v29, v88, v88
	v_fmac_f32_e32 v30, v82, v82
	v_fmac_f32_e32 v31, v84, v84
	v_add_f32_e32 v28, v28, v29
	v_add_f32_e32 v30, v30, v31
	v_add_f32_e32 v28, v28, v30
	v_add_f32_e32 v151, v151, v28
	v_add_u32_e32 v28, 0x80, v86
	v_add_u32_e32 v29, 0x80, v87
	v_add_u32_e32 v30, 0x80, v88
	v_add_u32_e32 v31, 0x80, v89
	v_perm_b32 v36, v29, v28, s78
	v_perm_b32 v37, v31, v30, s78
	v_perm_b32 v26, v29, v28, s79
	v_perm_b32 v27, v31, v30, s79
	v_perm_b32 v146, v27, v26, s60
	v_add_u32_e32 v28, 0x80, v82
	v_add_u32_e32 v29, 0x80, v83
	v_add_u32_e32 v30, 0x80, v84
	v_add_u32_e32 v31, 0x80, v85
	v_perm_b32 v38, v29, v28, s78
	v_perm_b32 v39, v31, v30, s78
	v_perm_b32 v26, v29, v28, s79
	v_perm_b32 v27, v31, v30, s79
	v_perm_b32 v147, v27, v26, s60
	s_mov_b64 vcc, s[66:67]
	v_cndmask_b32_dpp v116, v36, v32, vcc quad_perm:[1,0,3,2] row_mask:0xf bank_mask:0xf
	v_cndmask_b32_dpp v117, v37, v33, vcc quad_perm:[1,0,3,2] row_mask:0xf bank_mask:0xf
	v_cndmask_b32_dpp v118, v38, v34, vcc quad_perm:[1,0,3,2] row_mask:0xf bank_mask:0xf
	v_cndmask_b32_dpp v119, v39, v35, vcc quad_perm:[1,0,3,2] row_mask:0xf bank_mask:0xf
	s_mov_b64 vcc, s[62:63]
	v_cndmask_b32_dpp v36, v32, v36, vcc quad_perm:[1,0,3,2] row_mask:0xf bank_mask:0xf
	v_cndmask_b32_dpp v37, v33, v37, vcc quad_perm:[1,0,3,2] row_mask:0xf bank_mask:0xf
	v_cndmask_b32_dpp v38, v34, v38, vcc quad_perm:[1,0,3,2] row_mask:0xf bank_mask:0xf
	v_cndmask_b32_dpp v39, v35, v39, vcc quad_perm:[1,0,3,2] row_mask:0xf bank_mask:0xf
	s_mov_b64 vcc, s[66:67]
	v_cndmask_b32_dpp v122, v146, v40, vcc quad_perm:[1,0,3,2] row_mask:0xf bank_mask:0xf
	v_cndmask_b32_dpp v123, v147, v41, vcc quad_perm:[1,0,3,2] row_mask:0xf bank_mask:0xf
	s_mov_b64 vcc, s[62:63]
	v_cndmask_b32_dpp v146, v40, v146, vcc quad_perm:[1,0,3,2] row_mask:0xf bank_mask:0xf
	v_cndmask_b32_dpp v147, v41, v147, vcc quad_perm:[1,0,3,2] row_mask:0xf bank_mask:0xf
	s_add_u32 s88, s58, 0x18000
	s_addc_u32 s89, s59, 0
	s_add_u32 s90, s74, 0xc000
	s_addc_u32 s91, s75, 0
	global_store_dwordx4 v149, v[116:119], s[88:89]
	global_store_dwordx4 v149, v[36:39], s[88:89] offset:2048
	global_store_dwordx2 v148, v[122:123], s[90:91]
	global_store_dwordx2 v148, v[146:147], s[90:91] offset:1024
	s_add_u32 s92, s96, 0x18000
	s_addc_u32 s93, s97, 0
	v_pk_mul_f32 v[94:95], v[210:211], v[94:95]
	v_pk_mul_f32 v[96:97], v[212:213], v[96:97]
	v_pk_mul_f32 v[90:91], v[214:215], v[90:91]
	v_pk_mul_f32 v[92:93], v[216:217], v[92:93]
	v_cvt_pk_bf16_f32 v32, v94, v95
	v_cvt_pk_bf16_f32 v33, v96, v97
	v_cvt_pk_bf16_f32 v34, v90, v91
	v_cvt_pk_bf16_f32 v35, v92, v93
	v_pk_mul_f32 v[86:87], v[218:219], v[86:87]
	v_pk_mul_f32 v[88:89], v[220:221], v[88:89]
	v_pk_mul_f32 v[82:83], v[222:223], v[82:83]
	v_pk_mul_f32 v[84:85], v[224:225], v[84:85]
	v_cvt_pk_bf16_f32 v36, v86, v87
	v_cvt_pk_bf16_f32 v37, v88, v89
	v_cvt_pk_bf16_f32 v38, v82, v83
	v_cvt_pk_bf16_f32 v39, v84, v85
	s_mov_b64 vcc, s[66:67]
	v_cndmask_b32_dpp v116, v36, v32, vcc quad_perm:[1,0,3,2] row_mask:0xf bank_mask:0xf
	v_cndmask_b32_dpp v117, v37, v33, vcc quad_perm:[1,0,3,2] row_mask:0xf bank_mask:0xf
	v_cndmask_b32_dpp v118, v38, v34, vcc quad_perm:[1,0,3,2] row_mask:0xf bank_mask:0xf
	v_cndmask_b32_dpp v119, v39, v35, vcc quad_perm:[1,0,3,2] row_mask:0xf bank_mask:0xf
	s_mov_b64 vcc, s[62:63]
	v_cndmask_b32_dpp v36, v32, v36, vcc quad_perm:[1,0,3,2] row_mask:0xf bank_mask:0xf
	v_cndmask_b32_dpp v37, v33, v37, vcc quad_perm:[1,0,3,2] row_mask:0xf bank_mask:0xf
	v_cndmask_b32_dpp v38, v34, v38, vcc quad_perm:[1,0,3,2] row_mask:0xf bank_mask:0xf
	v_cndmask_b32_dpp v39, v35, v39, vcc quad_perm:[1,0,3,2] row_mask:0xf bank_mask:0xf
	global_store_dwordx4 v149, v[116:119], s[92:93]
	global_store_dwordx4 v149, v[36:39], s[92:93] offset:2048
	v_mov_b32_e32 v82, v151
	s_add_u32 s84, s58, 0x48000
	s_addc_u32 s85, s59, 0
	s_add_u32 s86, s74, 0x24000
	s_addc_u32 s87, s75, 0
	global_load_dwordx4 v[84:87], v149, s[84:85]
	global_load_dwordx2 v[88:89], v148, s[86:87]
	global_load_dwordx4 v[90:93], v149, s[84:85] offset:2048
	global_load_dwordx2 v[94:95], v148, s[86:87] offset:1024
	s_waitcnt vmcnt(10)
	s_mov_b64 vcc, s[66:67]
	v_cndmask_b32_dpp v32, v106, v100, vcc quad_perm:[1,0,3,2] row_mask:0xf bank_mask:0xf
	v_cndmask_b32_dpp v33, v107, v101, vcc quad_perm:[1,0,3,2] row_mask:0xf bank_mask:0xf
	v_cndmask_b32_dpp v34, v108, v102, vcc quad_perm:[1,0,3,2] row_mask:0xf bank_mask:0xf
	v_cndmask_b32_dpp v35, v109, v103, vcc quad_perm:[1,0,3,2] row_mask:0xf bank_mask:0xf
	s_mov_b64 vcc, s[62:63]
	v_cndmask_b32_dpp v106, v100, v106, vcc quad_perm:[1,0,3,2] row_mask:0xf bank_mask:0xf
	v_cndmask_b32_dpp v107, v101, v107, vcc quad_perm:[1,0,3,2] row_mask:0xf bank_mask:0xf
	v_cndmask_b32_dpp v108, v102, v108, vcc quad_perm:[1,0,3,2] row_mask:0xf bank_mask:0xf
	v_cndmask_b32_dpp v109, v103, v109, vcc quad_perm:[1,0,3,2] row_mask:0xf bank_mask:0xf
	s_mov_b64 vcc, s[66:67]
	v_cndmask_b32_dpp v36, v110, v104, vcc quad_perm:[1,0,3,2] row_mask:0xf bank_mask:0xf
	v_cndmask_b32_dpp v37, v111, v105, vcc quad_perm:[1,0,3,2] row_mask:0xf bank_mask:0xf
	s_mov_b64 vcc, s[62:63]
	v_cndmask_b32_dpp v110, v104, v110, vcc quad_perm:[1,0,3,2] row_mask:0xf bank_mask:0xf
	v_cndmask_b32_dpp v111, v105, v111, vcc quad_perm:[1,0,3,2] row_mask:0xf bank_mask:0xf
	v_perm_b32 v28, v32, v36, s32
	v_perm_b32 v29, v32, v36, s8
	v_perm_b32 v30, v33, v36, s61
	v_perm_b32 v31, v33, v36, s98
	v_pk_fma_f32 v[78:79], v[78:79], v[176:177], v[28:29]
	v_pk_fma_f32 v[80:81], v[80:81], v[178:179], v[30:31]
	v_perm_b32 v28, v34, v37, s32
	v_perm_b32 v29, v34, v37, s8
	v_perm_b32 v30, v35, v37, s61
	v_perm_b32 v31, v35, v37, s98
	v_pk_fma_f32 v[74:75], v[74:75], v[180:181], v[28:29]
	v_pk_fma_f32 v[76:77], v[76:77], v[182:183], v[30:31]
	v_perm_b32 v28, v106, v110, s32
	v_perm_b32 v29, v106, v110, s8
	v_perm_b32 v30, v107, v110, s61
	v_perm_b32 v31, v107, v110, s98
	v_pk_fma_f32 v[70:71], v[70:71], v[184:185], v[28:29]
	v_pk_fma_f32 v[72:73], v[72:73], v[186:187], v[30:31]
	v_perm_b32 v28, v108, v111, s32
	v_perm_b32 v29, v108, v111, s8
	v_perm_b32 v30, v109, v111, s61
	v_perm_b32 v31, v109, v111, s98
	v_pk_fma_f32 v[66:67], v[66:67], v[188:189], v[28:29]
	v_pk_fma_f32 v[68:69], v[68:69], v[190:191], v[30:31]
	v_mul_f32_e32 v28, v79, v79
	v_mul_f32_e32 v29, v81, v81
	v_mul_f32_e32 v30, v75, v75
	v_mul_f32_e32 v31, v77, v77
	v_fmac_f32_e32 v28, v78, v78
	v_fmac_f32_e32 v29, v80, v80
	v_fmac_f32_e32 v30, v74, v74
	v_fmac_f32_e32 v31, v76, v76
	v_add_f32_e32 v28, v28, v29
	v_add_f32_e32 v30, v30, v31
	v_add_f32_e32 v151, v28, v30
	v_add_u32_e32 v28, 0x80, v78
	v_add_u32_e32 v29, 0x80, v79
	v_add_u32_e32 v30, 0x80, v80
	v_add_u32_e32 v31, 0x80, v81
	v_perm_b32 v32, v29, v28, s78
	v_perm_b32 v33, v31, v30, s78
	v_perm_b32 v26, v29, v28, s79
	v_perm_b32 v27, v31, v30, s79
	v_perm_b32 v40, v27, v26, s60
	v_add_u32_e32 v28, 0x80, v74
	v_add_u32_e32 v29, 0x80, v75
	v_add_u32_e32 v30, 0x80, v76
	v_add_u32_e32 v31, 0x80, v77
	v_perm_b32 v34, v29, v28, s78
	v_perm_b32 v35, v31, v30, s78
	v_perm_b32 v26, v29, v28, s79
	v_perm_b32 v27, v31, v30, s79
	v_perm_b32 v41, v27, v26, s60
	v_mul_f32_e32 v28, v71, v71
	v_mul_f32_e32 v29, v73, v73
	v_mul_f32_e32 v30, v67, v67
	v_mul_f32_e32 v31, v69, v69
	v_fmac_f32_e32 v28, v70, v70
	v_fmac_f32_e32 v29, v72, v72
	v_fmac_f32_e32 v30, v66, v66
	v_fmac_f32_e32 v31, v68, v68
	v_add_f32_e32 v28, v28, v29
	v_add_f32_e32 v30, v30, v31
	v_add_f32_e32 v28, v28, v30
	v_add_f32_e32 v151, v151, v28
	v_add_u32_e32 v28, 0x80, v70
	v_add_u32_e32 v29, 0x80, v71
	v_add_u32_e32 v30, 0x80, v72
	v_add_u32_e32 v31, 0x80, v73
	v_perm_b32 v36, v29, v28, s78
	v_perm_b32 v37, v31, v30, s78
	v_perm_b32 v26, v29, v28, s79
	v_perm_b32 v27, v31, v30, s79
	v_perm_b32 v146, v27, v26, s60
	v_add_u32_e32 v28, 0x80, v66
	v_add_u32_e32 v29, 0x80, v67
	v_add_u32_e32 v30, 0x80, v68
	v_add_u32_e32 v31, 0x80, v69
	v_perm_b32 v38, v29, v28, s78
	v_perm_b32 v39, v31, v30, s78
	v_perm_b32 v26, v29, v28, s79
	v_perm_b32 v27, v31, v30, s79
	v_perm_b32 v147, v27, v26, s60
	s_mov_b64 vcc, s[66:67]
	v_cndmask_b32_dpp v100, v36, v32, vcc quad_perm:[1,0,3,2] row_mask:0xf bank_mask:0xf
	v_cndmask_b32_dpp v101, v37, v33, vcc quad_perm:[1,0,3,2] row_mask:0xf bank_mask:0xf
	v_cndmask_b32_dpp v102, v38, v34, vcc quad_perm:[1,0,3,2] row_mask:0xf bank_mask:0xf
	v_cndmask_b32_dpp v103, v39, v35, vcc quad_perm:[1,0,3,2] row_mask:0xf bank_mask:0xf
	s_mov_b64 vcc, s[62:63]
	v_cndmask_b32_dpp v36, v32, v36, vcc quad_perm:[1,0,3,2] row_mask:0xf bank_mask:0xf
	v_cndmask_b32_dpp v37, v33, v37, vcc quad_perm:[1,0,3,2] row_mask:0xf bank_mask:0xf
	v_cndmask_b32_dpp v38, v34, v38, vcc quad_perm:[1,0,3,2] row_mask:0xf bank_mask:0xf
	v_cndmask_b32_dpp v39, v35, v39, vcc quad_perm:[1,0,3,2] row_mask:0xf bank_mask:0xf
	s_mov_b64 vcc, s[66:67]
	v_cndmask_b32_dpp v106, v146, v40, vcc quad_perm:[1,0,3,2] row_mask:0xf bank_mask:0xf
	v_cndmask_b32_dpp v107, v147, v41, vcc quad_perm:[1,0,3,2] row_mask:0xf bank_mask:0xf
	s_mov_b64 vcc, s[62:63]
	v_cndmask_b32_dpp v146, v40, v146, vcc quad_perm:[1,0,3,2] row_mask:0xf bank_mask:0xf
	v_cndmask_b32_dpp v147, v41, v147, vcc quad_perm:[1,0,3,2] row_mask:0xf bank_mask:0xf
	s_add_u32 s88, s58, 0x40000
	s_addc_u32 s89, s59, 0
	s_add_u32 s90, s74, 0x20000
	s_addc_u32 s91, s75, 0
	global_store_dwordx4 v149, v[100:103], s[88:89]
	global_store_dwordx4 v149, v[36:39], s[88:89] offset:2048
	global_store_dwordx2 v148, v[106:107], s[90:91]
	global_store_dwordx2 v148, v[146:147], s[90:91] offset:1024
	s_add_u32 s92, s96, 0x40000
	s_addc_u32 s93, s97, 0
	v_pk_mul_f32 v[78:79], v[210:211], v[78:79]
	v_pk_mul_f32 v[80:81], v[212:213], v[80:81]
	v_pk_mul_f32 v[74:75], v[214:215], v[74:75]
	v_pk_mul_f32 v[76:77], v[216:217], v[76:77]
	v_cvt_pk_bf16_f32 v32, v78, v79
	v_cvt_pk_bf16_f32 v33, v80, v81
	v_cvt_pk_bf16_f32 v34, v74, v75
	v_cvt_pk_bf16_f32 v35, v76, v77
	v_pk_mul_f32 v[70:71], v[218:219], v[70:71]
	v_pk_mul_f32 v[72:73], v[220:221], v[72:73]
	v_pk_mul_f32 v[66:67], v[222:223], v[66:67]
	v_pk_mul_f32 v[68:69], v[224:225], v[68:69]
	v_cvt_pk_bf16_f32 v36, v70, v71
	v_cvt_pk_bf16_f32 v37, v72, v73
	v_cvt_pk_bf16_f32 v38, v66, v67
	v_cvt_pk_bf16_f32 v39, v68, v69
	s_mov_b64 vcc, s[66:67]
	v_cndmask_b32_dpp v100, v36, v32, vcc quad_perm:[1,0,3,2] row_mask:0xf bank_mask:0xf
	v_cndmask_b32_dpp v101, v37, v33, vcc quad_perm:[1,0,3,2] row_mask:0xf bank_mask:0xf
	v_cndmask_b32_dpp v102, v38, v34, vcc quad_perm:[1,0,3,2] row_mask:0xf bank_mask:0xf
	v_cndmask_b32_dpp v103, v39, v35, vcc quad_perm:[1,0,3,2] row_mask:0xf bank_mask:0xf
	s_mov_b64 vcc, s[62:63]
	v_cndmask_b32_dpp v36, v32, v36, vcc quad_perm:[1,0,3,2] row_mask:0xf bank_mask:0xf
	v_cndmask_b32_dpp v37, v33, v37, vcc quad_perm:[1,0,3,2] row_mask:0xf bank_mask:0xf
	v_cndmask_b32_dpp v38, v34, v38, vcc quad_perm:[1,0,3,2] row_mask:0xf bank_mask:0xf
	v_cndmask_b32_dpp v39, v35, v39, vcc quad_perm:[1,0,3,2] row_mask:0xf bank_mask:0xf
	global_store_dwordx4 v149, v[100:103], s[92:93]
	global_store_dwordx4 v149, v[36:39], s[92:93] offset:2048
	v_mov_b32_e32 v66, v151
	s_add_u32 s84, s58, 0x50000
	s_addc_u32 s85, s59, 0
	s_add_u32 s86, s74, 0x28000
	s_addc_u32 s87, s75, 0
	global_load_dwordx4 v[68:71], v149, s[84:85]
	global_load_dwordx2 v[72:73], v148, s[86:87]
	global_load_dwordx4 v[74:77], v149, s[84:85] offset:2048
	global_load_dwordx2 v[78:79], v148, s[86:87] offset:1024
	s_waitcnt vmcnt(10)
	s_mov_b64 vcc, s[66:67]
	v_cndmask_b32_dpp v32, v90, v84, vcc quad_perm:[1,0,3,2] row_mask:0xf bank_mask:0xf
	v_cndmask_b32_dpp v33, v91, v85, vcc quad_perm:[1,0,3,2] row_mask:0xf bank_mask:0xf
	v_cndmask_b32_dpp v34, v92, v86, vcc quad_perm:[1,0,3,2] row_mask:0xf bank_mask:0xf
	v_cndmask_b32_dpp v35, v93, v87, vcc quad_perm:[1,0,3,2] row_mask:0xf bank_mask:0xf
	s_mov_b64 vcc, s[62:63]
	v_cndmask_b32_dpp v90, v84, v90, vcc quad_perm:[1,0,3,2] row_mask:0xf bank_mask:0xf
	v_cndmask_b32_dpp v91, v85, v91, vcc quad_perm:[1,0,3,2] row_mask:0xf bank_mask:0xf
	v_cndmask_b32_dpp v92, v86, v92, vcc quad_perm:[1,0,3,2] row_mask:0xf bank_mask:0xf
	v_cndmask_b32_dpp v93, v87, v93, vcc quad_perm:[1,0,3,2] row_mask:0xf bank_mask:0xf
	s_mov_b64 vcc, s[66:67]
	v_cndmask_b32_dpp v36, v94, v88, vcc quad_perm:[1,0,3,2] row_mask:0xf bank_mask:0xf
	v_cndmask_b32_dpp v37, v95, v89, vcc quad_perm:[1,0,3,2] row_mask:0xf bank_mask:0xf
	s_mov_b64 vcc, s[62:63]
	v_cndmask_b32_dpp v94, v88, v94, vcc quad_perm:[1,0,3,2] row_mask:0xf bank_mask:0xf
	v_cndmask_b32_dpp v95, v89, v95, vcc quad_perm:[1,0,3,2] row_mask:0xf bank_mask:0xf
	v_perm_b32 v28, v32, v36, s32
	v_perm_b32 v29, v32, v36, s8
	v_perm_b32 v30, v33, v36, s61
	v_perm_b32 v31, v33, v36, s98
	v_pk_fma_f32 v[62:63], v[62:63], v[176:177], v[28:29]
	v_pk_fma_f32 v[64:65], v[64:65], v[178:179], v[30:31]
	v_perm_b32 v28, v34, v37, s32
	v_perm_b32 v29, v34, v37, s8
	v_perm_b32 v30, v35, v37, s61
	v_perm_b32 v31, v35, v37, s98
	v_pk_fma_f32 v[58:59], v[58:59], v[180:181], v[28:29]
	v_pk_fma_f32 v[60:61], v[60:61], v[182:183], v[30:31]
	v_perm_b32 v28, v90, v94, s32
	v_perm_b32 v29, v90, v94, s8
	v_perm_b32 v30, v91, v94, s61
	v_perm_b32 v31, v91, v94, s98
	v_pk_fma_f32 v[54:55], v[54:55], v[184:185], v[28:29]
	v_pk_fma_f32 v[56:57], v[56:57], v[186:187], v[30:31]
	v_perm_b32 v28, v92, v95, s32
	v_perm_b32 v29, v92, v95, s8
	v_perm_b32 v30, v93, v95, s61
	v_perm_b32 v31, v93, v95, s98
	v_pk_fma_f32 v[50:51], v[50:51], v[188:189], v[28:29]
	v_pk_fma_f32 v[52:53], v[52:53], v[190:191], v[30:31]
	v_mul_f32_e32 v28, v63, v63
	v_mul_f32_e32 v29, v65, v65
	v_mul_f32_e32 v30, v59, v59
	v_mul_f32_e32 v31, v61, v61
	v_fmac_f32_e32 v28, v62, v62
	v_fmac_f32_e32 v29, v64, v64
	v_fmac_f32_e32 v30, v58, v58
	v_fmac_f32_e32 v31, v60, v60
	v_add_f32_e32 v28, v28, v29
	v_add_f32_e32 v30, v30, v31
	v_add_f32_e32 v151, v28, v30
	v_add_u32_e32 v28, 0x80, v62
	v_add_u32_e32 v29, 0x80, v63
	v_add_u32_e32 v30, 0x80, v64
	v_add_u32_e32 v31, 0x80, v65
	v_perm_b32 v32, v29, v28, s78
	v_perm_b32 v33, v31, v30, s78
	v_perm_b32 v26, v29, v28, s79
	v_perm_b32 v27, v31, v30, s79
	v_perm_b32 v40, v27, v26, s60
	v_add_u32_e32 v28, 0x80, v58
	v_add_u32_e32 v29, 0x80, v59
	v_add_u32_e32 v30, 0x80, v60
	v_add_u32_e32 v31, 0x80, v61
	v_perm_b32 v34, v29, v28, s78
	v_perm_b32 v35, v31, v30, s78
	v_perm_b32 v26, v29, v28, s79
	v_perm_b32 v27, v31, v30, s79
	v_perm_b32 v41, v27, v26, s60
	v_mul_f32_e32 v28, v55, v55
	v_mul_f32_e32 v29, v57, v57
	v_mul_f32_e32 v30, v51, v51
	v_mul_f32_e32 v31, v53, v53
	v_fmac_f32_e32 v28, v54, v54
	v_fmac_f32_e32 v29, v56, v56
	v_fmac_f32_e32 v30, v50, v50
	v_fmac_f32_e32 v31, v52, v52
	v_add_f32_e32 v28, v28, v29
	v_add_f32_e32 v30, v30, v31
	v_add_f32_e32 v28, v28, v30
	v_add_f32_e32 v151, v151, v28
	v_add_u32_e32 v28, 0x80, v54
	v_add_u32_e32 v29, 0x80, v55
	v_add_u32_e32 v30, 0x80, v56
	v_add_u32_e32 v31, 0x80, v57
	v_perm_b32 v36, v29, v28, s78
	v_perm_b32 v37, v31, v30, s78
	v_perm_b32 v26, v29, v28, s79
	v_perm_b32 v27, v31, v30, s79
	v_perm_b32 v146, v27, v26, s60
	v_add_u32_e32 v28, 0x80, v50
	v_add_u32_e32 v29, 0x80, v51
	v_add_u32_e32 v30, 0x80, v52
	v_add_u32_e32 v31, 0x80, v53
	v_perm_b32 v38, v29, v28, s78
	v_perm_b32 v39, v31, v30, s78
	v_perm_b32 v26, v29, v28, s79
	v_perm_b32 v27, v31, v30, s79
	v_perm_b32 v147, v27, v26, s60
	s_mov_b64 vcc, s[66:67]
	v_cndmask_b32_dpp v84, v36, v32, vcc quad_perm:[1,0,3,2] row_mask:0xf bank_mask:0xf
	v_cndmask_b32_dpp v85, v37, v33, vcc quad_perm:[1,0,3,2] row_mask:0xf bank_mask:0xf
	v_cndmask_b32_dpp v86, v38, v34, vcc quad_perm:[1,0,3,2] row_mask:0xf bank_mask:0xf
	v_cndmask_b32_dpp v87, v39, v35, vcc quad_perm:[1,0,3,2] row_mask:0xf bank_mask:0xf
	s_mov_b64 vcc, s[62:63]
	v_cndmask_b32_dpp v36, v32, v36, vcc quad_perm:[1,0,3,2] row_mask:0xf bank_mask:0xf
	v_cndmask_b32_dpp v37, v33, v37, vcc quad_perm:[1,0,3,2] row_mask:0xf bank_mask:0xf
	v_cndmask_b32_dpp v38, v34, v38, vcc quad_perm:[1,0,3,2] row_mask:0xf bank_mask:0xf
	v_cndmask_b32_dpp v39, v35, v39, vcc quad_perm:[1,0,3,2] row_mask:0xf bank_mask:0xf
	s_mov_b64 vcc, s[66:67]
	v_cndmask_b32_dpp v90, v146, v40, vcc quad_perm:[1,0,3,2] row_mask:0xf bank_mask:0xf
	v_cndmask_b32_dpp v91, v147, v41, vcc quad_perm:[1,0,3,2] row_mask:0xf bank_mask:0xf
	s_mov_b64 vcc, s[62:63]
	v_cndmask_b32_dpp v146, v40, v146, vcc quad_perm:[1,0,3,2] row_mask:0xf bank_mask:0xf
	v_cndmask_b32_dpp v147, v41, v147, vcc quad_perm:[1,0,3,2] row_mask:0xf bank_mask:0xf
	s_add_u32 s88, s58, 0x48000
	s_addc_u32 s89, s59, 0
	s_add_u32 s90, s74, 0x24000
	s_addc_u32 s91, s75, 0
	global_store_dwordx4 v149, v[84:87], s[88:89]
	global_store_dwordx4 v149, v[36:39], s[88:89] offset:2048
	global_store_dwordx2 v148, v[90:91], s[90:91]
	global_store_dwordx2 v148, v[146:147], s[90:91] offset:1024
	s_add_u32 s92, s96, 0x48000
	s_addc_u32 s93, s97, 0
	v_pk_mul_f32 v[62:63], v[210:211], v[62:63]
	v_pk_mul_f32 v[64:65], v[212:213], v[64:65]
	v_pk_mul_f32 v[58:59], v[214:215], v[58:59]
	v_pk_mul_f32 v[60:61], v[216:217], v[60:61]
	v_cvt_pk_bf16_f32 v32, v62, v63
	v_cvt_pk_bf16_f32 v33, v64, v65
	v_cvt_pk_bf16_f32 v34, v58, v59
	v_cvt_pk_bf16_f32 v35, v60, v61
	v_pk_mul_f32 v[54:55], v[218:219], v[54:55]
	v_pk_mul_f32 v[56:57], v[220:221], v[56:57]
	v_pk_mul_f32 v[50:51], v[222:223], v[50:51]
	v_pk_mul_f32 v[52:53], v[224:225], v[52:53]
	v_cvt_pk_bf16_f32 v36, v54, v55
	v_cvt_pk_bf16_f32 v37, v56, v57
	v_cvt_pk_bf16_f32 v38, v50, v51
	v_cvt_pk_bf16_f32 v39, v52, v53
	s_mov_b64 vcc, s[66:67]
	v_cndmask_b32_dpp v84, v36, v32, vcc quad_perm:[1,0,3,2] row_mask:0xf bank_mask:0xf
	v_cndmask_b32_dpp v85, v37, v33, vcc quad_perm:[1,0,3,2] row_mask:0xf bank_mask:0xf
	v_cndmask_b32_dpp v86, v38, v34, vcc quad_perm:[1,0,3,2] row_mask:0xf bank_mask:0xf
	v_cndmask_b32_dpp v87, v39, v35, vcc quad_perm:[1,0,3,2] row_mask:0xf bank_mask:0xf
	s_mov_b64 vcc, s[62:63]
	v_cndmask_b32_dpp v36, v32, v36, vcc quad_perm:[1,0,3,2] row_mask:0xf bank_mask:0xf
	v_cndmask_b32_dpp v37, v33, v37, vcc quad_perm:[1,0,3,2] row_mask:0xf bank_mask:0xf
	v_cndmask_b32_dpp v38, v34, v38, vcc quad_perm:[1,0,3,2] row_mask:0xf bank_mask:0xf
	v_cndmask_b32_dpp v39, v35, v39, vcc quad_perm:[1,0,3,2] row_mask:0xf bank_mask:0xf
	global_store_dwordx4 v149, v[84:87], s[92:93]
	global_store_dwordx4 v149, v[36:39], s[92:93] offset:2048
	v_mov_b32_e32 v50, v151
	s_add_u32 s84, s58, 0x58000
	s_addc_u32 s85, s59, 0
	s_add_u32 s86, s74, 0x2c000
	s_addc_u32 s87, s75, 0
	global_load_dwordx4 v[52:55], v149, s[84:85]
	global_load_dwordx2 v[56:57], v148, s[86:87]
	global_load_dwordx4 v[58:61], v149, s[84:85] offset:2048
	global_load_dwordx2 v[62:63], v148, s[86:87] offset:1024
	s_waitcnt vmcnt(10)
	s_mov_b64 vcc, s[66:67]
	v_cndmask_b32_dpp v32, v74, v68, vcc quad_perm:[1,0,3,2] row_mask:0xf bank_mask:0xf
	v_cndmask_b32_dpp v33, v75, v69, vcc quad_perm:[1,0,3,2] row_mask:0xf bank_mask:0xf
	v_cndmask_b32_dpp v34, v76, v70, vcc quad_perm:[1,0,3,2] row_mask:0xf bank_mask:0xf
	v_cndmask_b32_dpp v35, v77, v71, vcc quad_perm:[1,0,3,2] row_mask:0xf bank_mask:0xf
	s_mov_b64 vcc, s[62:63]
	v_cndmask_b32_dpp v74, v68, v74, vcc quad_perm:[1,0,3,2] row_mask:0xf bank_mask:0xf
	v_cndmask_b32_dpp v75, v69, v75, vcc quad_perm:[1,0,3,2] row_mask:0xf bank_mask:0xf
	v_cndmask_b32_dpp v76, v70, v76, vcc quad_perm:[1,0,3,2] row_mask:0xf bank_mask:0xf
	v_cndmask_b32_dpp v77, v71, v77, vcc quad_perm:[1,0,3,2] row_mask:0xf bank_mask:0xf
	s_mov_b64 vcc, s[66:67]
	v_cndmask_b32_dpp v36, v78, v72, vcc quad_perm:[1,0,3,2] row_mask:0xf bank_mask:0xf
	v_cndmask_b32_dpp v37, v79, v73, vcc quad_perm:[1,0,3,2] row_mask:0xf bank_mask:0xf
	s_mov_b64 vcc, s[62:63]
	v_cndmask_b32_dpp v78, v72, v78, vcc quad_perm:[1,0,3,2] row_mask:0xf bank_mask:0xf
	v_cndmask_b32_dpp v79, v73, v79, vcc quad_perm:[1,0,3,2] row_mask:0xf bank_mask:0xf
	v_perm_b32 v28, v32, v36, s32
	v_perm_b32 v29, v32, v36, s8
	v_perm_b32 v30, v33, v36, s61
	v_perm_b32 v31, v33, v36, s98
	v_pk_fma_f32 v[46:47], v[46:47], v[176:177], v[28:29]
	v_pk_fma_f32 v[48:49], v[48:49], v[178:179], v[30:31]
	v_perm_b32 v28, v34, v37, s32
	v_perm_b32 v29, v34, v37, s8
	v_perm_b32 v30, v35, v37, s61
	v_perm_b32 v31, v35, v37, s98
	v_pk_fma_f32 v[42:43], v[42:43], v[180:181], v[28:29]
	v_pk_fma_f32 v[44:45], v[44:45], v[182:183], v[30:31]
	v_perm_b32 v28, v74, v78, s32
	v_perm_b32 v29, v74, v78, s8
	v_perm_b32 v30, v75, v78, s61
	v_perm_b32 v31, v75, v78, s98
	v_pk_fma_f32 v[22:23], v[22:23], v[184:185], v[28:29]
	v_pk_fma_f32 v[24:25], v[24:25], v[186:187], v[30:31]
	v_perm_b32 v28, v76, v79, s32
	v_perm_b32 v29, v76, v79, s8
	v_perm_b32 v30, v77, v79, s61
	v_perm_b32 v31, v77, v79, s98
	v_pk_fma_f32 v[18:19], v[18:19], v[188:189], v[28:29]
	v_pk_fma_f32 v[20:21], v[20:21], v[190:191], v[30:31]
	v_mul_f32_e32 v28, v47, v47
	v_mul_f32_e32 v29, v49, v49
	v_mul_f32_e32 v30, v43, v43
	v_mul_f32_e32 v31, v45, v45
	v_fmac_f32_e32 v28, v46, v46
	v_fmac_f32_e32 v29, v48, v48
	v_fmac_f32_e32 v30, v42, v42
	v_fmac_f32_e32 v31, v44, v44
	v_add_f32_e32 v28, v28, v29
	v_add_f32_e32 v30, v30, v31
	v_add_f32_e32 v151, v28, v30
	v_add_u32_e32 v28, 0x80, v46
	v_add_u32_e32 v29, 0x80, v47
	v_add_u32_e32 v30, 0x80, v48
	v_add_u32_e32 v31, 0x80, v49
	v_perm_b32 v32, v29, v28, s78
	v_perm_b32 v33, v31, v30, s78
	v_perm_b32 v26, v29, v28, s79
	v_perm_b32 v27, v31, v30, s79
	v_perm_b32 v40, v27, v26, s60
	v_add_u32_e32 v28, 0x80, v42
	v_add_u32_e32 v29, 0x80, v43
	v_add_u32_e32 v30, 0x80, v44
	v_add_u32_e32 v31, 0x80, v45
	v_perm_b32 v34, v29, v28, s78
	v_perm_b32 v35, v31, v30, s78
	v_perm_b32 v26, v29, v28, s79
	v_perm_b32 v27, v31, v30, s79
	v_perm_b32 v41, v27, v26, s60
	v_mul_f32_e32 v28, v23, v23
	v_mul_f32_e32 v29, v25, v25
	v_mul_f32_e32 v30, v19, v19
	v_mul_f32_e32 v31, v21, v21
	v_fmac_f32_e32 v28, v22, v22
	v_fmac_f32_e32 v29, v24, v24
	v_fmac_f32_e32 v30, v18, v18
	v_fmac_f32_e32 v31, v20, v20
	v_add_f32_e32 v28, v28, v29
	v_add_f32_e32 v30, v30, v31
	v_add_f32_e32 v28, v28, v30
	v_add_f32_e32 v151, v151, v28
	v_add_u32_e32 v28, 0x80, v22
	v_add_u32_e32 v29, 0x80, v23
	v_add_u32_e32 v30, 0x80, v24
	v_add_u32_e32 v31, 0x80, v25
	v_perm_b32 v36, v29, v28, s78
	v_perm_b32 v37, v31, v30, s78
	v_perm_b32 v26, v29, v28, s79
	v_perm_b32 v27, v31, v30, s79
	v_perm_b32 v146, v27, v26, s60
	v_add_u32_e32 v28, 0x80, v18
	v_add_u32_e32 v29, 0x80, v19
	v_add_u32_e32 v30, 0x80, v20
	v_add_u32_e32 v31, 0x80, v21
	v_perm_b32 v38, v29, v28, s78
	v_perm_b32 v39, v31, v30, s78
	v_perm_b32 v26, v29, v28, s79
	v_perm_b32 v27, v31, v30, s79
	v_perm_b32 v147, v27, v26, s60
	s_mov_b64 vcc, s[66:67]
	v_cndmask_b32_dpp v68, v36, v32, vcc quad_perm:[1,0,3,2] row_mask:0xf bank_mask:0xf
	v_cndmask_b32_dpp v69, v37, v33, vcc quad_perm:[1,0,3,2] row_mask:0xf bank_mask:0xf
	v_cndmask_b32_dpp v70, v38, v34, vcc quad_perm:[1,0,3,2] row_mask:0xf bank_mask:0xf
	v_cndmask_b32_dpp v71, v39, v35, vcc quad_perm:[1,0,3,2] row_mask:0xf bank_mask:0xf
	s_mov_b64 vcc, s[62:63]
	v_cndmask_b32_dpp v36, v32, v36, vcc quad_perm:[1,0,3,2] row_mask:0xf bank_mask:0xf
	v_cndmask_b32_dpp v37, v33, v37, vcc quad_perm:[1,0,3,2] row_mask:0xf bank_mask:0xf
	v_cndmask_b32_dpp v38, v34, v38, vcc quad_perm:[1,0,3,2] row_mask:0xf bank_mask:0xf
	v_cndmask_b32_dpp v39, v35, v39, vcc quad_perm:[1,0,3,2] row_mask:0xf bank_mask:0xf
	s_mov_b64 vcc, s[66:67]
	v_cndmask_b32_dpp v74, v146, v40, vcc quad_perm:[1,0,3,2] row_mask:0xf bank_mask:0xf
	v_cndmask_b32_dpp v75, v147, v41, vcc quad_perm:[1,0,3,2] row_mask:0xf bank_mask:0xf
	s_mov_b64 vcc, s[62:63]
	v_cndmask_b32_dpp v146, v40, v146, vcc quad_perm:[1,0,3,2] row_mask:0xf bank_mask:0xf
	v_cndmask_b32_dpp v147, v41, v147, vcc quad_perm:[1,0,3,2] row_mask:0xf bank_mask:0xf
	s_add_u32 s88, s58, 0x50000
	s_addc_u32 s89, s59, 0
	s_add_u32 s90, s74, 0x28000
	s_addc_u32 s91, s75, 0
	global_store_dwordx4 v149, v[68:71], s[88:89]
	global_store_dwordx4 v149, v[36:39], s[88:89] offset:2048
	global_store_dwordx2 v148, v[74:75], s[90:91]
	global_store_dwordx2 v148, v[146:147], s[90:91] offset:1024
	s_add_u32 s92, s96, 0x50000
	s_addc_u32 s93, s97, 0
	v_pk_mul_f32 v[46:47], v[210:211], v[46:47]
	v_pk_mul_f32 v[48:49], v[212:213], v[48:49]
	v_pk_mul_f32 v[42:43], v[214:215], v[42:43]
	v_pk_mul_f32 v[44:45], v[216:217], v[44:45]
	v_cvt_pk_bf16_f32 v32, v46, v47
	v_cvt_pk_bf16_f32 v33, v48, v49
	v_cvt_pk_bf16_f32 v34, v42, v43
	v_cvt_pk_bf16_f32 v35, v44, v45
	v_pk_mul_f32 v[22:23], v[218:219], v[22:23]
	v_pk_mul_f32 v[24:25], v[220:221], v[24:25]
	v_pk_mul_f32 v[18:19], v[222:223], v[18:19]
	v_pk_mul_f32 v[20:21], v[224:225], v[20:21]
	v_cvt_pk_bf16_f32 v36, v22, v23
	v_cvt_pk_bf16_f32 v37, v24, v25
	v_cvt_pk_bf16_f32 v38, v18, v19
	v_cvt_pk_bf16_f32 v39, v20, v21
	s_mov_b64 vcc, s[66:67]
	v_cndmask_b32_dpp v68, v36, v32, vcc quad_perm:[1,0,3,2] row_mask:0xf bank_mask:0xf
	v_cndmask_b32_dpp v69, v37, v33, vcc quad_perm:[1,0,3,2] row_mask:0xf bank_mask:0xf
	v_cndmask_b32_dpp v70, v38, v34, vcc quad_perm:[1,0,3,2] row_mask:0xf bank_mask:0xf
	v_cndmask_b32_dpp v71, v39, v35, vcc quad_perm:[1,0,3,2] row_mask:0xf bank_mask:0xf
	s_mov_b64 vcc, s[62:63]
	v_cndmask_b32_dpp v36, v32, v36, vcc quad_perm:[1,0,3,2] row_mask:0xf bank_mask:0xf
	v_cndmask_b32_dpp v37, v33, v37, vcc quad_perm:[1,0,3,2] row_mask:0xf bank_mask:0xf
	v_cndmask_b32_dpp v38, v34, v38, vcc quad_perm:[1,0,3,2] row_mask:0xf bank_mask:0xf
	v_cndmask_b32_dpp v39, v35, v39, vcc quad_perm:[1,0,3,2] row_mask:0xf bank_mask:0xf
	global_store_dwordx4 v149, v[68:71], s[92:93]
	global_store_dwordx4 v149, v[36:39], s[92:93] offset:2048
	v_mov_b32_e32 v18, v151
	s_waitcnt vmcnt(6)
	s_mov_b64 vcc, s[66:67]
	v_cndmask_b32_dpp v32, v58, v52, vcc quad_perm:[1,0,3,2] row_mask:0xf bank_mask:0xf
	v_cndmask_b32_dpp v33, v59, v53, vcc quad_perm:[1,0,3,2] row_mask:0xf bank_mask:0xf
	v_cndmask_b32_dpp v34, v60, v54, vcc quad_perm:[1,0,3,2] row_mask:0xf bank_mask:0xf
	v_cndmask_b32_dpp v35, v61, v55, vcc quad_perm:[1,0,3,2] row_mask:0xf bank_mask:0xf
	s_mov_b64 vcc, s[62:63]
	v_cndmask_b32_dpp v58, v52, v58, vcc quad_perm:[1,0,3,2] row_mask:0xf bank_mask:0xf
	v_cndmask_b32_dpp v59, v53, v59, vcc quad_perm:[1,0,3,2] row_mask:0xf bank_mask:0xf
	v_cndmask_b32_dpp v60, v54, v60, vcc quad_perm:[1,0,3,2] row_mask:0xf bank_mask:0xf
	v_cndmask_b32_dpp v61, v55, v61, vcc quad_perm:[1,0,3,2] row_mask:0xf bank_mask:0xf
	s_mov_b64 vcc, s[66:67]
	v_cndmask_b32_dpp v36, v62, v56, vcc quad_perm:[1,0,3,2] row_mask:0xf bank_mask:0xf
	v_cndmask_b32_dpp v37, v63, v57, vcc quad_perm:[1,0,3,2] row_mask:0xf bank_mask:0xf
	s_mov_b64 vcc, s[62:63]
	v_cndmask_b32_dpp v62, v56, v62, vcc quad_perm:[1,0,3,2] row_mask:0xf bank_mask:0xf
	v_cndmask_b32_dpp v63, v57, v63, vcc quad_perm:[1,0,3,2] row_mask:0xf bank_mask:0xf
	v_perm_b32 v28, v32, v36, s32
	v_perm_b32 v29, v32, v36, s8
	v_perm_b32 v30, v33, v36, s61
	v_perm_b32 v31, v33, v36, s98
	v_pk_fma_f32 v[14:15], v[14:15], v[176:177], v[28:29]
	v_pk_fma_f32 v[16:17], v[16:17], v[178:179], v[30:31]
	v_perm_b32 v28, v34, v37, s32
	v_perm_b32 v29, v34, v37, s8
	v_perm_b32 v30, v35, v37, s61
	v_perm_b32 v31, v35, v37, s98
	v_pk_fma_f32 v[10:11], v[10:11], v[180:181], v[28:29]
	v_pk_fma_f32 v[12:13], v[12:13], v[182:183], v[30:31]
	v_perm_b32 v28, v58, v62, s32
	v_perm_b32 v29, v58, v62, s8
	v_perm_b32 v30, v59, v62, s61
	v_perm_b32 v31, v59, v62, s98
	v_pk_fma_f32 v[6:7], v[6:7], v[184:185], v[28:29]
	v_pk_fma_f32 v[8:9], v[8:9], v[186:187], v[30:31]
	v_perm_b32 v28, v60, v63, s32
	v_perm_b32 v29, v60, v63, s8
	v_perm_b32 v30, v61, v63, s61
	v_perm_b32 v31, v61, v63, s98
	v_pk_fma_f32 v[2:3], v[2:3], v[188:189], v[28:29]
	v_pk_fma_f32 v[4:5], v[4:5], v[190:191], v[30:31]
	v_mul_f32_e32 v28, v15, v15
	v_mul_f32_e32 v29, v17, v17
	v_mul_f32_e32 v30, v11, v11
	v_mul_f32_e32 v31, v13, v13
	v_fmac_f32_e32 v28, v14, v14
	v_fmac_f32_e32 v29, v16, v16
	v_fmac_f32_e32 v30, v10, v10
	v_fmac_f32_e32 v31, v12, v12
	v_add_f32_e32 v28, v28, v29
	v_add_f32_e32 v30, v30, v31
	v_add_f32_e32 v151, v28, v30
	v_add_u32_e32 v28, 0x80, v14
	v_add_u32_e32 v29, 0x80, v15
	v_add_u32_e32 v30, 0x80, v16
	v_add_u32_e32 v31, 0x80, v17
	v_perm_b32 v32, v29, v28, s78
	v_perm_b32 v33, v31, v30, s78
	v_perm_b32 v26, v29, v28, s79
	v_perm_b32 v27, v31, v30, s79
	v_perm_b32 v40, v27, v26, s60
	v_add_u32_e32 v28, 0x80, v10
	v_add_u32_e32 v29, 0x80, v11
	v_add_u32_e32 v30, 0x80, v12
	v_add_u32_e32 v31, 0x80, v13
	v_perm_b32 v34, v29, v28, s78
	v_perm_b32 v35, v31, v30, s78
	v_perm_b32 v26, v29, v28, s79
	v_perm_b32 v27, v31, v30, s79
	v_perm_b32 v41, v27, v26, s60
	v_mul_f32_e32 v28, v7, v7
	v_mul_f32_e32 v29, v9, v9
	v_mul_f32_e32 v30, v3, v3
	v_mul_f32_e32 v31, v5, v5
	v_fmac_f32_e32 v28, v6, v6
	v_fmac_f32_e32 v29, v8, v8
	v_fmac_f32_e32 v30, v2, v2
	v_fmac_f32_e32 v31, v4, v4
	v_add_f32_e32 v28, v28, v29
	v_add_f32_e32 v30, v30, v31
	v_add_f32_e32 v28, v28, v30
	v_add_f32_e32 v151, v151, v28
	v_add_u32_e32 v28, 0x80, v6
	v_add_u32_e32 v29, 0x80, v7
	v_add_u32_e32 v30, 0x80, v8
	v_add_u32_e32 v31, 0x80, v9
	v_perm_b32 v36, v29, v28, s78
	v_perm_b32 v37, v31, v30, s78
	v_perm_b32 v26, v29, v28, s79
	v_perm_b32 v27, v31, v30, s79
	v_perm_b32 v146, v27, v26, s60
	v_add_u32_e32 v28, 0x80, v2
	v_add_u32_e32 v29, 0x80, v3
	v_add_u32_e32 v30, 0x80, v4
	v_add_u32_e32 v31, 0x80, v5
	v_perm_b32 v38, v29, v28, s78
	v_perm_b32 v39, v31, v30, s78
	v_perm_b32 v26, v29, v28, s79
	v_perm_b32 v27, v31, v30, s79
	v_perm_b32 v147, v27, v26, s60
	s_mov_b64 vcc, s[66:67]
	v_cndmask_b32_dpp v52, v36, v32, vcc quad_perm:[1,0,3,2] row_mask:0xf bank_mask:0xf
	v_cndmask_b32_dpp v53, v37, v33, vcc quad_perm:[1,0,3,2] row_mask:0xf bank_mask:0xf
	v_cndmask_b32_dpp v54, v38, v34, vcc quad_perm:[1,0,3,2] row_mask:0xf bank_mask:0xf
	v_cndmask_b32_dpp v55, v39, v35, vcc quad_perm:[1,0,3,2] row_mask:0xf bank_mask:0xf
	s_mov_b64 vcc, s[62:63]
	v_cndmask_b32_dpp v36, v32, v36, vcc quad_perm:[1,0,3,2] row_mask:0xf bank_mask:0xf
	v_cndmask_b32_dpp v37, v33, v37, vcc quad_perm:[1,0,3,2] row_mask:0xf bank_mask:0xf
	v_cndmask_b32_dpp v38, v34, v38, vcc quad_perm:[1,0,3,2] row_mask:0xf bank_mask:0xf
	v_cndmask_b32_dpp v39, v35, v39, vcc quad_perm:[1,0,3,2] row_mask:0xf bank_mask:0xf
	s_mov_b64 vcc, s[66:67]
	v_cndmask_b32_dpp v58, v146, v40, vcc quad_perm:[1,0,3,2] row_mask:0xf bank_mask:0xf
	v_cndmask_b32_dpp v59, v147, v41, vcc quad_perm:[1,0,3,2] row_mask:0xf bank_mask:0xf
	s_mov_b64 vcc, s[62:63]
	v_cndmask_b32_dpp v146, v40, v146, vcc quad_perm:[1,0,3,2] row_mask:0xf bank_mask:0xf
	v_cndmask_b32_dpp v147, v41, v147, vcc quad_perm:[1,0,3,2] row_mask:0xf bank_mask:0xf
	s_add_u32 s88, s58, 0x58000
	s_addc_u32 s89, s59, 0
	s_add_u32 s90, s74, 0x2c000
	s_addc_u32 s91, s75, 0
	global_store_dwordx4 v149, v[52:55], s[88:89]
	global_store_dwordx4 v149, v[36:39], s[88:89] offset:2048
	global_store_dwordx2 v148, v[58:59], s[90:91]
	global_store_dwordx2 v148, v[146:147], s[90:91] offset:1024
	s_add_u32 s92, s96, 0x58000
	s_addc_u32 s93, s97, 0
	v_pk_mul_f32 v[14:15], v[210:211], v[14:15]
	v_pk_mul_f32 v[16:17], v[212:213], v[16:17]
	v_pk_mul_f32 v[10:11], v[214:215], v[10:11]
	v_pk_mul_f32 v[12:13], v[216:217], v[12:13]
	v_cvt_pk_bf16_f32 v32, v14, v15
	v_cvt_pk_bf16_f32 v33, v16, v17
	v_cvt_pk_bf16_f32 v34, v10, v11
	v_cvt_pk_bf16_f32 v35, v12, v13
	v_pk_mul_f32 v[6:7], v[218:219], v[6:7]
	v_pk_mul_f32 v[8:9], v[220:221], v[8:9]
	v_pk_mul_f32 v[2:3], v[222:223], v[2:3]
	v_pk_mul_f32 v[4:5], v[224:225], v[4:5]
	v_cvt_pk_bf16_f32 v36, v6, v7
	v_cvt_pk_bf16_f32 v37, v8, v9
	v_cvt_pk_bf16_f32 v38, v2, v3
	v_cvt_pk_bf16_f32 v39, v4, v5
	s_mov_b64 vcc, s[66:67]
	v_cndmask_b32_dpp v52, v36, v32, vcc quad_perm:[1,0,3,2] row_mask:0xf bank_mask:0xf
	v_cndmask_b32_dpp v53, v37, v33, vcc quad_perm:[1,0,3,2] row_mask:0xf bank_mask:0xf
	v_cndmask_b32_dpp v54, v38, v34, vcc quad_perm:[1,0,3,2] row_mask:0xf bank_mask:0xf
	v_cndmask_b32_dpp v55, v39, v35, vcc quad_perm:[1,0,3,2] row_mask:0xf bank_mask:0xf
	s_mov_b64 vcc, s[62:63]
	v_cndmask_b32_dpp v36, v32, v36, vcc quad_perm:[1,0,3,2] row_mask:0xf bank_mask:0xf
	v_cndmask_b32_dpp v37, v33, v37, vcc quad_perm:[1,0,3,2] row_mask:0xf bank_mask:0xf
	v_cndmask_b32_dpp v38, v34, v38, vcc quad_perm:[1,0,3,2] row_mask:0xf bank_mask:0xf
	v_cndmask_b32_dpp v39, v35, v39, vcc quad_perm:[1,0,3,2] row_mask:0xf bank_mask:0xf
	global_store_dwordx4 v149, v[52:55], s[92:93]
	global_store_dwordx4 v149, v[36:39], s[92:93] offset:2048
	v_mov_b32_e32 v2, v151
	v_mbcnt_lo_u32_b32 v3, -1, 0
	v_mbcnt_hi_u32_b32 v3, -1, v3
	v_xor_b32_e32 v4, 16, v3
	v_xor_b32_e32 v5, 32, v3
	v_lshlrev_b32_e32 v4, 2, v4
	v_lshlrev_b32_e32 v5, 2, v5
	v_cmp_gt_u32_e64 s[34:35], 16, v3
	ds_bpermute_b32 v6, v4, v130
	ds_bpermute_b32 v7, v4, v114
	ds_bpermute_b32 v8, v4, v98
	ds_bpermute_b32 v9, v4, v82
	ds_bpermute_b32 v10, v4, v66
	ds_bpermute_b32 v11, v4, v50
	ds_bpermute_b32 v12, v4, v18
	ds_bpermute_b32 v13, v4, v2
	s_waitcnt lgkmcnt(0)
	v_add_f32_e32 v130, v130, v6
	v_add_f32_e32 v114, v114, v7
	v_add_f32_e32 v98, v98, v8
	v_add_f32_e32 v82, v82, v9
	v_add_f32_e32 v66, v66, v10
	v_add_f32_e32 v50, v50, v11
	v_add_f32_e32 v18, v18, v12
	v_add_f32_e32 v2, v2, v13
	ds_bpermute_b32 v6, v5, v130
	ds_bpermute_b32 v7, v5, v114
	ds_bpermute_b32 v8, v5, v98
	ds_bpermute_b32 v9, v5, v82
	ds_bpermute_b32 v10, v5, v66
	ds_bpermute_b32 v11, v5, v50
	ds_bpermute_b32 v12, v5, v18
	ds_bpermute_b32 v13, v5, v2
	s_waitcnt lgkmcnt(0)
	v_add_f32_e32 v130, v130, v6
	v_add_f32_e32 v114, v114, v7
	v_add_f32_e32 v98, v98, v8
	v_add_f32_e32 v82, v82, v9
	v_add_f32_e32 v66, v66, v10
	v_add_f32_e32 v50, v50, v11
	v_add_f32_e32 v18, v18, v12
	v_add_f32_e32 v2, v2, v13
	v_readlane_b32 s70, v244, 53
	v_readlane_b32 s71, v244, 54
	v_lshlrev_b32_e32 v3, 6, v192
	s_lshl_b32 s94, s55, 14
	s_lshl_b32 s95, s4, 4
	s_add_u32 s94, s94, s95
	s_lshl_b32 s95, s49, 2
	s_add_u32 s94, s94, s95
	s_add_u32 s94, s70, s94
	s_addc_u32 s95, s71, 0
	s_and_saveexec_b64 s[36:37], s[34:35]
	global_store_dword v3, v130, s[94:95]
	s_add_u32 s84, s94, 0x400
	s_addc_u32 s85, s95, 0
	global_store_dword v3, v114, s[84:85]
	s_add_u32 s84, s94, 0x800
	s_addc_u32 s85, s95, 0
	global_store_dword v3, v98, s[84:85]
	s_add_u32 s84, s94, 0xc00
	s_addc_u32 s85, s95, 0
	global_store_dword v3, v82, s[84:85]
	s_add_u32 s84, s94, 0x2000
	s_addc_u32 s85, s95, 0
	global_store_dword v3, v66, s[84:85]
	s_add_u32 s84, s94, 0x2400
	s_addc_u32 s85, s95, 0
	global_store_dword v3, v50, s[84:85]
	s_add_u32 s84, s94, 0x2800
	s_addc_u32 s85, s95, 0
	global_store_dword v3, v18, s[84:85]
	s_add_u32 s84, s94, 0x2c00
	s_addc_u32 s85, s95, 0
	global_store_dword v3, v2, s[84:85]
	s_or_b64 exec, exec, s[36:37]
	v_readlane_b32 s56, v246, 3
	v_readlane_b32 s57, v246, 4
	s_andn2_b64 vcc, exec, s[18:19]
	s_mov_b64 s[12:13], -1
	s_cbranch_vccnz .LBB0_1180
	s_andn2_b64 vcc, exec, s[0:1]
	s_cbranch_vccnz .LBB0_1179
	s_barrier
	s_branch .LBB0_1179

.LBB0_1229:
	s_ashr_i32 s12, s53, 31
	s_lshr_b32 s12, s12, 29
	s_add_i32 s12, s53, s12
	s_ashr_i32 s12, s12, 3
	s_mul_i32 s25, s12, 0x6000
	s_mul_hi_i32 s23, s12, 0x6000
	v_readlane_b32 s12, v246, 17
	v_readlane_b32 s13, v246, 18
	v_readlane_b32 s30, v246, 7
	v_readlane_b32 s31, v246, 8
	s_add_u32 s80, s40, s25
	s_addc_u32 s81, s41, s23
	s_add_u32 s82, s45, s25
	s_addc_u32 s83, s46, s23
	s_mov_b32 s62, 0xaaaaaaaa
	s_mov_b32 s63, 0xaaaaaaaa
	s_mov_b32 s66, 0x55555555
	s_mov_b32 s67, 0x55555555
	s_mov_b32 s32, 0x0504000c
	s_mov_b32 s61, 0x0504020c
	s_mov_b32 s98, 0x0706030c
	v_mbcnt_lo_u32_b32 v172, -1, 0
	v_mbcnt_hi_u32_b32 v172, -1, v172
	v_and_b32_e32 v172, 1, v172
	v_and_b32_e32 v49, 0x60, v192
	v_add_u32_e32 v49, v49, v192
	v_lshl_or_b32 v49, s4, 8, v49
	v_lshlrev_b32_e32 v28, 2, v49
	v_lshl_add_u32 v49, v172, 5, v49
	v_lshl_add_u32 v48, s53, 8, v190
	v_sub_u32_e32 v48, v48, v172
	v_lshl_add_u32 v48, v48, 10, v49
	v_lshlrev_b32_e32 v49, 1, v48
	v_and_b32_e32 v209, 0x60, v192
	v_add_u32_e32 v209, v209, v192
	v_lshl_or_b32 v209, s4, 8, v209
	v_lshl_add_u32 v29, s53, 8, v190
	v_lshl_add_u32 v209, v29, 10, v209
	v_lshlrev_b32_e32 v209, 2, v209
	global_load_dwordx4 v[174:177], v28, s[80:81] offset:0
	global_load_dwordx4 v[178:181], v28, s[80:81] offset:16
	global_load_dwordx4 v[194:197], v28, s[12:13] offset:0
	global_load_dwordx4 v[210:213], v28, s[12:13] offset:16
	global_load_dwordx4 v[182:185], v28, s[80:81] offset:128
	global_load_dwordx4 v[186:189], v28, s[80:81] offset:144
	global_load_dwordx4 v[214:217], v28, s[12:13] offset:128
	global_load_dwordx4 v[218:221], v28, s[12:13] offset:144
	global_load_dwordx4 v[222:225], v28, s[82:83] offset:0
	global_load_dwordx4 v[226:229], v28, s[82:83] offset:16
	global_load_dwordx4 v[230:233], v28, s[82:83] offset:128
	global_load_dwordx4 v[234:237], v28, s[82:83] offset:144
	s_waitcnt vmcnt(0)
	v_pk_add_f32 v[222:223], v[222:223], 1.0 op_sel_hi:[1,0]
	v_pk_add_f32 v[224:225], v[224:225], 1.0 op_sel_hi:[1,0]
	v_pk_add_f32 v[226:227], v[226:227], 1.0 op_sel_hi:[1,0]
	v_pk_add_f32 v[228:229], v[228:229], 1.0 op_sel_hi:[1,0]
	v_pk_mul_f32 v[194:195], v[194:195], v[222:223]
	v_pk_mul_f32 v[196:197], v[196:197], v[224:225]
	v_pk_mul_f32 v[210:211], v[210:211], v[226:227]
	v_pk_mul_f32 v[212:213], v[212:213], v[228:229]
	v_pk_add_f32 v[230:231], v[230:231], 1.0 op_sel_hi:[1,0]
	v_pk_add_f32 v[232:233], v[232:233], 1.0 op_sel_hi:[1,0]
	v_pk_add_f32 v[234:235], v[234:235], 1.0 op_sel_hi:[1,0]
	v_pk_add_f32 v[236:237], v[236:237], 1.0 op_sel_hi:[1,0]
	v_pk_mul_f32 v[214:215], v[214:215], v[230:231]
	v_pk_mul_f32 v[216:217], v[216:217], v[232:233]
	v_pk_mul_f32 v[218:219], v[218:219], v[234:235]
	v_pk_mul_f32 v[220:221], v[220:221], v[236:237]
	s_add_u32 s84, s30, 0x0
	s_addc_u32 s85, s31, 0
	global_load_dwordx4 v[222:225], v209, s[84:85] offset:0
	global_load_dwordx4 v[226:229], v209, s[84:85] offset:16
	global_load_dwordx4 v[230:233], v209, s[84:85] offset:128
	global_load_dwordx4 v[234:237], v209, s[84:85] offset:144
	s_waitcnt vmcnt(0)
	v_pk_fma_f32 v[142:143], v[142:143], v[174:175], v[222:223]
	v_pk_fma_f32 v[144:145], v[144:145], v[176:177], v[224:225]
	v_pk_fma_f32 v[138:139], v[138:139], v[178:179], v[226:227]
	v_pk_fma_f32 v[140:141], v[140:141], v[180:181], v[228:229]
	v_pk_fma_f32 v[134:135], v[134:135], v[182:183], v[230:231]
	v_pk_fma_f32 v[136:137], v[136:137], v[184:185], v[232:233]
	v_pk_fma_f32 v[130:131], v[130:131], v[186:187], v[234:235]
	v_pk_fma_f32 v[132:133], v[132:133], v[188:189], v[236:237]
	v_mul_f32_e32 v28, v143, v143
	v_mul_f32_e32 v29, v145, v145
	v_mul_f32_e32 v30, v139, v139
	v_mul_f32_e32 v31, v141, v141
	v_fmac_f32_e32 v28, v142, v142
	v_fmac_f32_e32 v29, v144, v144
	v_fmac_f32_e32 v30, v138, v138
	v_fmac_f32_e32 v31, v140, v140
	v_add_f32_e32 v28, v28, v29
	v_add_f32_e32 v30, v30, v31
	v_add_f32_e32 v173, v28, v30
	v_add_u32_e32 v28, 0x80, v142
	v_add_u32_e32 v29, 0x80, v143
	v_add_u32_e32 v30, 0x80, v144
	v_add_u32_e32 v31, 0x80, v145
	v_perm_b32 v44, v29, v28, s78
	v_perm_b32 v45, v31, v30, s78
	v_perm_b32 v26, v29, v28, s79
	v_perm_b32 v27, v31, v30, s79
	v_perm_b32 v32, v27, v26, s60
	v_add_u32_e32 v28, 0x80, v138
	v_add_u32_e32 v29, 0x80, v139
	v_add_u32_e32 v30, 0x80, v140
	v_add_u32_e32 v31, 0x80, v141
	v_perm_b32 v46, v29, v28, s78
	v_perm_b32 v47, v31, v30, s78
	v_perm_b32 v26, v29, v28, s79
	v_perm_b32 v27, v31, v30, s79
	v_perm_b32 v33, v27, v26, s60
	v_mul_f32_e32 v28, v135, v135
	v_mul_f32_e32 v29, v137, v137
	v_mul_f32_e32 v30, v131, v131
	v_mul_f32_e32 v31, v133, v133
	v_fmac_f32_e32 v28, v134, v134
	v_fmac_f32_e32 v29, v136, v136
	v_fmac_f32_e32 v30, v130, v130
	v_fmac_f32_e32 v31, v132, v132
	v_add_f32_e32 v28, v28, v29
	v_add_f32_e32 v30, v30, v31
	v_add_f32_e32 v28, v28, v30
	v_add_f32_e32 v173, v173, v28
	v_add_u32_e32 v28, 0x80, v134
	v_add_u32_e32 v29, 0x80, v135
	v_add_u32_e32 v30, 0x80, v136
	v_add_u32_e32 v31, 0x80, v137
	v_perm_b32 v168, v29, v28, s78
	v_perm_b32 v169, v31, v30, s78
	v_perm_b32 v26, v29, v28, s79
	v_perm_b32 v27, v31, v30, s79
	v_perm_b32 v42, v27, v26, s60
	v_add_u32_e32 v28, 0x80, v130
	v_add_u32_e32 v29, 0x80, v131
	v_add_u32_e32 v30, 0x80, v132
	v_add_u32_e32 v31, 0x80, v133
	v_perm_b32 v170, v29, v28, s78
	v_perm_b32 v171, v31, v30, s78
	v_perm_b32 v26, v29, v28, s79
	v_perm_b32 v27, v31, v30, s79
	v_perm_b32 v43, v27, v26, s60
	s_mov_b64 vcc, s[66:67]
	v_cndmask_b32_dpp v222, v168, v44, vcc quad_perm:[1,0,3,2] row_mask:0xf bank_mask:0xf
	v_cndmask_b32_dpp v223, v169, v45, vcc quad_perm:[1,0,3,2] row_mask:0xf bank_mask:0xf
	v_cndmask_b32_dpp v224, v170, v46, vcc quad_perm:[1,0,3,2] row_mask:0xf bank_mask:0xf
	v_cndmask_b32_dpp v225, v171, v47, vcc quad_perm:[1,0,3,2] row_mask:0xf bank_mask:0xf
	s_mov_b64 vcc, s[62:63]
	v_cndmask_b32_dpp v168, v44, v168, vcc quad_perm:[1,0,3,2] row_mask:0xf bank_mask:0xf
	v_cndmask_b32_dpp v169, v45, v169, vcc quad_perm:[1,0,3,2] row_mask:0xf bank_mask:0xf
	v_cndmask_b32_dpp v170, v46, v170, vcc quad_perm:[1,0,3,2] row_mask:0xf bank_mask:0xf
	v_cndmask_b32_dpp v171, v47, v171, vcc quad_perm:[1,0,3,2] row_mask:0xf bank_mask:0xf
	s_mov_b64 vcc, s[66:67]
	v_cndmask_b32_dpp v226, v42, v32, vcc quad_perm:[1,0,3,2] row_mask:0xf bank_mask:0xf
	v_cndmask_b32_dpp v227, v43, v33, vcc quad_perm:[1,0,3,2] row_mask:0xf bank_mask:0xf
	s_mov_b64 vcc, s[62:63]
	v_cndmask_b32_dpp v42, v32, v42, vcc quad_perm:[1,0,3,2] row_mask:0xf bank_mask:0xf
	v_cndmask_b32_dpp v43, v33, v43, vcc quad_perm:[1,0,3,2] row_mask:0xf bank_mask:0xf
	s_add_u32 s88, s58, 0x0
	s_addc_u32 s89, s59, 0
	s_add_u32 s90, s74, 0x0
	s_addc_u32 s91, s75, 0
	global_store_dwordx4 v49, v[222:225], s[88:89]
	global_store_dwordx4 v49, v[168:171], s[88:89] offset:2048
	global_store_dwordx2 v48, v[226:227], s[90:91]
	global_store_dwordx2 v48, v[42:43], s[90:91] offset:1024
	s_add_u32 s92, s96, 0x0
	s_addc_u32 s93, s97, 0
	v_pk_mul_f32 v[142:143], v[194:195], v[142:143]
	v_pk_mul_f32 v[144:145], v[196:197], v[144:145]
	v_pk_mul_f32 v[138:139], v[210:211], v[138:139]
	v_pk_mul_f32 v[140:141], v[212:213], v[140:141]
	v_cvt_pk_bf16_f32 v44, v142, v143
	v_cvt_pk_bf16_f32 v45, v144, v145
	v_cvt_pk_bf16_f32 v46, v138, v139
	v_cvt_pk_bf16_f32 v47, v140, v141
	v_pk_mul_f32 v[134:135], v[214:215], v[134:135]
	v_pk_mul_f32 v[136:137], v[216:217], v[136:137]
	v_pk_mul_f32 v[130:131], v[218:219], v[130:131]
	v_pk_mul_f32 v[132:133], v[220:221], v[132:133]
	v_cvt_pk_bf16_f32 v168, v134, v135
	v_cvt_pk_bf16_f32 v169, v136, v137
	v_cvt_pk_bf16_f32 v170, v130, v131
	v_cvt_pk_bf16_f32 v171, v132, v133
	s_mov_b64 vcc, s[66:67]
	v_cndmask_b32_dpp v222, v168, v44, vcc quad_perm:[1,0,3,2] row_mask:0xf bank_mask:0xf
	v_cndmask_b32_dpp v223, v169, v45, vcc quad_perm:[1,0,3,2] row_mask:0xf bank_mask:0xf
	v_cndmask_b32_dpp v224, v170, v46, vcc quad_perm:[1,0,3,2] row_mask:0xf bank_mask:0xf
	v_cndmask_b32_dpp v225, v171, v47, vcc quad_perm:[1,0,3,2] row_mask:0xf bank_mask:0xf
	s_mov_b64 vcc, s[62:63]
	v_cndmask_b32_dpp v168, v44, v168, vcc quad_perm:[1,0,3,2] row_mask:0xf bank_mask:0xf
	v_cndmask_b32_dpp v169, v45, v169, vcc quad_perm:[1,0,3,2] row_mask:0xf bank_mask:0xf
	v_cndmask_b32_dpp v170, v46, v170, vcc quad_perm:[1,0,3,2] row_mask:0xf bank_mask:0xf
	v_cndmask_b32_dpp v171, v47, v171, vcc quad_perm:[1,0,3,2] row_mask:0xf bank_mask:0xf
	global_store_dwordx4 v49, v[222:225], s[92:93]
	global_store_dwordx4 v49, v[168:171], s[92:93] offset:2048
	v_mov_b32_e32 v130, v173
	s_add_u32 s84, s30, 0x10000
	s_addc_u32 s85, s31, 0
	global_load_dwordx4 v[132:135], v209, s[84:85] offset:0
	global_load_dwordx4 v[136:139], v209, s[84:85] offset:16
	global_load_dwordx4 v[140:143], v209, s[84:85] offset:128
	global_load_dwordx4 v[222:225], v209, s[84:85] offset:144
	s_add_u32 s84, s30, 0x20000
	s_addc_u32 s85, s31, 0
	global_load_dwordx4 v[226:229], v209, s[84:85] offset:0
	global_load_dwordx4 v[230:233], v209, s[84:85] offset:16
	global_load_dwordx4 v[234:237], v209, s[84:85] offset:128
	global_load_dwordx4 v[238:241], v209, s[84:85] offset:144
	s_waitcnt vmcnt(4)
	v_pk_fma_f32 v[126:127], v[126:127], v[174:175], v[132:133]
	v_pk_fma_f32 v[128:129], v[128:129], v[176:177], v[134:135]
	v_pk_fma_f32 v[122:123], v[122:123], v[178:179], v[136:137]
	v_pk_fma_f32 v[124:125], v[124:125], v[180:181], v[138:139]
	v_pk_fma_f32 v[118:119], v[118:119], v[182:183], v[140:141]
	v_pk_fma_f32 v[120:121], v[120:121], v[184:185], v[142:143]
	v_pk_fma_f32 v[114:115], v[114:115], v[186:187], v[222:223]
	v_pk_fma_f32 v[116:117], v[116:117], v[188:189], v[224:225]
	v_mul_f32_e32 v28, v127, v127
	v_mul_f32_e32 v29, v129, v129
	v_mul_f32_e32 v30, v123, v123
	v_mul_f32_e32 v31, v125, v125
	v_fmac_f32_e32 v28, v126, v126
	v_fmac_f32_e32 v29, v128, v128
	v_fmac_f32_e32 v30, v122, v122
	v_fmac_f32_e32 v31, v124, v124
	v_add_f32_e32 v28, v28, v29
	v_add_f32_e32 v30, v30, v31
	v_add_f32_e32 v173, v28, v30
	v_add_u32_e32 v28, 0x80, v126
	v_add_u32_e32 v29, 0x80, v127
	v_add_u32_e32 v30, 0x80, v128
	v_add_u32_e32 v31, 0x80, v129
	v_perm_b32 v44, v29, v28, s78
	v_perm_b32 v45, v31, v30, s78
	v_perm_b32 v26, v29, v28, s79
	v_perm_b32 v27, v31, v30, s79
	v_perm_b32 v32, v27, v26, s60
	v_add_u32_e32 v28, 0x80, v122
	v_add_u32_e32 v29, 0x80, v123
	v_add_u32_e32 v30, 0x80, v124
	v_add_u32_e32 v31, 0x80, v125
	v_perm_b32 v46, v29, v28, s78
	v_perm_b32 v47, v31, v30, s78
	v_perm_b32 v26, v29, v28, s79
	v_perm_b32 v27, v31, v30, s79
	v_perm_b32 v33, v27, v26, s60
	v_mul_f32_e32 v28, v119, v119
	v_mul_f32_e32 v29, v121, v121
	v_mul_f32_e32 v30, v115, v115
	v_mul_f32_e32 v31, v117, v117
	v_fmac_f32_e32 v28, v118, v118
	v_fmac_f32_e32 v29, v120, v120
	v_fmac_f32_e32 v30, v114, v114
	v_fmac_f32_e32 v31, v116, v116
	v_add_f32_e32 v28, v28, v29
	v_add_f32_e32 v30, v30, v31
	v_add_f32_e32 v28, v28, v30
	v_add_f32_e32 v173, v173, v28
	v_add_u32_e32 v28, 0x80, v118
	v_add_u32_e32 v29, 0x80, v119
	v_add_u32_e32 v30, 0x80, v120
	v_add_u32_e32 v31, 0x80, v121
	v_perm_b32 v168, v29, v28, s78
	v_perm_b32 v169, v31, v30, s78
	v_perm_b32 v26, v29, v28, s79
	v_perm_b32 v27, v31, v30, s79
	v_perm_b32 v42, v27, v26, s60
	v_add_u32_e32 v28, 0x80, v114
	v_add_u32_e32 v29, 0x80, v115
	v_add_u32_e32 v30, 0x80, v116
	v_add_u32_e32 v31, 0x80, v117
	v_perm_b32 v170, v29, v28, s78
	v_perm_b32 v171, v31, v30, s78
	v_perm_b32 v26, v29, v28, s79
	v_perm_b32 v27, v31, v30, s79
	v_perm_b32 v43, v27, v26, s60
	s_mov_b64 vcc, s[66:67]
	v_cndmask_b32_dpp v132, v168, v44, vcc quad_perm:[1,0,3,2] row_mask:0xf bank_mask:0xf
	v_cndmask_b32_dpp v133, v169, v45, vcc quad_perm:[1,0,3,2] row_mask:0xf bank_mask:0xf
	v_cndmask_b32_dpp v134, v170, v46, vcc quad_perm:[1,0,3,2] row_mask:0xf bank_mask:0xf
	v_cndmask_b32_dpp v135, v171, v47, vcc quad_perm:[1,0,3,2] row_mask:0xf bank_mask:0xf
	s_mov_b64 vcc, s[62:63]
	v_cndmask_b32_dpp v168, v44, v168, vcc quad_perm:[1,0,3,2] row_mask:0xf bank_mask:0xf
	v_cndmask_b32_dpp v169, v45, v169, vcc quad_perm:[1,0,3,2] row_mask:0xf bank_mask:0xf
	v_cndmask_b32_dpp v170, v46, v170, vcc quad_perm:[1,0,3,2] row_mask:0xf bank_mask:0xf
	v_cndmask_b32_dpp v171, v47, v171, vcc quad_perm:[1,0,3,2] row_mask:0xf bank_mask:0xf
	s_mov_b64 vcc, s[66:67]
	v_cndmask_b32_dpp v136, v42, v32, vcc quad_perm:[1,0,3,2] row_mask:0xf bank_mask:0xf
	v_cndmask_b32_dpp v137, v43, v33, vcc quad_perm:[1,0,3,2] row_mask:0xf bank_mask:0xf
	s_mov_b64 vcc, s[62:63]
	v_cndmask_b32_dpp v42, v32, v42, vcc quad_perm:[1,0,3,2] row_mask:0xf bank_mask:0xf
	v_cndmask_b32_dpp v43, v33, v43, vcc quad_perm:[1,0,3,2] row_mask:0xf bank_mask:0xf
	s_add_u32 s88, s58, 0x8000
	s_addc_u32 s89, s59, 0
	s_add_u32 s90, s74, 0x4000
	s_addc_u32 s91, s75, 0
	global_store_dwordx4 v49, v[132:135], s[88:89]
	global_store_dwordx4 v49, v[168:171], s[88:89] offset:2048
	global_store_dwordx2 v48, v[136:137], s[90:91]
	global_store_dwordx2 v48, v[42:43], s[90:91] offset:1024
	s_add_u32 s92, s96, 0x8000
	s_addc_u32 s93, s97, 0
	v_pk_mul_f32 v[126:127], v[194:195], v[126:127]
	v_pk_mul_f32 v[128:129], v[196:197], v[128:129]
	v_pk_mul_f32 v[122:123], v[210:211], v[122:123]
	v_pk_mul_f32 v[124:125], v[212:213], v[124:125]
	v_cvt_pk_bf16_f32 v44, v126, v127
	v_cvt_pk_bf16_f32 v45, v128, v129
	v_cvt_pk_bf16_f32 v46, v122, v123
	v_cvt_pk_bf16_f32 v47, v124, v125
	v_pk_mul_f32 v[118:119], v[214:215], v[118:119]
	v_pk_mul_f32 v[120:121], v[216:217], v[120:121]
	v_pk_mul_f32 v[114:115], v[218:219], v[114:115]
	v_pk_mul_f32 v[116:117], v[220:221], v[116:117]
	v_cvt_pk_bf16_f32 v168, v118, v119
	v_cvt_pk_bf16_f32 v169, v120, v121
	v_cvt_pk_bf16_f32 v170, v114, v115
	v_cvt_pk_bf16_f32 v171, v116, v117
	s_mov_b64 vcc, s[66:67]
	v_cndmask_b32_dpp v132, v168, v44, vcc quad_perm:[1,0,3,2] row_mask:0xf bank_mask:0xf
	v_cndmask_b32_dpp v133, v169, v45, vcc quad_perm:[1,0,3,2] row_mask:0xf bank_mask:0xf
	v_cndmask_b32_dpp v134, v170, v46, vcc quad_perm:[1,0,3,2] row_mask:0xf bank_mask:0xf
	v_cndmask_b32_dpp v135, v171, v47, vcc quad_perm:[1,0,3,2] row_mask:0xf bank_mask:0xf
	s_mov_b64 vcc, s[62:63]
	v_cndmask_b32_dpp v168, v44, v168, vcc quad_perm:[1,0,3,2] row_mask:0xf bank_mask:0xf
	v_cndmask_b32_dpp v169, v45, v169, vcc quad_perm:[1,0,3,2] row_mask:0xf bank_mask:0xf
	v_cndmask_b32_dpp v170, v46, v170, vcc quad_perm:[1,0,3,2] row_mask:0xf bank_mask:0xf
	v_cndmask_b32_dpp v171, v47, v171, vcc quad_perm:[1,0,3,2] row_mask:0xf bank_mask:0xf
	global_store_dwordx4 v49, v[132:135], s[92:93]
	global_store_dwordx4 v49, v[168:171], s[92:93] offset:2048
	v_mov_b32_e32 v114, v173
	s_add_u32 s84, s30, 0x30000
	s_addc_u32 s85, s31, 0
	global_load_dwordx4 v[116:119], v209, s[84:85] offset:0
	global_load_dwordx4 v[120:123], v209, s[84:85] offset:16
	global_load_dwordx4 v[124:127], v209, s[84:85] offset:128
	global_load_dwordx4 v[132:135], v209, s[84:85] offset:144
	s_waitcnt vmcnt(10)
	v_pk_fma_f32 v[110:111], v[110:111], v[174:175], v[226:227]
	v_pk_fma_f32 v[112:113], v[112:113], v[176:177], v[228:229]
	v_pk_fma_f32 v[106:107], v[106:107], v[178:179], v[230:231]
	v_pk_fma_f32 v[108:109], v[108:109], v[180:181], v[232:233]
	v_pk_fma_f32 v[102:103], v[102:103], v[182:183], v[234:235]
	v_pk_fma_f32 v[104:105], v[104:105], v[184:185], v[236:237]
	v_pk_fma_f32 v[98:99], v[98:99], v[186:187], v[238:239]
	v_pk_fma_f32 v[100:101], v[100:101], v[188:189], v[240:241]
	v_mul_f32_e32 v28, v111, v111
	v_mul_f32_e32 v29, v113, v113
	v_mul_f32_e32 v30, v107, v107
	v_mul_f32_e32 v31, v109, v109
	v_fmac_f32_e32 v28, v110, v110
	v_fmac_f32_e32 v29, v112, v112
	v_fmac_f32_e32 v30, v106, v106
	v_fmac_f32_e32 v31, v108, v108
	v_add_f32_e32 v28, v28, v29
	v_add_f32_e32 v30, v30, v31
	v_add_f32_e32 v173, v28, v30
	v_add_u32_e32 v28, 0x80, v110
	v_add_u32_e32 v29, 0x80, v111
	v_add_u32_e32 v30, 0x80, v112
	v_add_u32_e32 v31, 0x80, v113
	v_perm_b32 v44, v29, v28, s78
	v_perm_b32 v45, v31, v30, s78
	v_perm_b32 v26, v29, v28, s79
	v_perm_b32 v27, v31, v30, s79
	v_perm_b32 v32, v27, v26, s60
	v_add_u32_e32 v28, 0x80, v106
	v_add_u32_e32 v29, 0x80, v107
	v_add_u32_e32 v30, 0x80, v108
	v_add_u32_e32 v31, 0x80, v109
	v_perm_b32 v46, v29, v28, s78
	v_perm_b32 v47, v31, v30, s78
	v_perm_b32 v26, v29, v28, s79
	v_perm_b32 v27, v31, v30, s79
	v_perm_b32 v33, v27, v26, s60
	v_mul_f32_e32 v28, v103, v103
	v_mul_f32_e32 v29, v105, v105
	v_mul_f32_e32 v30, v99, v99
	v_mul_f32_e32 v31, v101, v101
	v_fmac_f32_e32 v28, v102, v102
	v_fmac_f32_e32 v29, v104, v104
	v_fmac_f32_e32 v30, v98, v98
	v_fmac_f32_e32 v31, v100, v100
	v_add_f32_e32 v28, v28, v29
	v_add_f32_e32 v30, v30, v31
	v_add_f32_e32 v28, v28, v30
	v_add_f32_e32 v173, v173, v28
	v_add_u32_e32 v28, 0x80, v102
	v_add_u32_e32 v29, 0x80, v103
	v_add_u32_e32 v30, 0x80, v104
	v_add_u32_e32 v31, 0x80, v105
	v_perm_b32 v168, v29, v28, s78
	v_perm_b32 v169, v31, v30, s78
	v_perm_b32 v26, v29, v28, s79
	v_perm_b32 v27, v31, v30, s79
	v_perm_b32 v42, v27, v26, s60
	v_add_u32_e32 v28, 0x80, v98
	v_add_u32_e32 v29, 0x80, v99
	v_add_u32_e32 v30, 0x80, v100
	v_add_u32_e32 v31, 0x80, v101
	v_perm_b32 v170, v29, v28, s78
	v_perm_b32 v171, v31, v30, s78
	v_perm_b32 v26, v29, v28, s79
	v_perm_b32 v27, v31, v30, s79
	v_perm_b32 v43, v27, v26, s60
	s_mov_b64 vcc, s[66:67]
	v_cndmask_b32_dpp v226, v168, v44, vcc quad_perm:[1,0,3,2] row_mask:0xf bank_mask:0xf
	v_cndmask_b32_dpp v227, v169, v45, vcc quad_perm:[1,0,3,2] row_mask:0xf bank_mask:0xf
	v_cndmask_b32_dpp v228, v170, v46, vcc quad_perm:[1,0,3,2] row_mask:0xf bank_mask:0xf
	v_cndmask_b32_dpp v229, v171, v47, vcc quad_perm:[1,0,3,2] row_mask:0xf bank_mask:0xf
	s_mov_b64 vcc, s[62:63]
	v_cndmask_b32_dpp v168, v44, v168, vcc quad_perm:[1,0,3,2] row_mask:0xf bank_mask:0xf
	v_cndmask_b32_dpp v169, v45, v169, vcc quad_perm:[1,0,3,2] row_mask:0xf bank_mask:0xf
	v_cndmask_b32_dpp v170, v46, v170, vcc quad_perm:[1,0,3,2] row_mask:0xf bank_mask:0xf
	v_cndmask_b32_dpp v171, v47, v171, vcc quad_perm:[1,0,3,2] row_mask:0xf bank_mask:0xf
	s_mov_b64 vcc, s[66:67]
	v_cndmask_b32_dpp v230, v42, v32, vcc quad_perm:[1,0,3,2] row_mask:0xf bank_mask:0xf
	v_cndmask_b32_dpp v231, v43, v33, vcc quad_perm:[1,0,3,2] row_mask:0xf bank_mask:0xf
	s_mov_b64 vcc, s[62:63]
	v_cndmask_b32_dpp v42, v32, v42, vcc quad_perm:[1,0,3,2] row_mask:0xf bank_mask:0xf
	v_cndmask_b32_dpp v43, v33, v43, vcc quad_perm:[1,0,3,2] row_mask:0xf bank_mask:0xf
	s_add_u32 s88, s58, 0x10000
	s_addc_u32 s89, s59, 0
	s_add_u32 s90, s74, 0x8000
	s_addc_u32 s91, s75, 0
	global_store_dwordx4 v49, v[226:229], s[88:89]
	global_store_dwordx4 v49, v[168:171], s[88:89] offset:2048
	global_store_dwordx2 v48, v[230:231], s[90:91]
	global_store_dwordx2 v48, v[42:43], s[90:91] offset:1024
	s_add_u32 s92, s96, 0x10000
	s_addc_u32 s93, s97, 0
	v_pk_mul_f32 v[110:111], v[194:195], v[110:111]
	v_pk_mul_f32 v[112:113], v[196:197], v[112:113]
	v_pk_mul_f32 v[106:107], v[210:211], v[106:107]
	v_pk_mul_f32 v[108:109], v[212:213], v[108:109]
	v_cvt_pk_bf16_f32 v44, v110, v111
	v_cvt_pk_bf16_f32 v45, v112, v113
	v_cvt_pk_bf16_f32 v46, v106, v107
	v_cvt_pk_bf16_f32 v47, v108, v109
	v_pk_mul_f32 v[102:103], v[214:215], v[102:103]
	v_pk_mul_f32 v[104:105], v[216:217], v[104:105]
	v_pk_mul_f32 v[98:99], v[218:219], v[98:99]
	v_pk_mul_f32 v[100:101], v[220:221], v[100:101]
	v_cvt_pk_bf16_f32 v168, v102, v103
	v_cvt_pk_bf16_f32 v169, v104, v105
	v_cvt_pk_bf16_f32 v170, v98, v99
	v_cvt_pk_bf16_f32 v171, v100, v101
	s_mov_b64 vcc, s[66:67]
	v_cndmask_b32_dpp v226, v168, v44, vcc quad_perm:[1,0,3,2] row_mask:0xf bank_mask:0xf
	v_cndmask_b32_dpp v227, v169, v45, vcc quad_perm:[1,0,3,2] row_mask:0xf bank_mask:0xf
	v_cndmask_b32_dpp v228, v170, v46, vcc quad_perm:[1,0,3,2] row_mask:0xf bank_mask:0xf
	v_cndmask_b32_dpp v229, v171, v47, vcc quad_perm:[1,0,3,2] row_mask:0xf bank_mask:0xf
	s_mov_b64 vcc, s[62:63]
	v_cndmask_b32_dpp v168, v44, v168, vcc quad_perm:[1,0,3,2] row_mask:0xf bank_mask:0xf
	v_cndmask_b32_dpp v169, v45, v169, vcc quad_perm:[1,0,3,2] row_mask:0xf bank_mask:0xf
	v_cndmask_b32_dpp v170, v46, v170, vcc quad_perm:[1,0,3,2] row_mask:0xf bank_mask:0xf
	v_cndmask_b32_dpp v171, v47, v171, vcc quad_perm:[1,0,3,2] row_mask:0xf bank_mask:0xf
	global_store_dwordx4 v49, v[226:229], s[92:93]
	global_store_dwordx4 v49, v[168:171], s[92:93] offset:2048
	v_mov_b32_e32 v98, v173
	s_add_u32 s84, s30, 0x80000
	s_addc_u32 s85, s31, 0
	global_load_dwordx4 v[100:103], v209, s[84:85] offset:0
	global_load_dwordx4 v[104:107], v209, s[84:85] offset:16
	global_load_dwordx4 v[108:111], v209, s[84:85] offset:128
	global_load_dwordx4 v[136:139], v209, s[84:85] offset:144
	s_waitcnt vmcnt(10)
	v_pk_fma_f32 v[94:95], v[94:95], v[174:175], v[116:117]
	v_pk_fma_f32 v[96:97], v[96:97], v[176:177], v[118:119]
	v_pk_fma_f32 v[90:91], v[90:91], v[178:179], v[120:121]
	v_pk_fma_f32 v[92:93], v[92:93], v[180:181], v[122:123]
	v_pk_fma_f32 v[86:87], v[86:87], v[182:183], v[124:125]
	v_pk_fma_f32 v[88:89], v[88:89], v[184:185], v[126:127]
	v_pk_fma_f32 v[82:83], v[82:83], v[186:187], v[132:133]
	v_pk_fma_f32 v[84:85], v[84:85], v[188:189], v[134:135]
	v_mul_f32_e32 v28, v95, v95
	v_mul_f32_e32 v29, v97, v97
	v_mul_f32_e32 v30, v91, v91
	v_mul_f32_e32 v31, v93, v93
	v_fmac_f32_e32 v28, v94, v94
	v_fmac_f32_e32 v29, v96, v96
	v_fmac_f32_e32 v30, v90, v90
	v_fmac_f32_e32 v31, v92, v92
	v_add_f32_e32 v28, v28, v29
	v_add_f32_e32 v30, v30, v31
	v_add_f32_e32 v173, v28, v30
	v_add_u32_e32 v28, 0x80, v94
	v_add_u32_e32 v29, 0x80, v95
	v_add_u32_e32 v30, 0x80, v96
	v_add_u32_e32 v31, 0x80, v97
	v_perm_b32 v44, v29, v28, s78
	v_perm_b32 v45, v31, v30, s78
	v_perm_b32 v26, v29, v28, s79
	v_perm_b32 v27, v31, v30, s79
	v_perm_b32 v32, v27, v26, s60
	v_add_u32_e32 v28, 0x80, v90
	v_add_u32_e32 v29, 0x80, v91
	v_add_u32_e32 v30, 0x80, v92
	v_add_u32_e32 v31, 0x80, v93
	v_perm_b32 v46, v29, v28, s78
	v_perm_b32 v47, v31, v30, s78
	v_perm_b32 v26, v29, v28, s79
	v_perm_b32 v27, v31, v30, s79
	v_perm_b32 v33, v27, v26, s60
	v_mul_f32_e32 v28, v87, v87
	v_mul_f32_e32 v29, v89, v89
	v_mul_f32_e32 v30, v83, v83
	v_mul_f32_e32 v31, v85, v85
	v_fmac_f32_e32 v28, v86, v86
	v_fmac_f32_e32 v29, v88, v88
	v_fmac_f32_e32 v30, v82, v82
	v_fmac_f32_e32 v31, v84, v84
	v_add_f32_e32 v28, v28, v29
	v_add_f32_e32 v30, v30, v31
	v_add_f32_e32 v28, v28, v30
	v_add_f32_e32 v173, v173, v28
	v_add_u32_e32 v28, 0x80, v86
	v_add_u32_e32 v29, 0x80, v87
	v_add_u32_e32 v30, 0x80, v88
	v_add_u32_e32 v31, 0x80, v89
	v_perm_b32 v168, v29, v28, s78
	v_perm_b32 v169, v31, v30, s78
	v_perm_b32 v26, v29, v28, s79
	v_perm_b32 v27, v31, v30, s79
	v_perm_b32 v42, v27, v26, s60
	v_add_u32_e32 v28, 0x80, v82
	v_add_u32_e32 v29, 0x80, v83
	v_add_u32_e32 v30, 0x80, v84
	v_add_u32_e32 v31, 0x80, v85
	v_perm_b32 v170, v29, v28, s78
	v_perm_b32 v171, v31, v30, s78
	v_perm_b32 v26, v29, v28, s79
	v_perm_b32 v27, v31, v30, s79
	v_perm_b32 v43, v27, v26, s60
	s_mov_b64 vcc, s[66:67]
	v_cndmask_b32_dpp v116, v168, v44, vcc quad_perm:[1,0,3,2] row_mask:0xf bank_mask:0xf
	v_cndmask_b32_dpp v117, v169, v45, vcc quad_perm:[1,0,3,2] row_mask:0xf bank_mask:0xf
	v_cndmask_b32_dpp v118, v170, v46, vcc quad_perm:[1,0,3,2] row_mask:0xf bank_mask:0xf
	v_cndmask_b32_dpp v119, v171, v47, vcc quad_perm:[1,0,3,2] row_mask:0xf bank_mask:0xf
	s_mov_b64 vcc, s[62:63]
	v_cndmask_b32_dpp v168, v44, v168, vcc quad_perm:[1,0,3,2] row_mask:0xf bank_mask:0xf
	v_cndmask_b32_dpp v169, v45, v169, vcc quad_perm:[1,0,3,2] row_mask:0xf bank_mask:0xf
	v_cndmask_b32_dpp v170, v46, v170, vcc quad_perm:[1,0,3,2] row_mask:0xf bank_mask:0xf
	v_cndmask_b32_dpp v171, v47, v171, vcc quad_perm:[1,0,3,2] row_mask:0xf bank_mask:0xf
	s_mov_b64 vcc, s[66:67]
	v_cndmask_b32_dpp v120, v42, v32, vcc quad_perm:[1,0,3,2] row_mask:0xf bank_mask:0xf
	v_cndmask_b32_dpp v121, v43, v33, vcc quad_perm:[1,0,3,2] row_mask:0xf bank_mask:0xf
	s_mov_b64 vcc, s[62:63]
	v_cndmask_b32_dpp v42, v32, v42, vcc quad_perm:[1,0,3,2] row_mask:0xf bank_mask:0xf
	v_cndmask_b32_dpp v43, v33, v43, vcc quad_perm:[1,0,3,2] row_mask:0xf bank_mask:0xf
	s_add_u32 s88, s58, 0x18000
	s_addc_u32 s89, s59, 0
	s_add_u32 s90, s74, 0xc000
	s_addc_u32 s91, s75, 0
	global_store_dwordx4 v49, v[116:119], s[88:89]
	global_store_dwordx4 v49, v[168:171], s[88:89] offset:2048
	global_store_dwordx2 v48, v[120:121], s[90:91]
	global_store_dwordx2 v48, v[42:43], s[90:91] offset:1024
	s_add_u32 s92, s96, 0x18000
	s_addc_u32 s93, s97, 0
	v_pk_mul_f32 v[94:95], v[194:195], v[94:95]
	v_pk_mul_f32 v[96:97], v[196:197], v[96:97]
	v_pk_mul_f32 v[90:91], v[210:211], v[90:91]
	v_pk_mul_f32 v[92:93], v[212:213], v[92:93]
	v_cvt_pk_bf16_f32 v44, v94, v95
	v_cvt_pk_bf16_f32 v45, v96, v97
	v_cvt_pk_bf16_f32 v46, v90, v91
	v_cvt_pk_bf16_f32 v47, v92, v93
	v_pk_mul_f32 v[86:87], v[214:215], v[86:87]
	v_pk_mul_f32 v[88:89], v[216:217], v[88:89]
	v_pk_mul_f32 v[82:83], v[218:219], v[82:83]
	v_pk_mul_f32 v[84:85], v[220:221], v[84:85]
	v_cvt_pk_bf16_f32 v168, v86, v87
	v_cvt_pk_bf16_f32 v169, v88, v89
	v_cvt_pk_bf16_f32 v170, v82, v83
	v_cvt_pk_bf16_f32 v171, v84, v85
	s_mov_b64 vcc, s[66:67]
	v_cndmask_b32_dpp v116, v168, v44, vcc quad_perm:[1,0,3,2] row_mask:0xf bank_mask:0xf
	v_cndmask_b32_dpp v117, v169, v45, vcc quad_perm:[1,0,3,2] row_mask:0xf bank_mask:0xf
	v_cndmask_b32_dpp v118, v170, v46, vcc quad_perm:[1,0,3,2] row_mask:0xf bank_mask:0xf
	v_cndmask_b32_dpp v119, v171, v47, vcc quad_perm:[1,0,3,2] row_mask:0xf bank_mask:0xf
	s_mov_b64 vcc, s[62:63]
	v_cndmask_b32_dpp v168, v44, v168, vcc quad_perm:[1,0,3,2] row_mask:0xf bank_mask:0xf
	v_cndmask_b32_dpp v169, v45, v169, vcc quad_perm:[1,0,3,2] row_mask:0xf bank_mask:0xf
	v_cndmask_b32_dpp v170, v46, v170, vcc quad_perm:[1,0,3,2] row_mask:0xf bank_mask:0xf
	v_cndmask_b32_dpp v171, v47, v171, vcc quad_perm:[1,0,3,2] row_mask:0xf bank_mask:0xf
	global_store_dwordx4 v49, v[116:119], s[92:93]
	global_store_dwordx4 v49, v[168:171], s[92:93] offset:2048
	v_mov_b32_e32 v82, v173
	s_add_u32 s84, s30, 0x90000
	s_addc_u32 s85, s31, 0
	global_load_dwordx4 v[84:87], v209, s[84:85] offset:0
	global_load_dwordx4 v[88:91], v209, s[84:85] offset:16
	global_load_dwordx4 v[92:95], v209, s[84:85] offset:128
	global_load_dwordx4 v[116:119], v209, s[84:85] offset:144
	s_waitcnt vmcnt(10)
	v_pk_fma_f32 v[78:79], v[78:79], v[174:175], v[100:101]
	v_pk_fma_f32 v[80:81], v[80:81], v[176:177], v[102:103]
	v_pk_fma_f32 v[74:75], v[74:75], v[178:179], v[104:105]
	v_pk_fma_f32 v[76:77], v[76:77], v[180:181], v[106:107]
	v_pk_fma_f32 v[70:71], v[70:71], v[182:183], v[108:109]
	v_pk_fma_f32 v[72:73], v[72:73], v[184:185], v[110:111]
	v_pk_fma_f32 v[66:67], v[66:67], v[186:187], v[136:137]
	v_pk_fma_f32 v[68:69], v[68:69], v[188:189], v[138:139]
	v_mul_f32_e32 v28, v79, v79
	v_mul_f32_e32 v29, v81, v81
	v_mul_f32_e32 v30, v75, v75
	v_mul_f32_e32 v31, v77, v77
	v_fmac_f32_e32 v28, v78, v78
	v_fmac_f32_e32 v29, v80, v80
	v_fmac_f32_e32 v30, v74, v74
	v_fmac_f32_e32 v31, v76, v76
	v_add_f32_e32 v28, v28, v29
	v_add_f32_e32 v30, v30, v31
	v_add_f32_e32 v173, v28, v30
	v_add_u32_e32 v28, 0x80, v78
	v_add_u32_e32 v29, 0x80, v79
	v_add_u32_e32 v30, 0x80, v80
	v_add_u32_e32 v31, 0x80, v81
	v_perm_b32 v44, v29, v28, s78
	v_perm_b32 v45, v31, v30, s78
	v_perm_b32 v26, v29, v28, s79
	v_perm_b32 v27, v31, v30, s79
	v_perm_b32 v32, v27, v26, s60
	v_add_u32_e32 v28, 0x80, v74
	v_add_u32_e32 v29, 0x80, v75
	v_add_u32_e32 v30, 0x80, v76
	v_add_u32_e32 v31, 0x80, v77
	v_perm_b32 v46, v29, v28, s78
	v_perm_b32 v47, v31, v30, s78
	v_perm_b32 v26, v29, v28, s79
	v_perm_b32 v27, v31, v30, s79
	v_perm_b32 v33, v27, v26, s60
	v_mul_f32_e32 v28, v71, v71
	v_mul_f32_e32 v29, v73, v73
	v_mul_f32_e32 v30, v67, v67
	v_mul_f32_e32 v31, v69, v69
	v_fmac_f32_e32 v28, v70, v70
	v_fmac_f32_e32 v29, v72, v72
	v_fmac_f32_e32 v30, v66, v66
	v_fmac_f32_e32 v31, v68, v68
	v_add_f32_e32 v28, v28, v29
	v_add_f32_e32 v30, v30, v31
	v_add_f32_e32 v28, v28, v30
	v_add_f32_e32 v173, v173, v28
	v_add_u32_e32 v28, 0x80, v70
	v_add_u32_e32 v29, 0x80, v71
	v_add_u32_e32 v30, 0x80, v72
	v_add_u32_e32 v31, 0x80, v73
	v_perm_b32 v168, v29, v28, s78
	v_perm_b32 v169, v31, v30, s78
	v_perm_b32 v26, v29, v28, s79
	v_perm_b32 v27, v31, v30, s79
	v_perm_b32 v42, v27, v26, s60
	v_add_u32_e32 v28, 0x80, v66
	v_add_u32_e32 v29, 0x80, v67
	v_add_u32_e32 v30, 0x80, v68
	v_add_u32_e32 v31, 0x80, v69
	v_perm_b32 v170, v29, v28, s78
	v_perm_b32 v171, v31, v30, s78
	v_perm_b32 v26, v29, v28, s79
	v_perm_b32 v27, v31, v30, s79
	v_perm_b32 v43, v27, v26, s60
	s_mov_b64 vcc, s[66:67]
	v_cndmask_b32_dpp v100, v168, v44, vcc quad_perm:[1,0,3,2] row_mask:0xf bank_mask:0xf
	v_cndmask_b32_dpp v101, v169, v45, vcc quad_perm:[1,0,3,2] row_mask:0xf bank_mask:0xf
	v_cndmask_b32_dpp v102, v170, v46, vcc quad_perm:[1,0,3,2] row_mask:0xf bank_mask:0xf
	v_cndmask_b32_dpp v103, v171, v47, vcc quad_perm:[1,0,3,2] row_mask:0xf bank_mask:0xf
	s_mov_b64 vcc, s[62:63]
	v_cndmask_b32_dpp v168, v44, v168, vcc quad_perm:[1,0,3,2] row_mask:0xf bank_mask:0xf
	v_cndmask_b32_dpp v169, v45, v169, vcc quad_perm:[1,0,3,2] row_mask:0xf bank_mask:0xf
	v_cndmask_b32_dpp v170, v46, v170, vcc quad_perm:[1,0,3,2] row_mask:0xf bank_mask:0xf
	v_cndmask_b32_dpp v171, v47, v171, vcc quad_perm:[1,0,3,2] row_mask:0xf bank_mask:0xf
	s_mov_b64 vcc, s[66:67]
	v_cndmask_b32_dpp v104, v42, v32, vcc quad_perm:[1,0,3,2] row_mask:0xf bank_mask:0xf
	v_cndmask_b32_dpp v105, v43, v33, vcc quad_perm:[1,0,3,2] row_mask:0xf bank_mask:0xf
	s_mov_b64 vcc, s[62:63]
	v_cndmask_b32_dpp v42, v32, v42, vcc quad_perm:[1,0,3,2] row_mask:0xf bank_mask:0xf
	v_cndmask_b32_dpp v43, v33, v43, vcc quad_perm:[1,0,3,2] row_mask:0xf bank_mask:0xf
	s_add_u32 s88, s58, 0x40000
	s_addc_u32 s89, s59, 0
	s_add_u32 s90, s74, 0x20000
	s_addc_u32 s91, s75, 0
	global_store_dwordx4 v49, v[100:103], s[88:89]
	global_store_dwordx4 v49, v[168:171], s[88:89] offset:2048
	global_store_dwordx2 v48, v[104:105], s[90:91]
	global_store_dwordx2 v48, v[42:43], s[90:91] offset:1024
	s_add_u32 s92, s96, 0x40000
	s_addc_u32 s93, s97, 0
	v_pk_mul_f32 v[78:79], v[194:195], v[78:79]
	v_pk_mul_f32 v[80:81], v[196:197], v[80:81]
	v_pk_mul_f32 v[74:75], v[210:211], v[74:75]
	v_pk_mul_f32 v[76:77], v[212:213], v[76:77]
	v_cvt_pk_bf16_f32 v44, v78, v79
	v_cvt_pk_bf16_f32 v45, v80, v81
	v_cvt_pk_bf16_f32 v46, v74, v75
	v_cvt_pk_bf16_f32 v47, v76, v77
	v_pk_mul_f32 v[70:71], v[214:215], v[70:71]
	v_pk_mul_f32 v[72:73], v[216:217], v[72:73]
	v_pk_mul_f32 v[66:67], v[218:219], v[66:67]
	v_pk_mul_f32 v[68:69], v[220:221], v[68:69]
	v_cvt_pk_bf16_f32 v168, v70, v71
	v_cvt_pk_bf16_f32 v169, v72, v73
	v_cvt_pk_bf16_f32 v170, v66, v67
	v_cvt_pk_bf16_f32 v171, v68, v69
	s_mov_b64 vcc, s[66:67]
	v_cndmask_b32_dpp v100, v168, v44, vcc quad_perm:[1,0,3,2] row_mask:0xf bank_mask:0xf
	v_cndmask_b32_dpp v101, v169, v45, vcc quad_perm:[1,0,3,2] row_mask:0xf bank_mask:0xf
	v_cndmask_b32_dpp v102, v170, v46, vcc quad_perm:[1,0,3,2] row_mask:0xf bank_mask:0xf
	v_cndmask_b32_dpp v103, v171, v47, vcc quad_perm:[1,0,3,2] row_mask:0xf bank_mask:0xf
	s_mov_b64 vcc, s[62:63]
	v_cndmask_b32_dpp v168, v44, v168, vcc quad_perm:[1,0,3,2] row_mask:0xf bank_mask:0xf
	v_cndmask_b32_dpp v169, v45, v169, vcc quad_perm:[1,0,3,2] row_mask:0xf bank_mask:0xf
	v_cndmask_b32_dpp v170, v46, v170, vcc quad_perm:[1,0,3,2] row_mask:0xf bank_mask:0xf
	v_cndmask_b32_dpp v171, v47, v171, vcc quad_perm:[1,0,3,2] row_mask:0xf bank_mask:0xf
	global_store_dwordx4 v49, v[100:103], s[92:93]
	global_store_dwordx4 v49, v[168:171], s[92:93] offset:2048
	v_mov_b32_e32 v66, v173
	s_add_u32 s84, s30, 0xa0000
	s_addc_u32 s85, s31, 0
	global_load_dwordx4 v[68:71], v209, s[84:85] offset:0
	global_load_dwordx4 v[72:75], v209, s[84:85] offset:16
	global_load_dwordx4 v[76:79], v209, s[84:85] offset:128
	global_load_dwordx4 v[100:103], v209, s[84:85] offset:144
	s_waitcnt vmcnt(10)
	v_pk_fma_f32 v[62:63], v[62:63], v[174:175], v[84:85]
	v_pk_fma_f32 v[64:65], v[64:65], v[176:177], v[86:87]
	v_pk_fma_f32 v[58:59], v[58:59], v[178:179], v[88:89]
	v_pk_fma_f32 v[60:61], v[60:61], v[180:181], v[90:91]
	v_pk_fma_f32 v[54:55], v[54:55], v[182:183], v[92:93]
	v_pk_fma_f32 v[56:57], v[56:57], v[184:185], v[94:95]
	v_pk_fma_f32 v[50:51], v[50:51], v[186:187], v[116:117]
	v_pk_fma_f32 v[52:53], v[52:53], v[188:189], v[118:119]
	v_mul_f32_e32 v28, v63, v63
	v_mul_f32_e32 v29, v65, v65
	v_mul_f32_e32 v30, v59, v59
	v_mul_f32_e32 v31, v61, v61
	v_fmac_f32_e32 v28, v62, v62
	v_fmac_f32_e32 v29, v64, v64
	v_fmac_f32_e32 v30, v58, v58
	v_fmac_f32_e32 v31, v60, v60
	v_add_f32_e32 v28, v28, v29
	v_add_f32_e32 v30, v30, v31
	v_add_f32_e32 v173, v28, v30
	v_add_u32_e32 v28, 0x80, v62
	v_add_u32_e32 v29, 0x80, v63
	v_add_u32_e32 v30, 0x80, v64
	v_add_u32_e32 v31, 0x80, v65
	v_perm_b32 v44, v29, v28, s78
	v_perm_b32 v45, v31, v30, s78
	v_perm_b32 v26, v29, v28, s79
	v_perm_b32 v27, v31, v30, s79
	v_perm_b32 v32, v27, v26, s60
	v_add_u32_e32 v28, 0x80, v58
	v_add_u32_e32 v29, 0x80, v59
	v_add_u32_e32 v30, 0x80, v60
	v_add_u32_e32 v31, 0x80, v61
	v_perm_b32 v46, v29, v28, s78
	v_perm_b32 v47, v31, v30, s78
	v_perm_b32 v26, v29, v28, s79
	v_perm_b32 v27, v31, v30, s79
	v_perm_b32 v33, v27, v26, s60
	v_mul_f32_e32 v28, v55, v55
	v_mul_f32_e32 v29, v57, v57
	v_mul_f32_e32 v30, v51, v51
	v_mul_f32_e32 v31, v53, v53
	v_fmac_f32_e32 v28, v54, v54
	v_fmac_f32_e32 v29, v56, v56
	v_fmac_f32_e32 v30, v50, v50
	v_fmac_f32_e32 v31, v52, v52
	v_add_f32_e32 v28, v28, v29
	v_add_f32_e32 v30, v30, v31
	v_add_f32_e32 v28, v28, v30
	v_add_f32_e32 v173, v173, v28
	v_add_u32_e32 v28, 0x80, v54
	v_add_u32_e32 v29, 0x80, v55
	v_add_u32_e32 v30, 0x80, v56
	v_add_u32_e32 v31, 0x80, v57
	v_perm_b32 v168, v29, v28, s78
	v_perm_b32 v169, v31, v30, s78
	v_perm_b32 v26, v29, v28, s79
	v_perm_b32 v27, v31, v30, s79
	v_perm_b32 v42, v27, v26, s60
	v_add_u32_e32 v28, 0x80, v50
	v_add_u32_e32 v29, 0x80, v51
	v_add_u32_e32 v30, 0x80, v52
	v_add_u32_e32 v31, 0x80, v53
	v_perm_b32 v170, v29, v28, s78
	v_perm_b32 v171, v31, v30, s78
	v_perm_b32 v26, v29, v28, s79
	v_perm_b32 v27, v31, v30, s79
	v_perm_b32 v43, v27, v26, s60
	s_mov_b64 vcc, s[66:67]
	v_cndmask_b32_dpp v84, v168, v44, vcc quad_perm:[1,0,3,2] row_mask:0xf bank_mask:0xf
	v_cndmask_b32_dpp v85, v169, v45, vcc quad_perm:[1,0,3,2] row_mask:0xf bank_mask:0xf
	v_cndmask_b32_dpp v86, v170, v46, vcc quad_perm:[1,0,3,2] row_mask:0xf bank_mask:0xf
	v_cndmask_b32_dpp v87, v171, v47, vcc quad_perm:[1,0,3,2] row_mask:0xf bank_mask:0xf
	s_mov_b64 vcc, s[62:63]
	v_cndmask_b32_dpp v168, v44, v168, vcc quad_perm:[1,0,3,2] row_mask:0xf bank_mask:0xf
	v_cndmask_b32_dpp v169, v45, v169, vcc quad_perm:[1,0,3,2] row_mask:0xf bank_mask:0xf
	v_cndmask_b32_dpp v170, v46, v170, vcc quad_perm:[1,0,3,2] row_mask:0xf bank_mask:0xf
	v_cndmask_b32_dpp v171, v47, v171, vcc quad_perm:[1,0,3,2] row_mask:0xf bank_mask:0xf
	s_mov_b64 vcc, s[66:67]
	v_cndmask_b32_dpp v88, v42, v32, vcc quad_perm:[1,0,3,2] row_mask:0xf bank_mask:0xf
	v_cndmask_b32_dpp v89, v43, v33, vcc quad_perm:[1,0,3,2] row_mask:0xf bank_mask:0xf
	s_mov_b64 vcc, s[62:63]
	v_cndmask_b32_dpp v42, v32, v42, vcc quad_perm:[1,0,3,2] row_mask:0xf bank_mask:0xf
	v_cndmask_b32_dpp v43, v33, v43, vcc quad_perm:[1,0,3,2] row_mask:0xf bank_mask:0xf
	s_add_u32 s88, s58, 0x48000
	s_addc_u32 s89, s59, 0
	s_add_u32 s90, s74, 0x24000
	s_addc_u32 s91, s75, 0
	global_store_dwordx4 v49, v[84:87], s[88:89]
	global_store_dwordx4 v49, v[168:171], s[88:89] offset:2048
	global_store_dwordx2 v48, v[88:89], s[90:91]
	global_store_dwordx2 v48, v[42:43], s[90:91] offset:1024
	s_add_u32 s92, s96, 0x48000
	s_addc_u32 s93, s97, 0
	v_pk_mul_f32 v[62:63], v[194:195], v[62:63]
	v_pk_mul_f32 v[64:65], v[196:197], v[64:65]
	v_pk_mul_f32 v[58:59], v[210:211], v[58:59]
	v_pk_mul_f32 v[60:61], v[212:213], v[60:61]
	v_cvt_pk_bf16_f32 v44, v62, v63
	v_cvt_pk_bf16_f32 v45, v64, v65
	v_cvt_pk_bf16_f32 v46, v58, v59
	v_cvt_pk_bf16_f32 v47, v60, v61
	v_pk_mul_f32 v[54:55], v[214:215], v[54:55]
	v_pk_mul_f32 v[56:57], v[216:217], v[56:57]
	v_pk_mul_f32 v[50:51], v[218:219], v[50:51]
	v_pk_mul_f32 v[52:53], v[220:221], v[52:53]
	v_cvt_pk_bf16_f32 v168, v54, v55
	v_cvt_pk_bf16_f32 v169, v56, v57
	v_cvt_pk_bf16_f32 v170, v50, v51
	v_cvt_pk_bf16_f32 v171, v52, v53
	s_mov_b64 vcc, s[66:67]
	v_cndmask_b32_dpp v84, v168, v44, vcc quad_perm:[1,0,3,2] row_mask:0xf bank_mask:0xf
	v_cndmask_b32_dpp v85, v169, v45, vcc quad_perm:[1,0,3,2] row_mask:0xf bank_mask:0xf
	v_cndmask_b32_dpp v86, v170, v46, vcc quad_perm:[1,0,3,2] row_mask:0xf bank_mask:0xf
	v_cndmask_b32_dpp v87, v171, v47, vcc quad_perm:[1,0,3,2] row_mask:0xf bank_mask:0xf
	s_mov_b64 vcc, s[62:63]
	v_cndmask_b32_dpp v168, v44, v168, vcc quad_perm:[1,0,3,2] row_mask:0xf bank_mask:0xf
	v_cndmask_b32_dpp v169, v45, v169, vcc quad_perm:[1,0,3,2] row_mask:0xf bank_mask:0xf
	v_cndmask_b32_dpp v170, v46, v170, vcc quad_perm:[1,0,3,2] row_mask:0xf bank_mask:0xf
	v_cndmask_b32_dpp v171, v47, v171, vcc quad_perm:[1,0,3,2] row_mask:0xf bank_mask:0xf
	global_store_dwordx4 v49, v[84:87], s[92:93]
	global_store_dwordx4 v49, v[168:171], s[92:93] offset:2048
	v_mov_b32_e32 v50, v173
	s_add_u32 s84, s30, 0xb0000
	s_addc_u32 s85, s31, 0
	global_load_dwordx4 v[52:55], v209, s[84:85] offset:0
	global_load_dwordx4 v[56:59], v209, s[84:85] offset:16
	global_load_dwordx4 v[60:63], v209, s[84:85] offset:128
	global_load_dwordx4 v[84:87], v209, s[84:85] offset:144
	s_waitcnt vmcnt(10)
	v_pk_fma_f32 v[38:39], v[38:39], v[174:175], v[68:69]
	v_pk_fma_f32 v[40:41], v[40:41], v[176:177], v[70:71]
	v_pk_fma_f32 v[34:35], v[34:35], v[178:179], v[72:73]
	v_pk_fma_f32 v[36:37], v[36:37], v[180:181], v[74:75]
	v_pk_fma_f32 v[22:23], v[22:23], v[182:183], v[76:77]
	v_pk_fma_f32 v[24:25], v[24:25], v[184:185], v[78:79]
	v_pk_fma_f32 v[18:19], v[18:19], v[186:187], v[100:101]
	v_pk_fma_f32 v[20:21], v[20:21], v[188:189], v[102:103]
	v_mul_f32_e32 v28, v39, v39
	v_mul_f32_e32 v29, v41, v41
	v_mul_f32_e32 v30, v35, v35
	v_mul_f32_e32 v31, v37, v37
	v_fmac_f32_e32 v28, v38, v38
	v_fmac_f32_e32 v29, v40, v40
	v_fmac_f32_e32 v30, v34, v34
	v_fmac_f32_e32 v31, v36, v36
	v_add_f32_e32 v28, v28, v29
	v_add_f32_e32 v30, v30, v31
	v_add_f32_e32 v173, v28, v30
	v_add_u32_e32 v28, 0x80, v38
	v_add_u32_e32 v29, 0x80, v39
	v_add_u32_e32 v30, 0x80, v40
	v_add_u32_e32 v31, 0x80, v41
	v_perm_b32 v44, v29, v28, s78
	v_perm_b32 v45, v31, v30, s78
	v_perm_b32 v26, v29, v28, s79
	v_perm_b32 v27, v31, v30, s79
	v_perm_b32 v32, v27, v26, s60
	v_add_u32_e32 v28, 0x80, v34
	v_add_u32_e32 v29, 0x80, v35
	v_add_u32_e32 v30, 0x80, v36
	v_add_u32_e32 v31, 0x80, v37
	v_perm_b32 v46, v29, v28, s78
	v_perm_b32 v47, v31, v30, s78
	v_perm_b32 v26, v29, v28, s79
	v_perm_b32 v27, v31, v30, s79
	v_perm_b32 v33, v27, v26, s60
	v_mul_f32_e32 v28, v23, v23
	v_mul_f32_e32 v29, v25, v25
	v_mul_f32_e32 v30, v19, v19
	v_mul_f32_e32 v31, v21, v21
	v_fmac_f32_e32 v28, v22, v22
	v_fmac_f32_e32 v29, v24, v24
	v_fmac_f32_e32 v30, v18, v18
	v_fmac_f32_e32 v31, v20, v20
	v_add_f32_e32 v28, v28, v29
	v_add_f32_e32 v30, v30, v31
	v_add_f32_e32 v28, v28, v30
	v_add_f32_e32 v173, v173, v28
	v_add_u32_e32 v28, 0x80, v22
	v_add_u32_e32 v29, 0x80, v23
	v_add_u32_e32 v30, 0x80, v24
	v_add_u32_e32 v31, 0x80, v25
	v_perm_b32 v168, v29, v28, s78
	v_perm_b32 v169, v31, v30, s78
	v_perm_b32 v26, v29, v28, s79
	v_perm_b32 v27, v31, v30, s79
	v_perm_b32 v42, v27, v26, s60
	v_add_u32_e32 v28, 0x80, v18
	v_add_u32_e32 v29, 0x80, v19
	v_add_u32_e32 v30, 0x80, v20
	v_add_u32_e32 v31, 0x80, v21
	v_perm_b32 v170, v29, v28, s78
	v_perm_b32 v171, v31, v30, s78
	v_perm_b32 v26, v29, v28, s79
	v_perm_b32 v27, v31, v30, s79
	v_perm_b32 v43, v27, v26, s60
	s_mov_b64 vcc, s[66:67]
	v_cndmask_b32_dpp v68, v168, v44, vcc quad_perm:[1,0,3,2] row_mask:0xf bank_mask:0xf
	v_cndmask_b32_dpp v69, v169, v45, vcc quad_perm:[1,0,3,2] row_mask:0xf bank_mask:0xf
	v_cndmask_b32_dpp v70, v170, v46, vcc quad_perm:[1,0,3,2] row_mask:0xf bank_mask:0xf
	v_cndmask_b32_dpp v71, v171, v47, vcc quad_perm:[1,0,3,2] row_mask:0xf bank_mask:0xf
	s_mov_b64 vcc, s[62:63]
	v_cndmask_b32_dpp v168, v44, v168, vcc quad_perm:[1,0,3,2] row_mask:0xf bank_mask:0xf
	v_cndmask_b32_dpp v169, v45, v169, vcc quad_perm:[1,0,3,2] row_mask:0xf bank_mask:0xf
	v_cndmask_b32_dpp v170, v46, v170, vcc quad_perm:[1,0,3,2] row_mask:0xf bank_mask:0xf
	v_cndmask_b32_dpp v171, v47, v171, vcc quad_perm:[1,0,3,2] row_mask:0xf bank_mask:0xf
	s_mov_b64 vcc, s[66:67]
	v_cndmask_b32_dpp v72, v42, v32, vcc quad_perm:[1,0,3,2] row_mask:0xf bank_mask:0xf
	v_cndmask_b32_dpp v73, v43, v33, vcc quad_perm:[1,0,3,2] row_mask:0xf bank_mask:0xf
	s_mov_b64 vcc, s[62:63]
	v_cndmask_b32_dpp v42, v32, v42, vcc quad_perm:[1,0,3,2] row_mask:0xf bank_mask:0xf
	v_cndmask_b32_dpp v43, v33, v43, vcc quad_perm:[1,0,3,2] row_mask:0xf bank_mask:0xf
	s_add_u32 s88, s58, 0x50000
	s_addc_u32 s89, s59, 0
	s_add_u32 s90, s74, 0x28000
	s_addc_u32 s91, s75, 0
	global_store_dwordx4 v49, v[68:71], s[88:89]
	global_store_dwordx4 v49, v[168:171], s[88:89] offset:2048
	global_store_dwordx2 v48, v[72:73], s[90:91]
	global_store_dwordx2 v48, v[42:43], s[90:91] offset:1024
	s_add_u32 s92, s96, 0x50000
	s_addc_u32 s93, s97, 0
	v_pk_mul_f32 v[38:39], v[194:195], v[38:39]
	v_pk_mul_f32 v[40:41], v[196:197], v[40:41]
	v_pk_mul_f32 v[34:35], v[210:211], v[34:35]
	v_pk_mul_f32 v[36:37], v[212:213], v[36:37]
	v_cvt_pk_bf16_f32 v44, v38, v39
	v_cvt_pk_bf16_f32 v45, v40, v41
	v_cvt_pk_bf16_f32 v46, v34, v35
	v_cvt_pk_bf16_f32 v47, v36, v37
	v_pk_mul_f32 v[22:23], v[214:215], v[22:23]
	v_pk_mul_f32 v[24:25], v[216:217], v[24:25]
	v_pk_mul_f32 v[18:19], v[218:219], v[18:19]
	v_pk_mul_f32 v[20:21], v[220:221], v[20:21]
	v_cvt_pk_bf16_f32 v168, v22, v23
	v_cvt_pk_bf16_f32 v169, v24, v25
	v_cvt_pk_bf16_f32 v170, v18, v19
	v_cvt_pk_bf16_f32 v171, v20, v21
	s_mov_b64 vcc, s[66:67]
	v_cndmask_b32_dpp v68, v168, v44, vcc quad_perm:[1,0,3,2] row_mask:0xf bank_mask:0xf
	v_cndmask_b32_dpp v69, v169, v45, vcc quad_perm:[1,0,3,2] row_mask:0xf bank_mask:0xf
	v_cndmask_b32_dpp v70, v170, v46, vcc quad_perm:[1,0,3,2] row_mask:0xf bank_mask:0xf
	v_cndmask_b32_dpp v71, v171, v47, vcc quad_perm:[1,0,3,2] row_mask:0xf bank_mask:0xf
	s_mov_b64 vcc, s[62:63]
	v_cndmask_b32_dpp v168, v44, v168, vcc quad_perm:[1,0,3,2] row_mask:0xf bank_mask:0xf
	v_cndmask_b32_dpp v169, v45, v169, vcc quad_perm:[1,0,3,2] row_mask:0xf bank_mask:0xf
	v_cndmask_b32_dpp v170, v46, v170, vcc quad_perm:[1,0,3,2] row_mask:0xf bank_mask:0xf
	v_cndmask_b32_dpp v171, v47, v171, vcc quad_perm:[1,0,3,2] row_mask:0xf bank_mask:0xf
	global_store_dwordx4 v49, v[68:71], s[92:93]
	global_store_dwordx4 v49, v[168:171], s[92:93] offset:2048
	v_mov_b32_e32 v18, v173
	s_waitcnt vmcnt(6)
	v_pk_fma_f32 v[14:15], v[14:15], v[174:175], v[52:53]
	v_pk_fma_f32 v[16:17], v[16:17], v[176:177], v[54:55]
	v_pk_fma_f32 v[10:11], v[10:11], v[178:179], v[56:57]
	v_pk_fma_f32 v[12:13], v[12:13], v[180:181], v[58:59]
	v_pk_fma_f32 v[6:7], v[6:7], v[182:183], v[60:61]
	v_pk_fma_f32 v[8:9], v[8:9], v[184:185], v[62:63]
	v_pk_fma_f32 v[2:3], v[2:3], v[186:187], v[84:85]
	v_pk_fma_f32 v[4:5], v[4:5], v[188:189], v[86:87]
	v_mul_f32_e32 v28, v15, v15
	v_mul_f32_e32 v29, v17, v17
	v_mul_f32_e32 v30, v11, v11
	v_mul_f32_e32 v31, v13, v13
	v_fmac_f32_e32 v28, v14, v14
	v_fmac_f32_e32 v29, v16, v16
	v_fmac_f32_e32 v30, v10, v10
	v_fmac_f32_e32 v31, v12, v12
	v_add_f32_e32 v28, v28, v29
	v_add_f32_e32 v30, v30, v31
	v_add_f32_e32 v173, v28, v30
	v_add_u32_e32 v28, 0x80, v14
	v_add_u32_e32 v29, 0x80, v15
	v_add_u32_e32 v30, 0x80, v16
	v_add_u32_e32 v31, 0x80, v17
	v_perm_b32 v44, v29, v28, s78
	v_perm_b32 v45, v31, v30, s78
	v_perm_b32 v26, v29, v28, s79
	v_perm_b32 v27, v31, v30, s79
	v_perm_b32 v32, v27, v26, s60
	v_add_u32_e32 v28, 0x80, v10
	v_add_u32_e32 v29, 0x80, v11
	v_add_u32_e32 v30, 0x80, v12
	v_add_u32_e32 v31, 0x80, v13
	v_perm_b32 v46, v29, v28, s78
	v_perm_b32 v47, v31, v30, s78
	v_perm_b32 v26, v29, v28, s79
	v_perm_b32 v27, v31, v30, s79
	v_perm_b32 v33, v27, v26, s60
	v_mul_f32_e32 v28, v7, v7
	v_mul_f32_e32 v29, v9, v9
	v_mul_f32_e32 v30, v3, v3
	v_mul_f32_e32 v31, v5, v5
	v_fmac_f32_e32 v28, v6, v6
	v_fmac_f32_e32 v29, v8, v8
	v_fmac_f32_e32 v30, v2, v2
	v_fmac_f32_e32 v31, v4, v4
	v_add_f32_e32 v28, v28, v29
	v_add_f32_e32 v30, v30, v31
	v_add_f32_e32 v28, v28, v30
	v_add_f32_e32 v173, v173, v28
	v_add_u32_e32 v28, 0x80, v6
	v_add_u32_e32 v29, 0x80, v7
	v_add_u32_e32 v30, 0x80, v8
	v_add_u32_e32 v31, 0x80, v9
	v_perm_b32 v168, v29, v28, s78
	v_perm_b32 v169, v31, v30, s78
	v_perm_b32 v26, v29, v28, s79
	v_perm_b32 v27, v31, v30, s79
	v_perm_b32 v42, v27, v26, s60
	v_add_u32_e32 v28, 0x80, v2
	v_add_u32_e32 v29, 0x80, v3
	v_add_u32_e32 v30, 0x80, v4
	v_add_u32_e32 v31, 0x80, v5
	v_perm_b32 v170, v29, v28, s78
	v_perm_b32 v171, v31, v30, s78
	v_perm_b32 v26, v29, v28, s79
	v_perm_b32 v27, v31, v30, s79
	v_perm_b32 v43, v27, v26, s60
	s_mov_b64 vcc, s[66:67]
	v_cndmask_b32_dpp v52, v168, v44, vcc quad_perm:[1,0,3,2] row_mask:0xf bank_mask:0xf
	v_cndmask_b32_dpp v53, v169, v45, vcc quad_perm:[1,0,3,2] row_mask:0xf bank_mask:0xf
	v_cndmask_b32_dpp v54, v170, v46, vcc quad_perm:[1,0,3,2] row_mask:0xf bank_mask:0xf
	v_cndmask_b32_dpp v55, v171, v47, vcc quad_perm:[1,0,3,2] row_mask:0xf bank_mask:0xf
	s_mov_b64 vcc, s[62:63]
	v_cndmask_b32_dpp v168, v44, v168, vcc quad_perm:[1,0,3,2] row_mask:0xf bank_mask:0xf
	v_cndmask_b32_dpp v169, v45, v169, vcc quad_perm:[1,0,3,2] row_mask:0xf bank_mask:0xf
	v_cndmask_b32_dpp v170, v46, v170, vcc quad_perm:[1,0,3,2] row_mask:0xf bank_mask:0xf
	v_cndmask_b32_dpp v171, v47, v171, vcc quad_perm:[1,0,3,2] row_mask:0xf bank_mask:0xf
	s_mov_b64 vcc, s[66:67]
	v_cndmask_b32_dpp v56, v42, v32, vcc quad_perm:[1,0,3,2] row_mask:0xf bank_mask:0xf
	v_cndmask_b32_dpp v57, v43, v33, vcc quad_perm:[1,0,3,2] row_mask:0xf bank_mask:0xf
	s_mov_b64 vcc, s[62:63]
	v_cndmask_b32_dpp v42, v32, v42, vcc quad_perm:[1,0,3,2] row_mask:0xf bank_mask:0xf
	v_cndmask_b32_dpp v43, v33, v43, vcc quad_perm:[1,0,3,2] row_mask:0xf bank_mask:0xf
	s_add_u32 s88, s58, 0x58000
	s_addc_u32 s89, s59, 0
	s_add_u32 s90, s74, 0x2c000
	s_addc_u32 s91, s75, 0
	global_store_dwordx4 v49, v[52:55], s[88:89]
	global_store_dwordx4 v49, v[168:171], s[88:89] offset:2048
	global_store_dwordx2 v48, v[56:57], s[90:91]
	global_store_dwordx2 v48, v[42:43], s[90:91] offset:1024
	s_add_u32 s92, s96, 0x58000
	s_addc_u32 s93, s97, 0
	v_pk_mul_f32 v[14:15], v[194:195], v[14:15]
	v_pk_mul_f32 v[16:17], v[196:197], v[16:17]
	v_pk_mul_f32 v[10:11], v[210:211], v[10:11]
	v_pk_mul_f32 v[12:13], v[212:213], v[12:13]
	v_cvt_pk_bf16_f32 v44, v14, v15
	v_cvt_pk_bf16_f32 v45, v16, v17
	v_cvt_pk_bf16_f32 v46, v10, v11
	v_cvt_pk_bf16_f32 v47, v12, v13
	v_pk_mul_f32 v[6:7], v[214:215], v[6:7]
	v_pk_mul_f32 v[8:9], v[216:217], v[8:9]
	v_pk_mul_f32 v[2:3], v[218:219], v[2:3]
	v_pk_mul_f32 v[4:5], v[220:221], v[4:5]
	v_cvt_pk_bf16_f32 v168, v6, v7
	v_cvt_pk_bf16_f32 v169, v8, v9
	v_cvt_pk_bf16_f32 v170, v2, v3
	v_cvt_pk_bf16_f32 v171, v4, v5
	s_mov_b64 vcc, s[66:67]
	v_cndmask_b32_dpp v52, v168, v44, vcc quad_perm:[1,0,3,2] row_mask:0xf bank_mask:0xf
	v_cndmask_b32_dpp v53, v169, v45, vcc quad_perm:[1,0,3,2] row_mask:0xf bank_mask:0xf
	v_cndmask_b32_dpp v54, v170, v46, vcc quad_perm:[1,0,3,2] row_mask:0xf bank_mask:0xf
	v_cndmask_b32_dpp v55, v171, v47, vcc quad_perm:[1,0,3,2] row_mask:0xf bank_mask:0xf
	s_mov_b64 vcc, s[62:63]
	v_cndmask_b32_dpp v168, v44, v168, vcc quad_perm:[1,0,3,2] row_mask:0xf bank_mask:0xf
	v_cndmask_b32_dpp v169, v45, v169, vcc quad_perm:[1,0,3,2] row_mask:0xf bank_mask:0xf
	v_cndmask_b32_dpp v170, v46, v170, vcc quad_perm:[1,0,3,2] row_mask:0xf bank_mask:0xf
	v_cndmask_b32_dpp v171, v47, v171, vcc quad_perm:[1,0,3,2] row_mask:0xf bank_mask:0xf
	global_store_dwordx4 v49, v[52:55], s[92:93]
	global_store_dwordx4 v49, v[168:171], s[92:93] offset:2048
	v_mov_b32_e32 v2, v173
	v_mbcnt_lo_u32_b32 v3, -1, 0
	v_mbcnt_hi_u32_b32 v3, -1, v3
	v_xor_b32_e32 v4, 16, v3
	v_xor_b32_e32 v5, 32, v3
	v_lshlrev_b32_e32 v4, 2, v4
	v_lshlrev_b32_e32 v5, 2, v5
	v_cmp_gt_u32_e64 s[54:55], 16, v3
	ds_bpermute_b32 v6, v4, v130
	ds_bpermute_b32 v7, v4, v114
	ds_bpermute_b32 v8, v4, v98
	ds_bpermute_b32 v9, v4, v82
	ds_bpermute_b32 v10, v4, v66
	ds_bpermute_b32 v11, v4, v50
	ds_bpermute_b32 v12, v4, v18
	ds_bpermute_b32 v13, v4, v2
	s_waitcnt lgkmcnt(0)
	v_add_f32_e32 v130, v130, v6
	v_add_f32_e32 v114, v114, v7
	v_add_f32_e32 v98, v98, v8
	v_add_f32_e32 v82, v82, v9
	v_add_f32_e32 v66, v66, v10
	v_add_f32_e32 v50, v50, v11
	v_add_f32_e32 v18, v18, v12
	v_add_f32_e32 v2, v2, v13
	ds_bpermute_b32 v6, v5, v130
	ds_bpermute_b32 v7, v5, v114
	ds_bpermute_b32 v8, v5, v98
	ds_bpermute_b32 v9, v5, v82
	ds_bpermute_b32 v10, v5, v66
	ds_bpermute_b32 v11, v5, v50
	ds_bpermute_b32 v12, v5, v18
	ds_bpermute_b32 v13, v5, v2
	s_waitcnt lgkmcnt(0)
	v_add_f32_e32 v130, v130, v6
	v_add_f32_e32 v114, v114, v7
	v_add_f32_e32 v98, v98, v8
	v_add_f32_e32 v82, v82, v9
	v_add_f32_e32 v66, v66, v10
	v_add_f32_e32 v50, v50, v11
	v_add_f32_e32 v18, v18, v12
	v_add_f32_e32 v2, v2, v13
	v_readlane_b32 s70, v244, 53
	v_readlane_b32 s71, v244, 54
	v_lshlrev_b32_e32 v3, 6, v190
	s_lshl_b32 s94, s53, 14
	s_lshl_b32 s95, s4, 4
	s_add_u32 s94, s94, s95
	s_lshl_b32 s95, s47, 2
	s_add_u32 s94, s94, s95
	s_add_u32 s94, s70, s94
	s_addc_u32 s95, s71, 0
	s_and_saveexec_b64 s[56:57], s[54:55]
	global_store_dword v3, v130, s[94:95]
	s_add_u32 s84, s94, 0x400
	s_addc_u32 s85, s95, 0
	global_store_dword v3, v114, s[84:85]
	s_add_u32 s84, s94, 0x800
	s_addc_u32 s85, s95, 0
	global_store_dword v3, v98, s[84:85]
	s_add_u32 s84, s94, 0xc00
	s_addc_u32 s85, s95, 0
	global_store_dword v3, v82, s[84:85]
	s_add_u32 s84, s94, 0x2000
	s_addc_u32 s85, s95, 0
	global_store_dword v3, v66, s[84:85]
	s_add_u32 s84, s94, 0x2400
	s_addc_u32 s85, s95, 0
	global_store_dword v3, v50, s[84:85]
	s_add_u32 s84, s94, 0x2800
	s_addc_u32 s85, s95, 0
	global_store_dword v3, v18, s[84:85]
	s_add_u32 s84, s94, 0x2c00
	s_addc_u32 s85, s95, 0
	global_store_dword v3, v2, s[84:85]
	s_or_b64 exec, exec, s[56:57]
	v_readlane_b32 s56, v246, 3
	v_readlane_b32 s57, v246, 4
	s_andn2_b64 vcc, exec, s[18:19]
	s_mov_b64 s[12:13], -1
	s_cbranch_vccnz .LBB0_1218
	s_andn2_b64 vcc, exec, s[0:1]
	s_cbranch_vccnz .LBB0_1217
	s_barrier
	s_branch .LBB0_1217

.LBB0_1512:
	s_and_b64 vcc, exec, s[18:19]
	s_cbranch_vccz .Lepi3_nulla1
	s_ashr_i32 s16, s54, 31
	s_lshr_b32 s16, s16, 29
	s_add_i32 s16, s54, s16
	s_ashr_i32 s16, s16, 3
	s_mul_i32 s27, s16, 0x6000
	s_mul_hi_i32 s25, s16, 0x6000
	s_add_u32 s80, s45, s27
	s_addc_u32 s81, s47, s25
	s_add_u32 s82, s49, s27
	s_addc_u32 s83, s50, s25
	s_mov_b32 s62, 0xaaaaaaaa
	s_mov_b32 s63, 0xaaaaaaaa
	s_mov_b32 s66, 0x55555555
	s_mov_b32 s67, 0x55555555
	s_mov_b32 s32, 0x0504000c
	s_mov_b32 s61, 0x0504020c
	s_mov_b32 s98, 0x0706030c
	v_mbcnt_lo_u32_b32 v172, -1, 0
	v_mbcnt_hi_u32_b32 v172, -1, v172
	v_and_b32_e32 v172, 1, v172
	v_and_b32_e32 v171, 0x60, v196
	v_add_u32_e32 v171, v171, v196
	v_lshl_or_b32 v171, s4, 8, v171
	v_lshlrev_b32_e32 v44, 2, v171
	v_lshl_add_u32 v171, v172, 5, v171
	v_lshl_add_u32 v170, s54, 8, v194
	v_sub_u32_e32 v170, v170, v172
	v_lshl_add_u32 v170, v170, 10, v171
	v_lshlrev_b32_e32 v171, 1, v170
	global_load_dwordx4 v[174:177], v44, s[80:81] offset:0
	global_load_dwordx4 v[178:181], v44, s[80:81] offset:16
	global_load_dwordx4 v[190:193], v44, s[20:21] offset:0
	global_load_dwordx4 v[210:213], v44, s[20:21] offset:16
	global_load_dwordx4 v[182:185], v44, s[80:81] offset:128
	global_load_dwordx4 v[186:189], v44, s[80:81] offset:144
	global_load_dwordx4 v[214:217], v44, s[20:21] offset:128
	global_load_dwordx4 v[218:221], v44, s[20:21] offset:144
	global_load_dwordx4 v[222:225], v44, s[82:83] offset:0
	global_load_dwordx4 v[226:229], v44, s[82:83] offset:16
	global_load_dwordx4 v[230:233], v44, s[82:83] offset:128
	global_load_dwordx4 v[234:237], v44, s[82:83] offset:144
	s_waitcnt vmcnt(0)
	v_pk_add_f32 v[222:223], v[222:223], 1.0 op_sel_hi:[1,0]
	v_pk_add_f32 v[224:225], v[224:225], 1.0 op_sel_hi:[1,0]
	v_pk_add_f32 v[226:227], v[226:227], 1.0 op_sel_hi:[1,0]
	v_pk_add_f32 v[228:229], v[228:229], 1.0 op_sel_hi:[1,0]
	v_pk_mul_f32 v[190:191], v[190:191], v[222:223]
	v_pk_mul_f32 v[192:193], v[192:193], v[224:225]
	v_pk_mul_f32 v[210:211], v[210:211], v[226:227]
	v_pk_mul_f32 v[212:213], v[212:213], v[228:229]
	v_pk_add_f32 v[230:231], v[230:231], 1.0 op_sel_hi:[1,0]
	v_pk_add_f32 v[232:233], v[232:233], 1.0 op_sel_hi:[1,0]
	v_pk_add_f32 v[234:235], v[234:235], 1.0 op_sel_hi:[1,0]
	v_pk_add_f32 v[236:237], v[236:237], 1.0 op_sel_hi:[1,0]
	v_pk_mul_f32 v[214:215], v[214:215], v[230:231]
	v_pk_mul_f32 v[216:217], v[216:217], v[232:233]
	v_pk_mul_f32 v[218:219], v[218:219], v[234:235]
	v_pk_mul_f32 v[220:221], v[220:221], v[236:237]
	s_add_u32 s84, s58, 0x0
	s_addc_u32 s85, s59, 0
	s_add_u32 s86, s74, 0x0
	s_addc_u32 s87, s75, 0
	global_load_dwordx4 v[222:225], v171, s[84:85]
	global_load_dwordx2 v[226:227], v170, s[86:87]
	global_load_dwordx4 v[228:231], v171, s[84:85] offset:2048
	global_load_dwordx2 v[232:233], v170, s[86:87] offset:1024
	s_waitcnt vmcnt(0)
	s_mov_b64 vcc, s[66:67]
	v_cndmask_b32_dpp v48, v228, v222, vcc quad_perm:[1,0,3,2] row_mask:0xf bank_mask:0xf
	v_cndmask_b32_dpp v49, v229, v223, vcc quad_perm:[1,0,3,2] row_mask:0xf bank_mask:0xf
	v_cndmask_b32_dpp v50, v230, v224, vcc quad_perm:[1,0,3,2] row_mask:0xf bank_mask:0xf
	v_cndmask_b32_dpp v51, v231, v225, vcc quad_perm:[1,0,3,2] row_mask:0xf bank_mask:0xf
	s_mov_b64 vcc, s[62:63]
	v_cndmask_b32_dpp v228, v222, v228, vcc quad_perm:[1,0,3,2] row_mask:0xf bank_mask:0xf
	v_cndmask_b32_dpp v229, v223, v229, vcc quad_perm:[1,0,3,2] row_mask:0xf bank_mask:0xf
	v_cndmask_b32_dpp v230, v224, v230, vcc quad_perm:[1,0,3,2] row_mask:0xf bank_mask:0xf
	v_cndmask_b32_dpp v231, v225, v231, vcc quad_perm:[1,0,3,2] row_mask:0xf bank_mask:0xf
	s_mov_b64 vcc, s[66:67]
	v_cndmask_b32_dpp v52, v232, v226, vcc quad_perm:[1,0,3,2] row_mask:0xf bank_mask:0xf
	v_cndmask_b32_dpp v53, v233, v227, vcc quad_perm:[1,0,3,2] row_mask:0xf bank_mask:0xf
	s_mov_b64 vcc, s[62:63]
	v_cndmask_b32_dpp v232, v226, v232, vcc quad_perm:[1,0,3,2] row_mask:0xf bank_mask:0xf
	v_cndmask_b32_dpp v233, v227, v233, vcc quad_perm:[1,0,3,2] row_mask:0xf bank_mask:0xf
	v_perm_b32 v44, v48, v52, s32
	v_perm_b32 v45, v48, v52, s8
	v_perm_b32 v46, v49, v52, s61
	v_perm_b32 v47, v49, v52, s98
	v_pk_fma_f32 v[142:143], v[142:143], v[174:175], v[44:45]
	v_pk_fma_f32 v[144:145], v[144:145], v[176:177], v[46:47]
	v_perm_b32 v44, v50, v53, s32
	v_perm_b32 v45, v50, v53, s8
	v_perm_b32 v46, v51, v53, s61
	v_perm_b32 v47, v51, v53, s98
	v_pk_fma_f32 v[138:139], v[138:139], v[178:179], v[44:45]
	v_pk_fma_f32 v[140:141], v[140:141], v[180:181], v[46:47]
	v_perm_b32 v44, v228, v232, s32
	v_perm_b32 v45, v228, v232, s8
	v_perm_b32 v46, v229, v232, s61
	v_perm_b32 v47, v229, v232, s98
	v_pk_fma_f32 v[134:135], v[134:135], v[182:183], v[44:45]
	v_pk_fma_f32 v[136:137], v[136:137], v[184:185], v[46:47]
	v_perm_b32 v44, v230, v233, s32
	v_perm_b32 v45, v230, v233, s8
	v_perm_b32 v46, v231, v233, s61
	v_perm_b32 v47, v231, v233, s98
	v_pk_fma_f32 v[130:131], v[130:131], v[186:187], v[44:45]
	v_pk_fma_f32 v[132:133], v[132:133], v[188:189], v[46:47]
	v_mul_f32_e32 v44, v143, v143
	v_mul_f32_e32 v45, v145, v145
	v_mul_f32_e32 v46, v139, v139
	v_mul_f32_e32 v47, v141, v141
	v_fmac_f32_e32 v44, v142, v142
	v_fmac_f32_e32 v45, v144, v144
	v_fmac_f32_e32 v46, v138, v138
	v_fmac_f32_e32 v47, v140, v140
	v_add_f32_e32 v44, v44, v45
	v_add_f32_e32 v46, v46, v47
	v_add_f32_e32 v173, v44, v46
	v_add_u32_e32 v44, 0x80, v142
	v_add_u32_e32 v45, 0x80, v143
	v_add_u32_e32 v46, 0x80, v144
	v_add_u32_e32 v47, 0x80, v145
	v_perm_b32 v48, v45, v44, s78
	v_perm_b32 v49, v47, v46, s78
	v_perm_b32 v42, v45, v44, s79
	v_perm_b32 v43, v47, v46, s79
	v_perm_b32 v56, v43, v42, s60
	v_add_u32_e32 v44, 0x80, v138
	v_add_u32_e32 v45, 0x80, v139
	v_add_u32_e32 v46, 0x80, v140
	v_add_u32_e32 v47, 0x80, v141
	v_perm_b32 v50, v45, v44, s78
	v_perm_b32 v51, v47, v46, s78
	v_perm_b32 v42, v45, v44, s79
	v_perm_b32 v43, v47, v46, s79
	v_perm_b32 v57, v43, v42, s60
	v_mul_f32_e32 v44, v135, v135
	v_mul_f32_e32 v45, v137, v137
	v_mul_f32_e32 v46, v131, v131
	v_mul_f32_e32 v47, v133, v133
	v_fmac_f32_e32 v44, v134, v134
	v_fmac_f32_e32 v45, v136, v136
	v_fmac_f32_e32 v46, v130, v130
	v_fmac_f32_e32 v47, v132, v132
	v_add_f32_e32 v44, v44, v45
	v_add_f32_e32 v46, v46, v47
	v_add_f32_e32 v44, v44, v46
	v_add_f32_e32 v173, v173, v44
	v_add_u32_e32 v44, 0x80, v134
	v_add_u32_e32 v45, 0x80, v135
	v_add_u32_e32 v46, 0x80, v136
	v_add_u32_e32 v47, 0x80, v137
	v_perm_b32 v52, v45, v44, s78
	v_perm_b32 v53, v47, v46, s78
	v_perm_b32 v42, v45, v44, s79
	v_perm_b32 v43, v47, v46, s79
	v_perm_b32 v168, v43, v42, s60
	v_add_u32_e32 v44, 0x80, v130
	v_add_u32_e32 v45, 0x80, v131
	v_add_u32_e32 v46, 0x80, v132
	v_add_u32_e32 v47, 0x80, v133
	v_perm_b32 v54, v45, v44, s78
	v_perm_b32 v55, v47, v46, s78
	v_perm_b32 v42, v45, v44, s79
	v_perm_b32 v43, v47, v46, s79
	v_perm_b32 v169, v43, v42, s60
	s_mov_b64 vcc, s[66:67]
	v_cndmask_b32_dpp v222, v52, v48, vcc quad_perm:[1,0,3,2] row_mask:0xf bank_mask:0xf
	v_cndmask_b32_dpp v223, v53, v49, vcc quad_perm:[1,0,3,2] row_mask:0xf bank_mask:0xf
	v_cndmask_b32_dpp v224, v54, v50, vcc quad_perm:[1,0,3,2] row_mask:0xf bank_mask:0xf
	v_cndmask_b32_dpp v225, v55, v51, vcc quad_perm:[1,0,3,2] row_mask:0xf bank_mask:0xf
	s_mov_b64 vcc, s[62:63]
	v_cndmask_b32_dpp v52, v48, v52, vcc quad_perm:[1,0,3,2] row_mask:0xf bank_mask:0xf
	v_cndmask_b32_dpp v53, v49, v53, vcc quad_perm:[1,0,3,2] row_mask:0xf bank_mask:0xf
	v_cndmask_b32_dpp v54, v50, v54, vcc quad_perm:[1,0,3,2] row_mask:0xf bank_mask:0xf
	v_cndmask_b32_dpp v55, v51, v55, vcc quad_perm:[1,0,3,2] row_mask:0xf bank_mask:0xf
	s_mov_b64 vcc, s[66:67]
	v_cndmask_b32_dpp v228, v168, v56, vcc quad_perm:[1,0,3,2] row_mask:0xf bank_mask:0xf
	v_cndmask_b32_dpp v229, v169, v57, vcc quad_perm:[1,0,3,2] row_mask:0xf bank_mask:0xf
	s_mov_b64 vcc, s[62:63]
	v_cndmask_b32_dpp v168, v56, v168, vcc quad_perm:[1,0,3,2] row_mask:0xf bank_mask:0xf
	v_cndmask_b32_dpp v169, v57, v169, vcc quad_perm:[1,0,3,2] row_mask:0xf bank_mask:0xf
	s_add_u32 s88, s58, 0x0
	s_addc_u32 s89, s59, 0
	s_add_u32 s90, s74, 0x0
	s_addc_u32 s91, s75, 0
	global_store_dwordx4 v171, v[222:225], s[88:89]
	global_store_dwordx4 v171, v[52:55], s[88:89] offset:2048
	global_store_dwordx2 v170, v[228:229], s[90:91]
	global_store_dwordx2 v170, v[168:169], s[90:91] offset:1024
	s_add_u32 s92, s96, 0x0
	s_addc_u32 s93, s97, 0
	v_pk_mul_f32 v[142:143], v[190:191], v[142:143]
	v_pk_mul_f32 v[144:145], v[192:193], v[144:145]
	v_pk_mul_f32 v[138:139], v[210:211], v[138:139]
	v_pk_mul_f32 v[140:141], v[212:213], v[140:141]
	v_cvt_pk_bf16_f32 v48, v142, v143
	v_cvt_pk_bf16_f32 v49, v144, v145
	v_cvt_pk_bf16_f32 v50, v138, v139
	v_cvt_pk_bf16_f32 v51, v140, v141
	v_pk_mul_f32 v[134:135], v[214:215], v[134:135]
	v_pk_mul_f32 v[136:137], v[216:217], v[136:137]
	v_pk_mul_f32 v[130:131], v[218:219], v[130:131]
	v_pk_mul_f32 v[132:133], v[220:221], v[132:133]
	v_cvt_pk_bf16_f32 v52, v134, v135
	v_cvt_pk_bf16_f32 v53, v136, v137
	v_cvt_pk_bf16_f32 v54, v130, v131
	v_cvt_pk_bf16_f32 v55, v132, v133
	s_mov_b64 vcc, s[66:67]
	v_cndmask_b32_dpp v222, v52, v48, vcc quad_perm:[1,0,3,2] row_mask:0xf bank_mask:0xf
	v_cndmask_b32_dpp v223, v53, v49, vcc quad_perm:[1,0,3,2] row_mask:0xf bank_mask:0xf
	v_cndmask_b32_dpp v224, v54, v50, vcc quad_perm:[1,0,3,2] row_mask:0xf bank_mask:0xf
	v_cndmask_b32_dpp v225, v55, v51, vcc quad_perm:[1,0,3,2] row_mask:0xf bank_mask:0xf
	s_mov_b64 vcc, s[62:63]
	v_cndmask_b32_dpp v52, v48, v52, vcc quad_perm:[1,0,3,2] row_mask:0xf bank_mask:0xf
	v_cndmask_b32_dpp v53, v49, v53, vcc quad_perm:[1,0,3,2] row_mask:0xf bank_mask:0xf
	v_cndmask_b32_dpp v54, v50, v54, vcc quad_perm:[1,0,3,2] row_mask:0xf bank_mask:0xf
	v_cndmask_b32_dpp v55, v51, v55, vcc quad_perm:[1,0,3,2] row_mask:0xf bank_mask:0xf
	global_store_dwordx4 v171, v[222:225], s[92:93]
	global_store_dwordx4 v171, v[52:55], s[92:93] offset:2048
	v_mov_b32_e32 v130, v173
	s_add_u32 s84, s58, 0x8000
	s_addc_u32 s85, s59, 0
	s_add_u32 s86, s74, 0x4000
	s_addc_u32 s87, s75, 0
	global_load_dwordx4 v[132:135], v171, s[84:85]
	global_load_dwordx2 v[136:137], v170, s[86:87]
	global_load_dwordx4 v[138:141], v171, s[84:85] offset:2048
	global_load_dwordx2 v[142:143], v170, s[86:87] offset:1024
	s_add_u32 s84, s58, 0x10000
	s_addc_u32 s85, s59, 0
	s_add_u32 s86, s74, 0x8000
	s_addc_u32 s87, s75, 0
	global_load_dwordx4 v[222:225], v171, s[84:85]
	global_load_dwordx2 v[144:145], v170, s[86:87]
	global_load_dwordx4 v[226:229], v171, s[84:85] offset:2048
	global_load_dwordx2 v[230:231], v170, s[86:87] offset:1024
	s_waitcnt vmcnt(4)
	s_mov_b64 vcc, s[66:67]
	v_cndmask_b32_dpp v48, v138, v132, vcc quad_perm:[1,0,3,2] row_mask:0xf bank_mask:0xf
	v_cndmask_b32_dpp v49, v139, v133, vcc quad_perm:[1,0,3,2] row_mask:0xf bank_mask:0xf
	v_cndmask_b32_dpp v50, v140, v134, vcc quad_perm:[1,0,3,2] row_mask:0xf bank_mask:0xf
	v_cndmask_b32_dpp v51, v141, v135, vcc quad_perm:[1,0,3,2] row_mask:0xf bank_mask:0xf
	s_mov_b64 vcc, s[62:63]
	v_cndmask_b32_dpp v138, v132, v138, vcc quad_perm:[1,0,3,2] row_mask:0xf bank_mask:0xf
	v_cndmask_b32_dpp v139, v133, v139, vcc quad_perm:[1,0,3,2] row_mask:0xf bank_mask:0xf
	v_cndmask_b32_dpp v140, v134, v140, vcc quad_perm:[1,0,3,2] row_mask:0xf bank_mask:0xf
	v_cndmask_b32_dpp v141, v135, v141, vcc quad_perm:[1,0,3,2] row_mask:0xf bank_mask:0xf
	s_mov_b64 vcc, s[66:67]
	v_cndmask_b32_dpp v52, v142, v136, vcc quad_perm:[1,0,3,2] row_mask:0xf bank_mask:0xf
	v_cndmask_b32_dpp v53, v143, v137, vcc quad_perm:[1,0,3,2] row_mask:0xf bank_mask:0xf
	s_mov_b64 vcc, s[62:63]
	v_cndmask_b32_dpp v142, v136, v142, vcc quad_perm:[1,0,3,2] row_mask:0xf bank_mask:0xf
	v_cndmask_b32_dpp v143, v137, v143, vcc quad_perm:[1,0,3,2] row_mask:0xf bank_mask:0xf
	v_perm_b32 v44, v48, v52, s32
	v_perm_b32 v45, v48, v52, s8
	v_perm_b32 v46, v49, v52, s61
	v_perm_b32 v47, v49, v52, s98
	v_pk_fma_f32 v[126:127], v[126:127], v[174:175], v[44:45]
	v_pk_fma_f32 v[128:129], v[128:129], v[176:177], v[46:47]
	v_perm_b32 v44, v50, v53, s32
	v_perm_b32 v45, v50, v53, s8
	v_perm_b32 v46, v51, v53, s61
	v_perm_b32 v47, v51, v53, s98
	v_pk_fma_f32 v[122:123], v[122:123], v[178:179], v[44:45]
	v_pk_fma_f32 v[124:125], v[124:125], v[180:181], v[46:47]
	v_perm_b32 v44, v138, v142, s32
	v_perm_b32 v45, v138, v142, s8
	v_perm_b32 v46, v139, v142, s61
	v_perm_b32 v47, v139, v142, s98
	v_pk_fma_f32 v[118:119], v[118:119], v[182:183], v[44:45]
	v_pk_fma_f32 v[120:121], v[120:121], v[184:185], v[46:47]
	v_perm_b32 v44, v140, v143, s32
	v_perm_b32 v45, v140, v143, s8
	v_perm_b32 v46, v141, v143, s61
	v_perm_b32 v47, v141, v143, s98
	v_pk_fma_f32 v[114:115], v[114:115], v[186:187], v[44:45]
	v_pk_fma_f32 v[116:117], v[116:117], v[188:189], v[46:47]
	v_mul_f32_e32 v44, v127, v127
	v_mul_f32_e32 v45, v129, v129
	v_mul_f32_e32 v46, v123, v123
	v_mul_f32_e32 v47, v125, v125
	v_fmac_f32_e32 v44, v126, v126
	v_fmac_f32_e32 v45, v128, v128
	v_fmac_f32_e32 v46, v122, v122
	v_fmac_f32_e32 v47, v124, v124
	v_add_f32_e32 v44, v44, v45
	v_add_f32_e32 v46, v46, v47
	v_add_f32_e32 v173, v44, v46
	v_add_u32_e32 v44, 0x80, v126
	v_add_u32_e32 v45, 0x80, v127
	v_add_u32_e32 v46, 0x80, v128
	v_add_u32_e32 v47, 0x80, v129
	v_perm_b32 v48, v45, v44, s78
	v_perm_b32 v49, v47, v46, s78
	v_perm_b32 v42, v45, v44, s79
	v_perm_b32 v43, v47, v46, s79
	v_perm_b32 v56, v43, v42, s60
	v_add_u32_e32 v44, 0x80, v122
	v_add_u32_e32 v45, 0x80, v123
	v_add_u32_e32 v46, 0x80, v124
	v_add_u32_e32 v47, 0x80, v125
	v_perm_b32 v50, v45, v44, s78
	v_perm_b32 v51, v47, v46, s78
	v_perm_b32 v42, v45, v44, s79
	v_perm_b32 v43, v47, v46, s79
	v_perm_b32 v57, v43, v42, s60
	v_mul_f32_e32 v44, v119, v119
	v_mul_f32_e32 v45, v121, v121
	v_mul_f32_e32 v46, v115, v115
	v_mul_f32_e32 v47, v117, v117
	v_fmac_f32_e32 v44, v118, v118
	v_fmac_f32_e32 v45, v120, v120
	v_fmac_f32_e32 v46, v114, v114
	v_fmac_f32_e32 v47, v116, v116
	v_add_f32_e32 v44, v44, v45
	v_add_f32_e32 v46, v46, v47
	v_add_f32_e32 v44, v44, v46
	v_add_f32_e32 v173, v173, v44
	v_add_u32_e32 v44, 0x80, v118
	v_add_u32_e32 v45, 0x80, v119
	v_add_u32_e32 v46, 0x80, v120
	v_add_u32_e32 v47, 0x80, v121
	v_perm_b32 v52, v45, v44, s78
	v_perm_b32 v53, v47, v46, s78
	v_perm_b32 v42, v45, v44, s79
	v_perm_b32 v43, v47, v46, s79
	v_perm_b32 v168, v43, v42, s60
	v_add_u32_e32 v44, 0x80, v114
	v_add_u32_e32 v45, 0x80, v115
	v_add_u32_e32 v46, 0x80, v116
	v_add_u32_e32 v47, 0x80, v117
	v_perm_b32 v54, v45, v44, s78
	v_perm_b32 v55, v47, v46, s78
	v_perm_b32 v42, v45, v44, s79
	v_perm_b32 v43, v47, v46, s79
	v_perm_b32 v169, v43, v42, s60
	s_mov_b64 vcc, s[66:67]
	v_cndmask_b32_dpp v132, v52, v48, vcc quad_perm:[1,0,3,2] row_mask:0xf bank_mask:0xf
	v_cndmask_b32_dpp v133, v53, v49, vcc quad_perm:[1,0,3,2] row_mask:0xf bank_mask:0xf
	v_cndmask_b32_dpp v134, v54, v50, vcc quad_perm:[1,0,3,2] row_mask:0xf bank_mask:0xf
	v_cndmask_b32_dpp v135, v55, v51, vcc quad_perm:[1,0,3,2] row_mask:0xf bank_mask:0xf
	s_mov_b64 vcc, s[62:63]
	v_cndmask_b32_dpp v52, v48, v52, vcc quad_perm:[1,0,3,2] row_mask:0xf bank_mask:0xf
	v_cndmask_b32_dpp v53, v49, v53, vcc quad_perm:[1,0,3,2] row_mask:0xf bank_mask:0xf
	v_cndmask_b32_dpp v54, v50, v54, vcc quad_perm:[1,0,3,2] row_mask:0xf bank_mask:0xf
	v_cndmask_b32_dpp v55, v51, v55, vcc quad_perm:[1,0,3,2] row_mask:0xf bank_mask:0xf
	s_mov_b64 vcc, s[66:67]
	v_cndmask_b32_dpp v138, v168, v56, vcc quad_perm:[1,0,3,2] row_mask:0xf bank_mask:0xf
	v_cndmask_b32_dpp v139, v169, v57, vcc quad_perm:[1,0,3,2] row_mask:0xf bank_mask:0xf
	s_mov_b64 vcc, s[62:63]
	v_cndmask_b32_dpp v168, v56, v168, vcc quad_perm:[1,0,3,2] row_mask:0xf bank_mask:0xf
	v_cndmask_b32_dpp v169, v57, v169, vcc quad_perm:[1,0,3,2] row_mask:0xf bank_mask:0xf
	s_add_u32 s88, s58, 0x8000
	s_addc_u32 s89, s59, 0
	s_add_u32 s90, s74, 0x4000
	s_addc_u32 s91, s75, 0
	global_store_dwordx4 v171, v[132:135], s[88:89]
	global_store_dwordx4 v171, v[52:55], s[88:89] offset:2048
	global_store_dwordx2 v170, v[138:139], s[90:91]
	global_store_dwordx2 v170, v[168:169], s[90:91] offset:1024
	s_add_u32 s92, s96, 0x8000
	s_addc_u32 s93, s97, 0
	v_pk_mul_f32 v[126:127], v[190:191], v[126:127]
	v_pk_mul_f32 v[128:129], v[192:193], v[128:129]
	v_pk_mul_f32 v[122:123], v[210:211], v[122:123]
	v_pk_mul_f32 v[124:125], v[212:213], v[124:125]
	v_cvt_pk_bf16_f32 v48, v126, v127
	v_cvt_pk_bf16_f32 v49, v128, v129
	v_cvt_pk_bf16_f32 v50, v122, v123
	v_cvt_pk_bf16_f32 v51, v124, v125
	v_pk_mul_f32 v[118:119], v[214:215], v[118:119]
	v_pk_mul_f32 v[120:121], v[216:217], v[120:121]
	v_pk_mul_f32 v[114:115], v[218:219], v[114:115]
	v_pk_mul_f32 v[116:117], v[220:221], v[116:117]
	v_cvt_pk_bf16_f32 v52, v118, v119
	v_cvt_pk_bf16_f32 v53, v120, v121
	v_cvt_pk_bf16_f32 v54, v114, v115
	v_cvt_pk_bf16_f32 v55, v116, v117
	s_mov_b64 vcc, s[66:67]
	v_cndmask_b32_dpp v132, v52, v48, vcc quad_perm:[1,0,3,2] row_mask:0xf bank_mask:0xf
	v_cndmask_b32_dpp v133, v53, v49, vcc quad_perm:[1,0,3,2] row_mask:0xf bank_mask:0xf
	v_cndmask_b32_dpp v134, v54, v50, vcc quad_perm:[1,0,3,2] row_mask:0xf bank_mask:0xf
	v_cndmask_b32_dpp v135, v55, v51, vcc quad_perm:[1,0,3,2] row_mask:0xf bank_mask:0xf
	s_mov_b64 vcc, s[62:63]
	v_cndmask_b32_dpp v52, v48, v52, vcc quad_perm:[1,0,3,2] row_mask:0xf bank_mask:0xf
	v_cndmask_b32_dpp v53, v49, v53, vcc quad_perm:[1,0,3,2] row_mask:0xf bank_mask:0xf
	v_cndmask_b32_dpp v54, v50, v54, vcc quad_perm:[1,0,3,2] row_mask:0xf bank_mask:0xf
	v_cndmask_b32_dpp v55, v51, v55, vcc quad_perm:[1,0,3,2] row_mask:0xf bank_mask:0xf
	global_store_dwordx4 v171, v[132:135], s[92:93]
	global_store_dwordx4 v171, v[52:55], s[92:93] offset:2048
	v_mov_b32_e32 v114, v173
	s_add_u32 s84, s58, 0x18000
	s_addc_u32 s85, s59, 0
	s_add_u32 s86, s74, 0xc000
	s_addc_u32 s87, s75, 0
	global_load_dwordx4 v[116:119], v171, s[84:85]
	global_load_dwordx2 v[120:121], v170, s[86:87]
	global_load_dwordx4 v[122:125], v171, s[84:85] offset:2048
	global_load_dwordx2 v[126:127], v170, s[86:87] offset:1024
	s_waitcnt vmcnt(10)
	s_mov_b64 vcc, s[66:67]
	v_cndmask_b32_dpp v48, v226, v222, vcc quad_perm:[1,0,3,2] row_mask:0xf bank_mask:0xf
	v_cndmask_b32_dpp v49, v227, v223, vcc quad_perm:[1,0,3,2] row_mask:0xf bank_mask:0xf
	v_cndmask_b32_dpp v50, v228, v224, vcc quad_perm:[1,0,3,2] row_mask:0xf bank_mask:0xf
	v_cndmask_b32_dpp v51, v229, v225, vcc quad_perm:[1,0,3,2] row_mask:0xf bank_mask:0xf
	s_mov_b64 vcc, s[62:63]
	v_cndmask_b32_dpp v226, v222, v226, vcc quad_perm:[1,0,3,2] row_mask:0xf bank_mask:0xf
	v_cndmask_b32_dpp v227, v223, v227, vcc quad_perm:[1,0,3,2] row_mask:0xf bank_mask:0xf
	v_cndmask_b32_dpp v228, v224, v228, vcc quad_perm:[1,0,3,2] row_mask:0xf bank_mask:0xf
	v_cndmask_b32_dpp v229, v225, v229, vcc quad_perm:[1,0,3,2] row_mask:0xf bank_mask:0xf
	s_mov_b64 vcc, s[66:67]
	v_cndmask_b32_dpp v52, v230, v144, vcc quad_perm:[1,0,3,2] row_mask:0xf bank_mask:0xf
	v_cndmask_b32_dpp v53, v231, v145, vcc quad_perm:[1,0,3,2] row_mask:0xf bank_mask:0xf
	s_mov_b64 vcc, s[62:63]
	v_cndmask_b32_dpp v230, v144, v230, vcc quad_perm:[1,0,3,2] row_mask:0xf bank_mask:0xf
	v_cndmask_b32_dpp v231, v145, v231, vcc quad_perm:[1,0,3,2] row_mask:0xf bank_mask:0xf
	v_perm_b32 v44, v48, v52, s32
	v_perm_b32 v45, v48, v52, s8
	v_perm_b32 v46, v49, v52, s61
	v_perm_b32 v47, v49, v52, s98
	v_pk_fma_f32 v[110:111], v[110:111], v[174:175], v[44:45]
	v_pk_fma_f32 v[112:113], v[112:113], v[176:177], v[46:47]
	v_perm_b32 v44, v50, v53, s32
	v_perm_b32 v45, v50, v53, s8
	v_perm_b32 v46, v51, v53, s61
	v_perm_b32 v47, v51, v53, s98
	v_pk_fma_f32 v[106:107], v[106:107], v[178:179], v[44:45]
	v_pk_fma_f32 v[108:109], v[108:109], v[180:181], v[46:47]
	v_perm_b32 v44, v226, v230, s32
	v_perm_b32 v45, v226, v230, s8
	v_perm_b32 v46, v227, v230, s61
	v_perm_b32 v47, v227, v230, s98
	v_pk_fma_f32 v[102:103], v[102:103], v[182:183], v[44:45]
	v_pk_fma_f32 v[104:105], v[104:105], v[184:185], v[46:47]
	v_perm_b32 v44, v228, v231, s32
	v_perm_b32 v45, v228, v231, s8
	v_perm_b32 v46, v229, v231, s61
	v_perm_b32 v47, v229, v231, s98
	v_pk_fma_f32 v[98:99], v[98:99], v[186:187], v[44:45]
	v_pk_fma_f32 v[100:101], v[100:101], v[188:189], v[46:47]
	v_mul_f32_e32 v44, v111, v111
	v_mul_f32_e32 v45, v113, v113
	v_mul_f32_e32 v46, v107, v107
	v_mul_f32_e32 v47, v109, v109
	v_fmac_f32_e32 v44, v110, v110
	v_fmac_f32_e32 v45, v112, v112
	v_fmac_f32_e32 v46, v106, v106
	v_fmac_f32_e32 v47, v108, v108
	v_add_f32_e32 v44, v44, v45
	v_add_f32_e32 v46, v46, v47
	v_add_f32_e32 v173, v44, v46
	v_add_u32_e32 v44, 0x80, v110
	v_add_u32_e32 v45, 0x80, v111
	v_add_u32_e32 v46, 0x80, v112
	v_add_u32_e32 v47, 0x80, v113
	v_perm_b32 v48, v45, v44, s78
	v_perm_b32 v49, v47, v46, s78
	v_perm_b32 v42, v45, v44, s79
	v_perm_b32 v43, v47, v46, s79
	v_perm_b32 v56, v43, v42, s60
	v_add_u32_e32 v44, 0x80, v106
	v_add_u32_e32 v45, 0x80, v107
	v_add_u32_e32 v46, 0x80, v108
	v_add_u32_e32 v47, 0x80, v109
	v_perm_b32 v50, v45, v44, s78
	v_perm_b32 v51, v47, v46, s78
	v_perm_b32 v42, v45, v44, s79
	v_perm_b32 v43, v47, v46, s79
	v_perm_b32 v57, v43, v42, s60
	v_mul_f32_e32 v44, v103, v103
	v_mul_f32_e32 v45, v105, v105
	v_mul_f32_e32 v46, v99, v99
	v_mul_f32_e32 v47, v101, v101
	v_fmac_f32_e32 v44, v102, v102
	v_fmac_f32_e32 v45, v104, v104
	v_fmac_f32_e32 v46, v98, v98
	v_fmac_f32_e32 v47, v100, v100
	v_add_f32_e32 v44, v44, v45
	v_add_f32_e32 v46, v46, v47
	v_add_f32_e32 v44, v44, v46
	v_add_f32_e32 v173, v173, v44
	v_add_u32_e32 v44, 0x80, v102
	v_add_u32_e32 v45, 0x80, v103
	v_add_u32_e32 v46, 0x80, v104
	v_add_u32_e32 v47, 0x80, v105
	v_perm_b32 v52, v45, v44, s78
	v_perm_b32 v53, v47, v46, s78
	v_perm_b32 v42, v45, v44, s79
	v_perm_b32 v43, v47, v46, s79
	v_perm_b32 v168, v43, v42, s60
	v_add_u32_e32 v44, 0x80, v98
	v_add_u32_e32 v45, 0x80, v99
	v_add_u32_e32 v46, 0x80, v100
	v_add_u32_e32 v47, 0x80, v101
	v_perm_b32 v54, v45, v44, s78
	v_perm_b32 v55, v47, v46, s78
	v_perm_b32 v42, v45, v44, s79
	v_perm_b32 v43, v47, v46, s79
	v_perm_b32 v169, v43, v42, s60
	s_mov_b64 vcc, s[66:67]
	v_cndmask_b32_dpp v222, v52, v48, vcc quad_perm:[1,0,3,2] row_mask:0xf bank_mask:0xf
	v_cndmask_b32_dpp v223, v53, v49, vcc quad_perm:[1,0,3,2] row_mask:0xf bank_mask:0xf
	v_cndmask_b32_dpp v224, v54, v50, vcc quad_perm:[1,0,3,2] row_mask:0xf bank_mask:0xf
	v_cndmask_b32_dpp v225, v55, v51, vcc quad_perm:[1,0,3,2] row_mask:0xf bank_mask:0xf
	s_mov_b64 vcc, s[62:63]
	v_cndmask_b32_dpp v52, v48, v52, vcc quad_perm:[1,0,3,2] row_mask:0xf bank_mask:0xf
	v_cndmask_b32_dpp v53, v49, v53, vcc quad_perm:[1,0,3,2] row_mask:0xf bank_mask:0xf
	v_cndmask_b32_dpp v54, v50, v54, vcc quad_perm:[1,0,3,2] row_mask:0xf bank_mask:0xf
	v_cndmask_b32_dpp v55, v51, v55, vcc quad_perm:[1,0,3,2] row_mask:0xf bank_mask:0xf
	s_mov_b64 vcc, s[66:67]
	v_cndmask_b32_dpp v226, v168, v56, vcc quad_perm:[1,0,3,2] row_mask:0xf bank_mask:0xf
	v_cndmask_b32_dpp v227, v169, v57, vcc quad_perm:[1,0,3,2] row_mask:0xf bank_mask:0xf
	s_mov_b64 vcc, s[62:63]
	v_cndmask_b32_dpp v168, v56, v168, vcc quad_perm:[1,0,3,2] row_mask:0xf bank_mask:0xf
	v_cndmask_b32_dpp v169, v57, v169, vcc quad_perm:[1,0,3,2] row_mask:0xf bank_mask:0xf
	s_add_u32 s88, s58, 0x10000
	s_addc_u32 s89, s59, 0
	s_add_u32 s90, s74, 0x8000
	s_addc_u32 s91, s75, 0
	global_store_dwordx4 v171, v[222:225], s[88:89]
	global_store_dwordx4 v171, v[52:55], s[88:89] offset:2048
	global_store_dwordx2 v170, v[226:227], s[90:91]
	global_store_dwordx2 v170, v[168:169], s[90:91] offset:1024
	s_add_u32 s92, s96, 0x10000
	s_addc_u32 s93, s97, 0
	v_pk_mul_f32 v[110:111], v[190:191], v[110:111]
	v_pk_mul_f32 v[112:113], v[192:193], v[112:113]
	v_pk_mul_f32 v[106:107], v[210:211], v[106:107]
	v_pk_mul_f32 v[108:109], v[212:213], v[108:109]
	v_cvt_pk_bf16_f32 v48, v110, v111
	v_cvt_pk_bf16_f32 v49, v112, v113
	v_cvt_pk_bf16_f32 v50, v106, v107
	v_cvt_pk_bf16_f32 v51, v108, v109
	v_pk_mul_f32 v[102:103], v[214:215], v[102:103]
	v_pk_mul_f32 v[104:105], v[216:217], v[104:105]
	v_pk_mul_f32 v[98:99], v[218:219], v[98:99]
	v_pk_mul_f32 v[100:101], v[220:221], v[100:101]
	v_cvt_pk_bf16_f32 v52, v102, v103
	v_cvt_pk_bf16_f32 v53, v104, v105
	v_cvt_pk_bf16_f32 v54, v98, v99
	v_cvt_pk_bf16_f32 v55, v100, v101
	s_mov_b64 vcc, s[66:67]
	v_cndmask_b32_dpp v222, v52, v48, vcc quad_perm:[1,0,3,2] row_mask:0xf bank_mask:0xf
	v_cndmask_b32_dpp v223, v53, v49, vcc quad_perm:[1,0,3,2] row_mask:0xf bank_mask:0xf
	v_cndmask_b32_dpp v224, v54, v50, vcc quad_perm:[1,0,3,2] row_mask:0xf bank_mask:0xf
	v_cndmask_b32_dpp v225, v55, v51, vcc quad_perm:[1,0,3,2] row_mask:0xf bank_mask:0xf
	s_mov_b64 vcc, s[62:63]
	v_cndmask_b32_dpp v52, v48, v52, vcc quad_perm:[1,0,3,2] row_mask:0xf bank_mask:0xf
	v_cndmask_b32_dpp v53, v49, v53, vcc quad_perm:[1,0,3,2] row_mask:0xf bank_mask:0xf
	v_cndmask_b32_dpp v54, v50, v54, vcc quad_perm:[1,0,3,2] row_mask:0xf bank_mask:0xf
	v_cndmask_b32_dpp v55, v51, v55, vcc quad_perm:[1,0,3,2] row_mask:0xf bank_mask:0xf
	global_store_dwordx4 v171, v[222:225], s[92:93]
	global_store_dwordx4 v171, v[52:55], s[92:93] offset:2048
	v_mov_b32_e32 v98, v173
	s_add_u32 s84, s58, 0x40000
	s_addc_u32 s85, s59, 0
	s_add_u32 s86, s74, 0x20000
	s_addc_u32 s87, s75, 0
	global_load_dwordx4 v[100:103], v171, s[84:85]
	global_load_dwordx2 v[104:105], v170, s[86:87]
	global_load_dwordx4 v[106:109], v171, s[84:85] offset:2048
	global_load_dwordx2 v[110:111], v170, s[86:87] offset:1024
	s_waitcnt vmcnt(10)
	s_mov_b64 vcc, s[66:67]
	v_cndmask_b32_dpp v48, v122, v116, vcc quad_perm:[1,0,3,2] row_mask:0xf bank_mask:0xf
	v_cndmask_b32_dpp v49, v123, v117, vcc quad_perm:[1,0,3,2] row_mask:0xf bank_mask:0xf
	v_cndmask_b32_dpp v50, v124, v118, vcc quad_perm:[1,0,3,2] row_mask:0xf bank_mask:0xf
	v_cndmask_b32_dpp v51, v125, v119, vcc quad_perm:[1,0,3,2] row_mask:0xf bank_mask:0xf
	s_mov_b64 vcc, s[62:63]
	v_cndmask_b32_dpp v122, v116, v122, vcc quad_perm:[1,0,3,2] row_mask:0xf bank_mask:0xf
	v_cndmask_b32_dpp v123, v117, v123, vcc quad_perm:[1,0,3,2] row_mask:0xf bank_mask:0xf
	v_cndmask_b32_dpp v124, v118, v124, vcc quad_perm:[1,0,3,2] row_mask:0xf bank_mask:0xf
	v_cndmask_b32_dpp v125, v119, v125, vcc quad_perm:[1,0,3,2] row_mask:0xf bank_mask:0xf
	s_mov_b64 vcc, s[66:67]
	v_cndmask_b32_dpp v52, v126, v120, vcc quad_perm:[1,0,3,2] row_mask:0xf bank_mask:0xf
	v_cndmask_b32_dpp v53, v127, v121, vcc quad_perm:[1,0,3,2] row_mask:0xf bank_mask:0xf
	s_mov_b64 vcc, s[62:63]
	v_cndmask_b32_dpp v126, v120, v126, vcc quad_perm:[1,0,3,2] row_mask:0xf bank_mask:0xf
	v_cndmask_b32_dpp v127, v121, v127, vcc quad_perm:[1,0,3,2] row_mask:0xf bank_mask:0xf
	v_perm_b32 v44, v48, v52, s32
	v_perm_b32 v45, v48, v52, s8
	v_perm_b32 v46, v49, v52, s61
	v_perm_b32 v47, v49, v52, s98
	v_pk_fma_f32 v[94:95], v[94:95], v[174:175], v[44:45]
	v_pk_fma_f32 v[96:97], v[96:97], v[176:177], v[46:47]
	v_perm_b32 v44, v50, v53, s32
	v_perm_b32 v45, v50, v53, s8
	v_perm_b32 v46, v51, v53, s61
	v_perm_b32 v47, v51, v53, s98
	v_pk_fma_f32 v[90:91], v[90:91], v[178:179], v[44:45]
	v_pk_fma_f32 v[92:93], v[92:93], v[180:181], v[46:47]
	v_perm_b32 v44, v122, v126, s32
	v_perm_b32 v45, v122, v126, s8
	v_perm_b32 v46, v123, v126, s61
	v_perm_b32 v47, v123, v126, s98
	v_pk_fma_f32 v[86:87], v[86:87], v[182:183], v[44:45]
	v_pk_fma_f32 v[88:89], v[88:89], v[184:185], v[46:47]
	v_perm_b32 v44, v124, v127, s32
	v_perm_b32 v45, v124, v127, s8
	v_perm_b32 v46, v125, v127, s61
	v_perm_b32 v47, v125, v127, s98
	v_pk_fma_f32 v[82:83], v[82:83], v[186:187], v[44:45]
	v_pk_fma_f32 v[84:85], v[84:85], v[188:189], v[46:47]
	v_mul_f32_e32 v44, v95, v95
	v_mul_f32_e32 v45, v97, v97
	v_mul_f32_e32 v46, v91, v91
	v_mul_f32_e32 v47, v93, v93
	v_fmac_f32_e32 v44, v94, v94
	v_fmac_f32_e32 v45, v96, v96
	v_fmac_f32_e32 v46, v90, v90
	v_fmac_f32_e32 v47, v92, v92
	v_add_f32_e32 v44, v44, v45
	v_add_f32_e32 v46, v46, v47
	v_add_f32_e32 v173, v44, v46
	v_add_u32_e32 v44, 0x80, v94
	v_add_u32_e32 v45, 0x80, v95
	v_add_u32_e32 v46, 0x80, v96
	v_add_u32_e32 v47, 0x80, v97
	v_perm_b32 v48, v45, v44, s78
	v_perm_b32 v49, v47, v46, s78
	v_perm_b32 v42, v45, v44, s79
	v_perm_b32 v43, v47, v46, s79
	v_perm_b32 v56, v43, v42, s60
	v_add_u32_e32 v44, 0x80, v90
	v_add_u32_e32 v45, 0x80, v91
	v_add_u32_e32 v46, 0x80, v92
	v_add_u32_e32 v47, 0x80, v93
	v_perm_b32 v50, v45, v44, s78
	v_perm_b32 v51, v47, v46, s78
	v_perm_b32 v42, v45, v44, s79
	v_perm_b32 v43, v47, v46, s79
	v_perm_b32 v57, v43, v42, s60
	v_mul_f32_e32 v44, v87, v87
	v_mul_f32_e32 v45, v89, v89
	v_mul_f32_e32 v46, v83, v83
	v_mul_f32_e32 v47, v85, v85
	v_fmac_f32_e32 v44, v86, v86
	v_fmac_f32_e32 v45, v88, v88
	v_fmac_f32_e32 v46, v82, v82
	v_fmac_f32_e32 v47, v84, v84
	v_add_f32_e32 v44, v44, v45
	v_add_f32_e32 v46, v46, v47
	v_add_f32_e32 v44, v44, v46
	v_add_f32_e32 v173, v173, v44
	v_add_u32_e32 v44, 0x80, v86
	v_add_u32_e32 v45, 0x80, v87
	v_add_u32_e32 v46, 0x80, v88
	v_add_u32_e32 v47, 0x80, v89
	v_perm_b32 v52, v45, v44, s78
	v_perm_b32 v53, v47, v46, s78
	v_perm_b32 v42, v45, v44, s79
	v_perm_b32 v43, v47, v46, s79
	v_perm_b32 v168, v43, v42, s60
	v_add_u32_e32 v44, 0x80, v82
	v_add_u32_e32 v45, 0x80, v83
	v_add_u32_e32 v46, 0x80, v84
	v_add_u32_e32 v47, 0x80, v85
	v_perm_b32 v54, v45, v44, s78
	v_perm_b32 v55, v47, v46, s78
	v_perm_b32 v42, v45, v44, s79
	v_perm_b32 v43, v47, v46, s79
	v_perm_b32 v169, v43, v42, s60
	s_mov_b64 vcc, s[66:67]
	v_cndmask_b32_dpp v116, v52, v48, vcc quad_perm:[1,0,3,2] row_mask:0xf bank_mask:0xf
	v_cndmask_b32_dpp v117, v53, v49, vcc quad_perm:[1,0,3,2] row_mask:0xf bank_mask:0xf
	v_cndmask_b32_dpp v118, v54, v50, vcc quad_perm:[1,0,3,2] row_mask:0xf bank_mask:0xf
	v_cndmask_b32_dpp v119, v55, v51, vcc quad_perm:[1,0,3,2] row_mask:0xf bank_mask:0xf
	s_mov_b64 vcc, s[62:63]
	v_cndmask_b32_dpp v52, v48, v52, vcc quad_perm:[1,0,3,2] row_mask:0xf bank_mask:0xf
	v_cndmask_b32_dpp v53, v49, v53, vcc quad_perm:[1,0,3,2] row_mask:0xf bank_mask:0xf
	v_cndmask_b32_dpp v54, v50, v54, vcc quad_perm:[1,0,3,2] row_mask:0xf bank_mask:0xf
	v_cndmask_b32_dpp v55, v51, v55, vcc quad_perm:[1,0,3,2] row_mask:0xf bank_mask:0xf
	s_mov_b64 vcc, s[66:67]
	v_cndmask_b32_dpp v122, v168, v56, vcc quad_perm:[1,0,3,2] row_mask:0xf bank_mask:0xf
	v_cndmask_b32_dpp v123, v169, v57, vcc quad_perm:[1,0,3,2] row_mask:0xf bank_mask:0xf
	s_mov_b64 vcc, s[62:63]
	v_cndmask_b32_dpp v168, v56, v168, vcc quad_perm:[1,0,3,2] row_mask:0xf bank_mask:0xf
	v_cndmask_b32_dpp v169, v57, v169, vcc quad_perm:[1,0,3,2] row_mask:0xf bank_mask:0xf
	s_add_u32 s88, s58, 0x18000
	s_addc_u32 s89, s59, 0
	s_add_u32 s90, s74, 0xc000
	s_addc_u32 s91, s75, 0
	global_store_dwordx4 v171, v[116:119], s[88:89]
	global_store_dwordx4 v171, v[52:55], s[88:89] offset:2048
	global_store_dwordx2 v170, v[122:123], s[90:91]
	global_store_dwordx2 v170, v[168:169], s[90:91] offset:1024
	s_add_u32 s92, s96, 0x18000
	s_addc_u32 s93, s97, 0
	v_pk_mul_f32 v[94:95], v[190:191], v[94:95]
	v_pk_mul_f32 v[96:97], v[192:193], v[96:97]
	v_pk_mul_f32 v[90:91], v[210:211], v[90:91]
	v_pk_mul_f32 v[92:93], v[212:213], v[92:93]
	v_cvt_pk_bf16_f32 v48, v94, v95
	v_cvt_pk_bf16_f32 v49, v96, v97
	v_cvt_pk_bf16_f32 v50, v90, v91
	v_cvt_pk_bf16_f32 v51, v92, v93
	v_pk_mul_f32 v[86:87], v[214:215], v[86:87]
	v_pk_mul_f32 v[88:89], v[216:217], v[88:89]
	v_pk_mul_f32 v[82:83], v[218:219], v[82:83]
	v_pk_mul_f32 v[84:85], v[220:221], v[84:85]
	v_cvt_pk_bf16_f32 v52, v86, v87
	v_cvt_pk_bf16_f32 v53, v88, v89
	v_cvt_pk_bf16_f32 v54, v82, v83
	v_cvt_pk_bf16_f32 v55, v84, v85
	s_mov_b64 vcc, s[66:67]
	v_cndmask_b32_dpp v116, v52, v48, vcc quad_perm:[1,0,3,2] row_mask:0xf bank_mask:0xf
	v_cndmask_b32_dpp v117, v53, v49, vcc quad_perm:[1,0,3,2] row_mask:0xf bank_mask:0xf
	v_cndmask_b32_dpp v118, v54, v50, vcc quad_perm:[1,0,3,2] row_mask:0xf bank_mask:0xf
	v_cndmask_b32_dpp v119, v55, v51, vcc quad_perm:[1,0,3,2] row_mask:0xf bank_mask:0xf
	s_mov_b64 vcc, s[62:63]
	v_cndmask_b32_dpp v52, v48, v52, vcc quad_perm:[1,0,3,2] row_mask:0xf bank_mask:0xf
	v_cndmask_b32_dpp v53, v49, v53, vcc quad_perm:[1,0,3,2] row_mask:0xf bank_mask:0xf
	v_cndmask_b32_dpp v54, v50, v54, vcc quad_perm:[1,0,3,2] row_mask:0xf bank_mask:0xf
	v_cndmask_b32_dpp v55, v51, v55, vcc quad_perm:[1,0,3,2] row_mask:0xf bank_mask:0xf
	global_store_dwordx4 v171, v[116:119], s[92:93]
	global_store_dwordx4 v171, v[52:55], s[92:93] offset:2048
	v_mov_b32_e32 v82, v173
	s_add_u32 s84, s58, 0x48000
	s_addc_u32 s85, s59, 0
	s_add_u32 s86, s74, 0x24000
	s_addc_u32 s87, s75, 0
	global_load_dwordx4 v[84:87], v171, s[84:85]
	global_load_dwordx2 v[88:89], v170, s[86:87]
	global_load_dwordx4 v[90:93], v171, s[84:85] offset:2048
	global_load_dwordx2 v[94:95], v170, s[86:87] offset:1024
	s_waitcnt vmcnt(10)
	s_mov_b64 vcc, s[66:67]
	v_cndmask_b32_dpp v48, v106, v100, vcc quad_perm:[1,0,3,2] row_mask:0xf bank_mask:0xf
	v_cndmask_b32_dpp v49, v107, v101, vcc quad_perm:[1,0,3,2] row_mask:0xf bank_mask:0xf
	v_cndmask_b32_dpp v50, v108, v102, vcc quad_perm:[1,0,3,2] row_mask:0xf bank_mask:0xf
	v_cndmask_b32_dpp v51, v109, v103, vcc quad_perm:[1,0,3,2] row_mask:0xf bank_mask:0xf
	s_mov_b64 vcc, s[62:63]
	v_cndmask_b32_dpp v106, v100, v106, vcc quad_perm:[1,0,3,2] row_mask:0xf bank_mask:0xf
	v_cndmask_b32_dpp v107, v101, v107, vcc quad_perm:[1,0,3,2] row_mask:0xf bank_mask:0xf
	v_cndmask_b32_dpp v108, v102, v108, vcc quad_perm:[1,0,3,2] row_mask:0xf bank_mask:0xf
	v_cndmask_b32_dpp v109, v103, v109, vcc quad_perm:[1,0,3,2] row_mask:0xf bank_mask:0xf
	s_mov_b64 vcc, s[66:67]
	v_cndmask_b32_dpp v52, v110, v104, vcc quad_perm:[1,0,3,2] row_mask:0xf bank_mask:0xf
	v_cndmask_b32_dpp v53, v111, v105, vcc quad_perm:[1,0,3,2] row_mask:0xf bank_mask:0xf
	s_mov_b64 vcc, s[62:63]
	v_cndmask_b32_dpp v110, v104, v110, vcc quad_perm:[1,0,3,2] row_mask:0xf bank_mask:0xf
	v_cndmask_b32_dpp v111, v105, v111, vcc quad_perm:[1,0,3,2] row_mask:0xf bank_mask:0xf
	v_perm_b32 v44, v48, v52, s32
	v_perm_b32 v45, v48, v52, s8
	v_perm_b32 v46, v49, v52, s61
	v_perm_b32 v47, v49, v52, s98
	v_pk_fma_f32 v[78:79], v[78:79], v[174:175], v[44:45]
	v_pk_fma_f32 v[80:81], v[80:81], v[176:177], v[46:47]
	v_perm_b32 v44, v50, v53, s32
	v_perm_b32 v45, v50, v53, s8
	v_perm_b32 v46, v51, v53, s61
	v_perm_b32 v47, v51, v53, s98
	v_pk_fma_f32 v[74:75], v[74:75], v[178:179], v[44:45]
	v_pk_fma_f32 v[76:77], v[76:77], v[180:181], v[46:47]
	v_perm_b32 v44, v106, v110, s32
	v_perm_b32 v45, v106, v110, s8
	v_perm_b32 v46, v107, v110, s61
	v_perm_b32 v47, v107, v110, s98
	v_pk_fma_f32 v[70:71], v[70:71], v[182:183], v[44:45]
	v_pk_fma_f32 v[72:73], v[72:73], v[184:185], v[46:47]
	v_perm_b32 v44, v108, v111, s32
	v_perm_b32 v45, v108, v111, s8
	v_perm_b32 v46, v109, v111, s61
	v_perm_b32 v47, v109, v111, s98
	v_pk_fma_f32 v[66:67], v[66:67], v[186:187], v[44:45]
	v_pk_fma_f32 v[68:69], v[68:69], v[188:189], v[46:47]
	v_mul_f32_e32 v44, v79, v79
	v_mul_f32_e32 v45, v81, v81
	v_mul_f32_e32 v46, v75, v75
	v_mul_f32_e32 v47, v77, v77
	v_fmac_f32_e32 v44, v78, v78
	v_fmac_f32_e32 v45, v80, v80
	v_fmac_f32_e32 v46, v74, v74
	v_fmac_f32_e32 v47, v76, v76
	v_add_f32_e32 v44, v44, v45
	v_add_f32_e32 v46, v46, v47
	v_add_f32_e32 v173, v44, v46
	v_add_u32_e32 v44, 0x80, v78
	v_add_u32_e32 v45, 0x80, v79
	v_add_u32_e32 v46, 0x80, v80
	v_add_u32_e32 v47, 0x80, v81
	v_perm_b32 v48, v45, v44, s78
	v_perm_b32 v49, v47, v46, s78
	v_perm_b32 v42, v45, v44, s79
	v_perm_b32 v43, v47, v46, s79
	v_perm_b32 v56, v43, v42, s60
	v_add_u32_e32 v44, 0x80, v74
	v_add_u32_e32 v45, 0x80, v75
	v_add_u32_e32 v46, 0x80, v76
	v_add_u32_e32 v47, 0x80, v77
	v_perm_b32 v50, v45, v44, s78
	v_perm_b32 v51, v47, v46, s78
	v_perm_b32 v42, v45, v44, s79
	v_perm_b32 v43, v47, v46, s79
	v_perm_b32 v57, v43, v42, s60
	v_mul_f32_e32 v44, v71, v71
	v_mul_f32_e32 v45, v73, v73
	v_mul_f32_e32 v46, v67, v67
	v_mul_f32_e32 v47, v69, v69
	v_fmac_f32_e32 v44, v70, v70
	v_fmac_f32_e32 v45, v72, v72
	v_fmac_f32_e32 v46, v66, v66
	v_fmac_f32_e32 v47, v68, v68
	v_add_f32_e32 v44, v44, v45
	v_add_f32_e32 v46, v46, v47
	v_add_f32_e32 v44, v44, v46
	v_add_f32_e32 v173, v173, v44
	v_add_u32_e32 v44, 0x80, v70
	v_add_u32_e32 v45, 0x80, v71
	v_add_u32_e32 v46, 0x80, v72
	v_add_u32_e32 v47, 0x80, v73
	v_perm_b32 v52, v45, v44, s78
	v_perm_b32 v53, v47, v46, s78
	v_perm_b32 v42, v45, v44, s79
	v_perm_b32 v43, v47, v46, s79
	v_perm_b32 v168, v43, v42, s60
	v_add_u32_e32 v44, 0x80, v66
	v_add_u32_e32 v45, 0x80, v67
	v_add_u32_e32 v46, 0x80, v68
	v_add_u32_e32 v47, 0x80, v69
	v_perm_b32 v54, v45, v44, s78
	v_perm_b32 v55, v47, v46, s78
	v_perm_b32 v42, v45, v44, s79
	v_perm_b32 v43, v47, v46, s79
	v_perm_b32 v169, v43, v42, s60
	s_mov_b64 vcc, s[66:67]
	v_cndmask_b32_dpp v100, v52, v48, vcc quad_perm:[1,0,3,2] row_mask:0xf bank_mask:0xf
	v_cndmask_b32_dpp v101, v53, v49, vcc quad_perm:[1,0,3,2] row_mask:0xf bank_mask:0xf
	v_cndmask_b32_dpp v102, v54, v50, vcc quad_perm:[1,0,3,2] row_mask:0xf bank_mask:0xf
	v_cndmask_b32_dpp v103, v55, v51, vcc quad_perm:[1,0,3,2] row_mask:0xf bank_mask:0xf
	s_mov_b64 vcc, s[62:63]
	v_cndmask_b32_dpp v52, v48, v52, vcc quad_perm:[1,0,3,2] row_mask:0xf bank_mask:0xf
	v_cndmask_b32_dpp v53, v49, v53, vcc quad_perm:[1,0,3,2] row_mask:0xf bank_mask:0xf
	v_cndmask_b32_dpp v54, v50, v54, vcc quad_perm:[1,0,3,2] row_mask:0xf bank_mask:0xf
	v_cndmask_b32_dpp v55, v51, v55, vcc quad_perm:[1,0,3,2] row_mask:0xf bank_mask:0xf
	s_mov_b64 vcc, s[66:67]
	v_cndmask_b32_dpp v106, v168, v56, vcc quad_perm:[1,0,3,2] row_mask:0xf bank_mask:0xf
	v_cndmask_b32_dpp v107, v169, v57, vcc quad_perm:[1,0,3,2] row_mask:0xf bank_mask:0xf
	s_mov_b64 vcc, s[62:63]
	v_cndmask_b32_dpp v168, v56, v168, vcc quad_perm:[1,0,3,2] row_mask:0xf bank_mask:0xf
	v_cndmask_b32_dpp v169, v57, v169, vcc quad_perm:[1,0,3,2] row_mask:0xf bank_mask:0xf
	s_add_u32 s88, s58, 0x40000
	s_addc_u32 s89, s59, 0
	s_add_u32 s90, s74, 0x20000
	s_addc_u32 s91, s75, 0
	global_store_dwordx4 v171, v[100:103], s[88:89]
	global_store_dwordx4 v171, v[52:55], s[88:89] offset:2048
	global_store_dwordx2 v170, v[106:107], s[90:91]
	global_store_dwordx2 v170, v[168:169], s[90:91] offset:1024
	s_add_u32 s92, s96, 0x40000
	s_addc_u32 s93, s97, 0
	v_pk_mul_f32 v[78:79], v[190:191], v[78:79]
	v_pk_mul_f32 v[80:81], v[192:193], v[80:81]
	v_pk_mul_f32 v[74:75], v[210:211], v[74:75]
	v_pk_mul_f32 v[76:77], v[212:213], v[76:77]
	v_cvt_pk_bf16_f32 v48, v78, v79
	v_cvt_pk_bf16_f32 v49, v80, v81
	v_cvt_pk_bf16_f32 v50, v74, v75
	v_cvt_pk_bf16_f32 v51, v76, v77
	v_pk_mul_f32 v[70:71], v[214:215], v[70:71]
	v_pk_mul_f32 v[72:73], v[216:217], v[72:73]
	v_pk_mul_f32 v[66:67], v[218:219], v[66:67]
	v_pk_mul_f32 v[68:69], v[220:221], v[68:69]
	v_cvt_pk_bf16_f32 v52, v70, v71
	v_cvt_pk_bf16_f32 v53, v72, v73
	v_cvt_pk_bf16_f32 v54, v66, v67
	v_cvt_pk_bf16_f32 v55, v68, v69
	s_mov_b64 vcc, s[66:67]
	v_cndmask_b32_dpp v100, v52, v48, vcc quad_perm:[1,0,3,2] row_mask:0xf bank_mask:0xf
	v_cndmask_b32_dpp v101, v53, v49, vcc quad_perm:[1,0,3,2] row_mask:0xf bank_mask:0xf
	v_cndmask_b32_dpp v102, v54, v50, vcc quad_perm:[1,0,3,2] row_mask:0xf bank_mask:0xf
	v_cndmask_b32_dpp v103, v55, v51, vcc quad_perm:[1,0,3,2] row_mask:0xf bank_mask:0xf
	s_mov_b64 vcc, s[62:63]
	v_cndmask_b32_dpp v52, v48, v52, vcc quad_perm:[1,0,3,2] row_mask:0xf bank_mask:0xf
	v_cndmask_b32_dpp v53, v49, v53, vcc quad_perm:[1,0,3,2] row_mask:0xf bank_mask:0xf
	v_cndmask_b32_dpp v54, v50, v54, vcc quad_perm:[1,0,3,2] row_mask:0xf bank_mask:0xf
	v_cndmask_b32_dpp v55, v51, v55, vcc quad_perm:[1,0,3,2] row_mask:0xf bank_mask:0xf
	global_store_dwordx4 v171, v[100:103], s[92:93]
	global_store_dwordx4 v171, v[52:55], s[92:93] offset:2048
	v_mov_b32_e32 v66, v173
	s_add_u32 s84, s58, 0x50000
	s_addc_u32 s85, s59, 0
	s_add_u32 s86, s74, 0x28000
	s_addc_u32 s87, s75, 0
	global_load_dwordx4 v[68:71], v171, s[84:85]
	global_load_dwordx2 v[72:73], v170, s[86:87]
	global_load_dwordx4 v[74:77], v171, s[84:85] offset:2048
	global_load_dwordx2 v[78:79], v170, s[86:87] offset:1024
	s_waitcnt vmcnt(10)
	s_mov_b64 vcc, s[66:67]
	v_cndmask_b32_dpp v48, v90, v84, vcc quad_perm:[1,0,3,2] row_mask:0xf bank_mask:0xf
	v_cndmask_b32_dpp v49, v91, v85, vcc quad_perm:[1,0,3,2] row_mask:0xf bank_mask:0xf
	v_cndmask_b32_dpp v50, v92, v86, vcc quad_perm:[1,0,3,2] row_mask:0xf bank_mask:0xf
	v_cndmask_b32_dpp v51, v93, v87, vcc quad_perm:[1,0,3,2] row_mask:0xf bank_mask:0xf
	s_mov_b64 vcc, s[62:63]
	v_cndmask_b32_dpp v90, v84, v90, vcc quad_perm:[1,0,3,2] row_mask:0xf bank_mask:0xf
	v_cndmask_b32_dpp v91, v85, v91, vcc quad_perm:[1,0,3,2] row_mask:0xf bank_mask:0xf
	v_cndmask_b32_dpp v92, v86, v92, vcc quad_perm:[1,0,3,2] row_mask:0xf bank_mask:0xf
	v_cndmask_b32_dpp v93, v87, v93, vcc quad_perm:[1,0,3,2] row_mask:0xf bank_mask:0xf
	s_mov_b64 vcc, s[66:67]
	v_cndmask_b32_dpp v52, v94, v88, vcc quad_perm:[1,0,3,2] row_mask:0xf bank_mask:0xf
	v_cndmask_b32_dpp v53, v95, v89, vcc quad_perm:[1,0,3,2] row_mask:0xf bank_mask:0xf
	s_mov_b64 vcc, s[62:63]
	v_cndmask_b32_dpp v94, v88, v94, vcc quad_perm:[1,0,3,2] row_mask:0xf bank_mask:0xf
	v_cndmask_b32_dpp v95, v89, v95, vcc quad_perm:[1,0,3,2] row_mask:0xf bank_mask:0xf
	v_perm_b32 v44, v48, v52, s32
	v_perm_b32 v45, v48, v52, s8
	v_perm_b32 v46, v49, v52, s61
	v_perm_b32 v47, v49, v52, s98
	v_pk_fma_f32 v[62:63], v[62:63], v[174:175], v[44:45]
	v_pk_fma_f32 v[64:65], v[64:65], v[176:177], v[46:47]
	v_perm_b32 v44, v50, v53, s32
	v_perm_b32 v45, v50, v53, s8
	v_perm_b32 v46, v51, v53, s61
	v_perm_b32 v47, v51, v53, s98
	v_pk_fma_f32 v[58:59], v[58:59], v[178:179], v[44:45]
	v_pk_fma_f32 v[60:61], v[60:61], v[180:181], v[46:47]
	v_perm_b32 v44, v90, v94, s32
	v_perm_b32 v45, v90, v94, s8
	v_perm_b32 v46, v91, v94, s61
	v_perm_b32 v47, v91, v94, s98
	v_pk_fma_f32 v[38:39], v[38:39], v[182:183], v[44:45]
	v_pk_fma_f32 v[40:41], v[40:41], v[184:185], v[46:47]
	v_perm_b32 v44, v92, v95, s32
	v_perm_b32 v45, v92, v95, s8
	v_perm_b32 v46, v93, v95, s61
	v_perm_b32 v47, v93, v95, s98
	v_pk_fma_f32 v[34:35], v[34:35], v[186:187], v[44:45]
	v_pk_fma_f32 v[36:37], v[36:37], v[188:189], v[46:47]
	v_mul_f32_e32 v44, v63, v63
	v_mul_f32_e32 v45, v65, v65
	v_mul_f32_e32 v46, v59, v59
	v_mul_f32_e32 v47, v61, v61
	v_fmac_f32_e32 v44, v62, v62
	v_fmac_f32_e32 v45, v64, v64
	v_fmac_f32_e32 v46, v58, v58
	v_fmac_f32_e32 v47, v60, v60
	v_add_f32_e32 v44, v44, v45
	v_add_f32_e32 v46, v46, v47
	v_add_f32_e32 v173, v44, v46
	v_add_u32_e32 v44, 0x80, v62
	v_add_u32_e32 v45, 0x80, v63
	v_add_u32_e32 v46, 0x80, v64
	v_add_u32_e32 v47, 0x80, v65
	v_perm_b32 v48, v45, v44, s78
	v_perm_b32 v49, v47, v46, s78
	v_perm_b32 v42, v45, v44, s79
	v_perm_b32 v43, v47, v46, s79
	v_perm_b32 v56, v43, v42, s60
	v_add_u32_e32 v44, 0x80, v58
	v_add_u32_e32 v45, 0x80, v59
	v_add_u32_e32 v46, 0x80, v60
	v_add_u32_e32 v47, 0x80, v61
	v_perm_b32 v50, v45, v44, s78
	v_perm_b32 v51, v47, v46, s78
	v_perm_b32 v42, v45, v44, s79
	v_perm_b32 v43, v47, v46, s79
	v_perm_b32 v57, v43, v42, s60
	v_mul_f32_e32 v44, v39, v39
	v_mul_f32_e32 v45, v41, v41
	v_mul_f32_e32 v46, v35, v35
	v_mul_f32_e32 v47, v37, v37
	v_fmac_f32_e32 v44, v38, v38
	v_fmac_f32_e32 v45, v40, v40
	v_fmac_f32_e32 v46, v34, v34
	v_fmac_f32_e32 v47, v36, v36
	v_add_f32_e32 v44, v44, v45
	v_add_f32_e32 v46, v46, v47
	v_add_f32_e32 v44, v44, v46
	v_add_f32_e32 v173, v173, v44
	v_add_u32_e32 v44, 0x80, v38
	v_add_u32_e32 v45, 0x80, v39
	v_add_u32_e32 v46, 0x80, v40
	v_add_u32_e32 v47, 0x80, v41
	v_perm_b32 v52, v45, v44, s78
	v_perm_b32 v53, v47, v46, s78
	v_perm_b32 v42, v45, v44, s79
	v_perm_b32 v43, v47, v46, s79
	v_perm_b32 v168, v43, v42, s60
	v_add_u32_e32 v44, 0x80, v34
	v_add_u32_e32 v45, 0x80, v35
	v_add_u32_e32 v46, 0x80, v36
	v_add_u32_e32 v47, 0x80, v37
	v_perm_b32 v54, v45, v44, s78
	v_perm_b32 v55, v47, v46, s78
	v_perm_b32 v42, v45, v44, s79
	v_perm_b32 v43, v47, v46, s79
	v_perm_b32 v169, v43, v42, s60
	s_mov_b64 vcc, s[66:67]
	v_cndmask_b32_dpp v84, v52, v48, vcc quad_perm:[1,0,3,2] row_mask:0xf bank_mask:0xf
	v_cndmask_b32_dpp v85, v53, v49, vcc quad_perm:[1,0,3,2] row_mask:0xf bank_mask:0xf
	v_cndmask_b32_dpp v86, v54, v50, vcc quad_perm:[1,0,3,2] row_mask:0xf bank_mask:0xf
	v_cndmask_b32_dpp v87, v55, v51, vcc quad_perm:[1,0,3,2] row_mask:0xf bank_mask:0xf
	s_mov_b64 vcc, s[62:63]
	v_cndmask_b32_dpp v52, v48, v52, vcc quad_perm:[1,0,3,2] row_mask:0xf bank_mask:0xf
	v_cndmask_b32_dpp v53, v49, v53, vcc quad_perm:[1,0,3,2] row_mask:0xf bank_mask:0xf
	v_cndmask_b32_dpp v54, v50, v54, vcc quad_perm:[1,0,3,2] row_mask:0xf bank_mask:0xf
	v_cndmask_b32_dpp v55, v51, v55, vcc quad_perm:[1,0,3,2] row_mask:0xf bank_mask:0xf
	s_mov_b64 vcc, s[66:67]
	v_cndmask_b32_dpp v90, v168, v56, vcc quad_perm:[1,0,3,2] row_mask:0xf bank_mask:0xf
	v_cndmask_b32_dpp v91, v169, v57, vcc quad_perm:[1,0,3,2] row_mask:0xf bank_mask:0xf
	s_mov_b64 vcc, s[62:63]
	v_cndmask_b32_dpp v168, v56, v168, vcc quad_perm:[1,0,3,2] row_mask:0xf bank_mask:0xf
	v_cndmask_b32_dpp v169, v57, v169, vcc quad_perm:[1,0,3,2] row_mask:0xf bank_mask:0xf
	s_add_u32 s88, s58, 0x48000
	s_addc_u32 s89, s59, 0
	s_add_u32 s90, s74, 0x24000
	s_addc_u32 s91, s75, 0
	global_store_dwordx4 v171, v[84:87], s[88:89]
	global_store_dwordx4 v171, v[52:55], s[88:89] offset:2048
	global_store_dwordx2 v170, v[90:91], s[90:91]
	global_store_dwordx2 v170, v[168:169], s[90:91] offset:1024
	s_add_u32 s92, s96, 0x48000
	s_addc_u32 s93, s97, 0
	v_pk_mul_f32 v[62:63], v[190:191], v[62:63]
	v_pk_mul_f32 v[64:65], v[192:193], v[64:65]
	v_pk_mul_f32 v[58:59], v[210:211], v[58:59]
	v_pk_mul_f32 v[60:61], v[212:213], v[60:61]
	v_cvt_pk_bf16_f32 v48, v62, v63
	v_cvt_pk_bf16_f32 v49, v64, v65
	v_cvt_pk_bf16_f32 v50, v58, v59
	v_cvt_pk_bf16_f32 v51, v60, v61
	v_pk_mul_f32 v[38:39], v[214:215], v[38:39]
	v_pk_mul_f32 v[40:41], v[216:217], v[40:41]
	v_pk_mul_f32 v[34:35], v[218:219], v[34:35]
	v_pk_mul_f32 v[36:37], v[220:221], v[36:37]
	v_cvt_pk_bf16_f32 v52, v38, v39
	v_cvt_pk_bf16_f32 v53, v40, v41
	v_cvt_pk_bf16_f32 v54, v34, v35
	v_cvt_pk_bf16_f32 v55, v36, v37
	s_mov_b64 vcc, s[66:67]
	v_cndmask_b32_dpp v84, v52, v48, vcc quad_perm:[1,0,3,2] row_mask:0xf bank_mask:0xf
	v_cndmask_b32_dpp v85, v53, v49, vcc quad_perm:[1,0,3,2] row_mask:0xf bank_mask:0xf
	v_cndmask_b32_dpp v86, v54, v50, vcc quad_perm:[1,0,3,2] row_mask:0xf bank_mask:0xf
	v_cndmask_b32_dpp v87, v55, v51, vcc quad_perm:[1,0,3,2] row_mask:0xf bank_mask:0xf
	s_mov_b64 vcc, s[62:63]
	v_cndmask_b32_dpp v52, v48, v52, vcc quad_perm:[1,0,3,2] row_mask:0xf bank_mask:0xf
	v_cndmask_b32_dpp v53, v49, v53, vcc quad_perm:[1,0,3,2] row_mask:0xf bank_mask:0xf
	v_cndmask_b32_dpp v54, v50, v54, vcc quad_perm:[1,0,3,2] row_mask:0xf bank_mask:0xf
	v_cndmask_b32_dpp v55, v51, v55, vcc quad_perm:[1,0,3,2] row_mask:0xf bank_mask:0xf
	global_store_dwordx4 v171, v[84:87], s[92:93]
	global_store_dwordx4 v171, v[52:55], s[92:93] offset:2048
	v_mov_b32_e32 v34, v173
	s_add_u32 s84, s58, 0x58000
	s_addc_u32 s85, s59, 0
	s_add_u32 s86, s74, 0x2c000
	s_addc_u32 s87, s75, 0
	global_load_dwordx4 v[36:39], v171, s[84:85]
	global_load_dwordx2 v[40:41], v170, s[86:87]
	global_load_dwordx4 v[58:61], v171, s[84:85] offset:2048
	global_load_dwordx2 v[62:63], v170, s[86:87] offset:1024
	s_waitcnt vmcnt(10)
	s_mov_b64 vcc, s[66:67]
	v_cndmask_b32_dpp v48, v74, v68, vcc quad_perm:[1,0,3,2] row_mask:0xf bank_mask:0xf
	v_cndmask_b32_dpp v49, v75, v69, vcc quad_perm:[1,0,3,2] row_mask:0xf bank_mask:0xf
	v_cndmask_b32_dpp v50, v76, v70, vcc quad_perm:[1,0,3,2] row_mask:0xf bank_mask:0xf
	v_cndmask_b32_dpp v51, v77, v71, vcc quad_perm:[1,0,3,2] row_mask:0xf bank_mask:0xf
	s_mov_b64 vcc, s[62:63]
	v_cndmask_b32_dpp v74, v68, v74, vcc quad_perm:[1,0,3,2] row_mask:0xf bank_mask:0xf
	v_cndmask_b32_dpp v75, v69, v75, vcc quad_perm:[1,0,3,2] row_mask:0xf bank_mask:0xf
	v_cndmask_b32_dpp v76, v70, v76, vcc quad_perm:[1,0,3,2] row_mask:0xf bank_mask:0xf
	v_cndmask_b32_dpp v77, v71, v77, vcc quad_perm:[1,0,3,2] row_mask:0xf bank_mask:0xf
	s_mov_b64 vcc, s[66:67]
	v_cndmask_b32_dpp v52, v78, v72, vcc quad_perm:[1,0,3,2] row_mask:0xf bank_mask:0xf
	v_cndmask_b32_dpp v53, v79, v73, vcc quad_perm:[1,0,3,2] row_mask:0xf bank_mask:0xf
	s_mov_b64 vcc, s[62:63]
	v_cndmask_b32_dpp v78, v72, v78, vcc quad_perm:[1,0,3,2] row_mask:0xf bank_mask:0xf
	v_cndmask_b32_dpp v79, v73, v79, vcc quad_perm:[1,0,3,2] row_mask:0xf bank_mask:0xf
	v_perm_b32 v44, v48, v52, s32
	v_perm_b32 v45, v48, v52, s8
	v_perm_b32 v46, v49, v52, s61
	v_perm_b32 v47, v49, v52, s98
	v_pk_fma_f32 v[30:31], v[30:31], v[174:175], v[44:45]
	v_pk_fma_f32 v[32:33], v[32:33], v[176:177], v[46:47]
	v_perm_b32 v44, v50, v53, s32
	v_perm_b32 v45, v50, v53, s8
	v_perm_b32 v46, v51, v53, s61
	v_perm_b32 v47, v51, v53, s98
	v_pk_fma_f32 v[26:27], v[26:27], v[178:179], v[44:45]
	v_pk_fma_f32 v[28:29], v[28:29], v[180:181], v[46:47]
	v_perm_b32 v44, v74, v78, s32
	v_perm_b32 v45, v74, v78, s8
	v_perm_b32 v46, v75, v78, s61
	v_perm_b32 v47, v75, v78, s98
	v_pk_fma_f32 v[22:23], v[22:23], v[182:183], v[44:45]
	v_pk_fma_f32 v[24:25], v[24:25], v[184:185], v[46:47]
	v_perm_b32 v44, v76, v79, s32
	v_perm_b32 v45, v76, v79, s8
	v_perm_b32 v46, v77, v79, s61
	v_perm_b32 v47, v77, v79, s98
	v_pk_fma_f32 v[18:19], v[18:19], v[186:187], v[44:45]
	v_pk_fma_f32 v[20:21], v[20:21], v[188:189], v[46:47]
	v_mul_f32_e32 v44, v31, v31
	v_mul_f32_e32 v45, v33, v33
	v_mul_f32_e32 v46, v27, v27
	v_mul_f32_e32 v47, v29, v29
	v_fmac_f32_e32 v44, v30, v30
	v_fmac_f32_e32 v45, v32, v32
	v_fmac_f32_e32 v46, v26, v26
	v_fmac_f32_e32 v47, v28, v28
	v_add_f32_e32 v44, v44, v45
	v_add_f32_e32 v46, v46, v47
	v_add_f32_e32 v173, v44, v46
	v_add_u32_e32 v44, 0x80, v30
	v_add_u32_e32 v45, 0x80, v31
	v_add_u32_e32 v46, 0x80, v32
	v_add_u32_e32 v47, 0x80, v33
	v_perm_b32 v48, v45, v44, s78
	v_perm_b32 v49, v47, v46, s78
	v_perm_b32 v42, v45, v44, s79
	v_perm_b32 v43, v47, v46, s79
	v_perm_b32 v56, v43, v42, s60
	v_add_u32_e32 v44, 0x80, v26
	v_add_u32_e32 v45, 0x80, v27
	v_add_u32_e32 v46, 0x80, v28
	v_add_u32_e32 v47, 0x80, v29
	v_perm_b32 v50, v45, v44, s78
	v_perm_b32 v51, v47, v46, s78
	v_perm_b32 v42, v45, v44, s79
	v_perm_b32 v43, v47, v46, s79
	v_perm_b32 v57, v43, v42, s60
	v_mul_f32_e32 v44, v23, v23
	v_mul_f32_e32 v45, v25, v25
	v_mul_f32_e32 v46, v19, v19
	v_mul_f32_e32 v47, v21, v21
	v_fmac_f32_e32 v44, v22, v22
	v_fmac_f32_e32 v45, v24, v24
	v_fmac_f32_e32 v46, v18, v18
	v_fmac_f32_e32 v47, v20, v20
	v_add_f32_e32 v44, v44, v45
	v_add_f32_e32 v46, v46, v47
	v_add_f32_e32 v44, v44, v46
	v_add_f32_e32 v173, v173, v44
	v_add_u32_e32 v44, 0x80, v22
	v_add_u32_e32 v45, 0x80, v23
	v_add_u32_e32 v46, 0x80, v24
	v_add_u32_e32 v47, 0x80, v25
	v_perm_b32 v52, v45, v44, s78
	v_perm_b32 v53, v47, v46, s78
	v_perm_b32 v42, v45, v44, s79
	v_perm_b32 v43, v47, v46, s79
	v_perm_b32 v168, v43, v42, s60
	v_add_u32_e32 v44, 0x80, v18
	v_add_u32_e32 v45, 0x80, v19
	v_add_u32_e32 v46, 0x80, v20
	v_add_u32_e32 v47, 0x80, v21
	v_perm_b32 v54, v45, v44, s78
	v_perm_b32 v55, v47, v46, s78
	v_perm_b32 v42, v45, v44, s79
	v_perm_b32 v43, v47, v46, s79
	v_perm_b32 v169, v43, v42, s60
	s_mov_b64 vcc, s[66:67]
	v_cndmask_b32_dpp v68, v52, v48, vcc quad_perm:[1,0,3,2] row_mask:0xf bank_mask:0xf
	v_cndmask_b32_dpp v69, v53, v49, vcc quad_perm:[1,0,3,2] row_mask:0xf bank_mask:0xf
	v_cndmask_b32_dpp v70, v54, v50, vcc quad_perm:[1,0,3,2] row_mask:0xf bank_mask:0xf
	v_cndmask_b32_dpp v71, v55, v51, vcc quad_perm:[1,0,3,2] row_mask:0xf bank_mask:0xf
	s_mov_b64 vcc, s[62:63]
	v_cndmask_b32_dpp v52, v48, v52, vcc quad_perm:[1,0,3,2] row_mask:0xf bank_mask:0xf
	v_cndmask_b32_dpp v53, v49, v53, vcc quad_perm:[1,0,3,2] row_mask:0xf bank_mask:0xf
	v_cndmask_b32_dpp v54, v50, v54, vcc quad_perm:[1,0,3,2] row_mask:0xf bank_mask:0xf
	v_cndmask_b32_dpp v55, v51, v55, vcc quad_perm:[1,0,3,2] row_mask:0xf bank_mask:0xf
	s_mov_b64 vcc, s[66:67]
	v_cndmask_b32_dpp v74, v168, v56, vcc quad_perm:[1,0,3,2] row_mask:0xf bank_mask:0xf
	v_cndmask_b32_dpp v75, v169, v57, vcc quad_perm:[1,0,3,2] row_mask:0xf bank_mask:0xf
	s_mov_b64 vcc, s[62:63]
	v_cndmask_b32_dpp v168, v56, v168, vcc quad_perm:[1,0,3,2] row_mask:0xf bank_mask:0xf
	v_cndmask_b32_dpp v169, v57, v169, vcc quad_perm:[1,0,3,2] row_mask:0xf bank_mask:0xf
	s_add_u32 s88, s58, 0x50000
	s_addc_u32 s89, s59, 0
	s_add_u32 s90, s74, 0x28000
	s_addc_u32 s91, s75, 0
	global_store_dwordx4 v171, v[68:71], s[88:89]
	global_store_dwordx4 v171, v[52:55], s[88:89] offset:2048
	global_store_dwordx2 v170, v[74:75], s[90:91]
	global_store_dwordx2 v170, v[168:169], s[90:91] offset:1024
	s_add_u32 s92, s96, 0x50000
	s_addc_u32 s93, s97, 0
	v_pk_mul_f32 v[30:31], v[190:191], v[30:31]
	v_pk_mul_f32 v[32:33], v[192:193], v[32:33]
	v_pk_mul_f32 v[26:27], v[210:211], v[26:27]
	v_pk_mul_f32 v[28:29], v[212:213], v[28:29]
	v_cvt_pk_bf16_f32 v48, v30, v31
	v_cvt_pk_bf16_f32 v49, v32, v33
	v_cvt_pk_bf16_f32 v50, v26, v27
	v_cvt_pk_bf16_f32 v51, v28, v29
	v_pk_mul_f32 v[22:23], v[214:215], v[22:23]
	v_pk_mul_f32 v[24:25], v[216:217], v[24:25]
	v_pk_mul_f32 v[18:19], v[218:219], v[18:19]
	v_pk_mul_f32 v[20:21], v[220:221], v[20:21]
	v_cvt_pk_bf16_f32 v52, v22, v23
	v_cvt_pk_bf16_f32 v53, v24, v25
	v_cvt_pk_bf16_f32 v54, v18, v19
	v_cvt_pk_bf16_f32 v55, v20, v21
	s_mov_b64 vcc, s[66:67]
	v_cndmask_b32_dpp v68, v52, v48, vcc quad_perm:[1,0,3,2] row_mask:0xf bank_mask:0xf
	v_cndmask_b32_dpp v69, v53, v49, vcc quad_perm:[1,0,3,2] row_mask:0xf bank_mask:0xf
	v_cndmask_b32_dpp v70, v54, v50, vcc quad_perm:[1,0,3,2] row_mask:0xf bank_mask:0xf
	v_cndmask_b32_dpp v71, v55, v51, vcc quad_perm:[1,0,3,2] row_mask:0xf bank_mask:0xf
	s_mov_b64 vcc, s[62:63]
	v_cndmask_b32_dpp v52, v48, v52, vcc quad_perm:[1,0,3,2] row_mask:0xf bank_mask:0xf
	v_cndmask_b32_dpp v53, v49, v53, vcc quad_perm:[1,0,3,2] row_mask:0xf bank_mask:0xf
	v_cndmask_b32_dpp v54, v50, v54, vcc quad_perm:[1,0,3,2] row_mask:0xf bank_mask:0xf
	v_cndmask_b32_dpp v55, v51, v55, vcc quad_perm:[1,0,3,2] row_mask:0xf bank_mask:0xf
	global_store_dwordx4 v171, v[68:71], s[92:93]
	global_store_dwordx4 v171, v[52:55], s[92:93] offset:2048
	v_mov_b32_e32 v18, v173
	s_waitcnt vmcnt(6)
	s_mov_b64 vcc, s[66:67]
	v_cndmask_b32_dpp v48, v58, v36, vcc quad_perm:[1,0,3,2] row_mask:0xf bank_mask:0xf
	v_cndmask_b32_dpp v49, v59, v37, vcc quad_perm:[1,0,3,2] row_mask:0xf bank_mask:0xf
	v_cndmask_b32_dpp v50, v60, v38, vcc quad_perm:[1,0,3,2] row_mask:0xf bank_mask:0xf
	v_cndmask_b32_dpp v51, v61, v39, vcc quad_perm:[1,0,3,2] row_mask:0xf bank_mask:0xf
	s_mov_b64 vcc, s[62:63]
	v_cndmask_b32_dpp v58, v36, v58, vcc quad_perm:[1,0,3,2] row_mask:0xf bank_mask:0xf
	v_cndmask_b32_dpp v59, v37, v59, vcc quad_perm:[1,0,3,2] row_mask:0xf bank_mask:0xf
	v_cndmask_b32_dpp v60, v38, v60, vcc quad_perm:[1,0,3,2] row_mask:0xf bank_mask:0xf
	v_cndmask_b32_dpp v61, v39, v61, vcc quad_perm:[1,0,3,2] row_mask:0xf bank_mask:0xf
	s_mov_b64 vcc, s[66:67]
	v_cndmask_b32_dpp v52, v62, v40, vcc quad_perm:[1,0,3,2] row_mask:0xf bank_mask:0xf
	v_cndmask_b32_dpp v53, v63, v41, vcc quad_perm:[1,0,3,2] row_mask:0xf bank_mask:0xf
	s_mov_b64 vcc, s[62:63]
	v_cndmask_b32_dpp v62, v40, v62, vcc quad_perm:[1,0,3,2] row_mask:0xf bank_mask:0xf
	v_cndmask_b32_dpp v63, v41, v63, vcc quad_perm:[1,0,3,2] row_mask:0xf bank_mask:0xf
	v_perm_b32 v44, v48, v52, s32
	v_perm_b32 v45, v48, v52, s8
	v_perm_b32 v46, v49, v52, s61
	v_perm_b32 v47, v49, v52, s98
	v_pk_fma_f32 v[14:15], v[14:15], v[174:175], v[44:45]
	v_pk_fma_f32 v[16:17], v[16:17], v[176:177], v[46:47]
	v_perm_b32 v44, v50, v53, s32
	v_perm_b32 v45, v50, v53, s8
	v_perm_b32 v46, v51, v53, s61
	v_perm_b32 v47, v51, v53, s98
	v_pk_fma_f32 v[10:11], v[10:11], v[178:179], v[44:45]
	v_pk_fma_f32 v[12:13], v[12:13], v[180:181], v[46:47]
	v_perm_b32 v44, v58, v62, s32
	v_perm_b32 v45, v58, v62, s8
	v_perm_b32 v46, v59, v62, s61
	v_perm_b32 v47, v59, v62, s98
	v_pk_fma_f32 v[6:7], v[6:7], v[182:183], v[44:45]
	v_pk_fma_f32 v[8:9], v[8:9], v[184:185], v[46:47]
	v_perm_b32 v44, v60, v63, s32
	v_perm_b32 v45, v60, v63, s8
	v_perm_b32 v46, v61, v63, s61
	v_perm_b32 v47, v61, v63, s98
	v_pk_fma_f32 v[2:3], v[2:3], v[186:187], v[44:45]
	v_pk_fma_f32 v[4:5], v[4:5], v[188:189], v[46:47]
	v_mul_f32_e32 v44, v15, v15
	v_mul_f32_e32 v45, v17, v17
	v_mul_f32_e32 v46, v11, v11
	v_mul_f32_e32 v47, v13, v13
	v_fmac_f32_e32 v44, v14, v14
	v_fmac_f32_e32 v45, v16, v16
	v_fmac_f32_e32 v46, v10, v10
	v_fmac_f32_e32 v47, v12, v12
	v_add_f32_e32 v44, v44, v45
	v_add_f32_e32 v46, v46, v47
	v_add_f32_e32 v173, v44, v46
	v_add_u32_e32 v44, 0x80, v14
	v_add_u32_e32 v45, 0x80, v15
	v_add_u32_e32 v46, 0x80, v16
	v_add_u32_e32 v47, 0x80, v17
	v_perm_b32 v48, v45, v44, s78
	v_perm_b32 v49, v47, v46, s78
	v_perm_b32 v42, v45, v44, s79
	v_perm_b32 v43, v47, v46, s79
	v_perm_b32 v56, v43, v42, s60
	v_add_u32_e32 v44, 0x80, v10
	v_add_u32_e32 v45, 0x80, v11
	v_add_u32_e32 v46, 0x80, v12
	v_add_u32_e32 v47, 0x80, v13
	v_perm_b32 v50, v45, v44, s78
	v_perm_b32 v51, v47, v46, s78
	v_perm_b32 v42, v45, v44, s79
	v_perm_b32 v43, v47, v46, s79
	v_perm_b32 v57, v43, v42, s60
	v_mul_f32_e32 v44, v7, v7
	v_mul_f32_e32 v45, v9, v9
	v_mul_f32_e32 v46, v3, v3
	v_mul_f32_e32 v47, v5, v5
	v_fmac_f32_e32 v44, v6, v6
	v_fmac_f32_e32 v45, v8, v8
	v_fmac_f32_e32 v46, v2, v2
	v_fmac_f32_e32 v47, v4, v4
	v_add_f32_e32 v44, v44, v45
	v_add_f32_e32 v46, v46, v47
	v_add_f32_e32 v44, v44, v46
	v_add_f32_e32 v173, v173, v44
	v_add_u32_e32 v44, 0x80, v6
	v_add_u32_e32 v45, 0x80, v7
	v_add_u32_e32 v46, 0x80, v8
	v_add_u32_e32 v47, 0x80, v9
	v_perm_b32 v52, v45, v44, s78
	v_perm_b32 v53, v47, v46, s78
	v_perm_b32 v42, v45, v44, s79
	v_perm_b32 v43, v47, v46, s79
	v_perm_b32 v168, v43, v42, s60
	v_add_u32_e32 v44, 0x80, v2
	v_add_u32_e32 v45, 0x80, v3
	v_add_u32_e32 v46, 0x80, v4
	v_add_u32_e32 v47, 0x80, v5
	v_perm_b32 v54, v45, v44, s78
	v_perm_b32 v55, v47, v46, s78
	v_perm_b32 v42, v45, v44, s79
	v_perm_b32 v43, v47, v46, s79
	v_perm_b32 v169, v43, v42, s60
	s_mov_b64 vcc, s[66:67]
	v_cndmask_b32_dpp v36, v52, v48, vcc quad_perm:[1,0,3,2] row_mask:0xf bank_mask:0xf
	v_cndmask_b32_dpp v37, v53, v49, vcc quad_perm:[1,0,3,2] row_mask:0xf bank_mask:0xf
	v_cndmask_b32_dpp v38, v54, v50, vcc quad_perm:[1,0,3,2] row_mask:0xf bank_mask:0xf
	v_cndmask_b32_dpp v39, v55, v51, vcc quad_perm:[1,0,3,2] row_mask:0xf bank_mask:0xf
	s_mov_b64 vcc, s[62:63]
	v_cndmask_b32_dpp v52, v48, v52, vcc quad_perm:[1,0,3,2] row_mask:0xf bank_mask:0xf
	v_cndmask_b32_dpp v53, v49, v53, vcc quad_perm:[1,0,3,2] row_mask:0xf bank_mask:0xf
	v_cndmask_b32_dpp v54, v50, v54, vcc quad_perm:[1,0,3,2] row_mask:0xf bank_mask:0xf
	v_cndmask_b32_dpp v55, v51, v55, vcc quad_perm:[1,0,3,2] row_mask:0xf bank_mask:0xf
	s_mov_b64 vcc, s[66:67]
	v_cndmask_b32_dpp v58, v168, v56, vcc quad_perm:[1,0,3,2] row_mask:0xf bank_mask:0xf
	v_cndmask_b32_dpp v59, v169, v57, vcc quad_perm:[1,0,3,2] row_mask:0xf bank_mask:0xf
	s_mov_b64 vcc, s[62:63]
	v_cndmask_b32_dpp v168, v56, v168, vcc quad_perm:[1,0,3,2] row_mask:0xf bank_mask:0xf
	v_cndmask_b32_dpp v169, v57, v169, vcc quad_perm:[1,0,3,2] row_mask:0xf bank_mask:0xf
	s_add_u32 s88, s58, 0x58000
	s_addc_u32 s89, s59, 0
	s_add_u32 s90, s74, 0x2c000
	s_addc_u32 s91, s75, 0
	global_store_dwordx4 v171, v[36:39], s[88:89]
	global_store_dwordx4 v171, v[52:55], s[88:89] offset:2048
	global_store_dwordx2 v170, v[58:59], s[90:91]
	global_store_dwordx2 v170, v[168:169], s[90:91] offset:1024
	s_add_u32 s92, s96, 0x58000
	s_addc_u32 s93, s97, 0
	v_pk_mul_f32 v[14:15], v[190:191], v[14:15]
	v_pk_mul_f32 v[16:17], v[192:193], v[16:17]
	v_pk_mul_f32 v[10:11], v[210:211], v[10:11]
	v_pk_mul_f32 v[12:13], v[212:213], v[12:13]
	v_cvt_pk_bf16_f32 v48, v14, v15
	v_cvt_pk_bf16_f32 v49, v16, v17
	v_cvt_pk_bf16_f32 v50, v10, v11
	v_cvt_pk_bf16_f32 v51, v12, v13
	v_pk_mul_f32 v[6:7], v[214:215], v[6:7]
	v_pk_mul_f32 v[8:9], v[216:217], v[8:9]
	v_pk_mul_f32 v[2:3], v[218:219], v[2:3]
	v_pk_mul_f32 v[4:5], v[220:221], v[4:5]
	v_cvt_pk_bf16_f32 v52, v6, v7
	v_cvt_pk_bf16_f32 v53, v8, v9
	v_cvt_pk_bf16_f32 v54, v2, v3
	v_cvt_pk_bf16_f32 v55, v4, v5
	s_mov_b64 vcc, s[66:67]
	v_cndmask_b32_dpp v36, v52, v48, vcc quad_perm:[1,0,3,2] row_mask:0xf bank_mask:0xf
	v_cndmask_b32_dpp v37, v53, v49, vcc quad_perm:[1,0,3,2] row_mask:0xf bank_mask:0xf
	v_cndmask_b32_dpp v38, v54, v50, vcc quad_perm:[1,0,3,2] row_mask:0xf bank_mask:0xf
	v_cndmask_b32_dpp v39, v55, v51, vcc quad_perm:[1,0,3,2] row_mask:0xf bank_mask:0xf
	s_mov_b64 vcc, s[62:63]
	v_cndmask_b32_dpp v52, v48, v52, vcc quad_perm:[1,0,3,2] row_mask:0xf bank_mask:0xf
	v_cndmask_b32_dpp v53, v49, v53, vcc quad_perm:[1,0,3,2] row_mask:0xf bank_mask:0xf
	v_cndmask_b32_dpp v54, v50, v54, vcc quad_perm:[1,0,3,2] row_mask:0xf bank_mask:0xf
	v_cndmask_b32_dpp v55, v51, v55, vcc quad_perm:[1,0,3,2] row_mask:0xf bank_mask:0xf
	global_store_dwordx4 v171, v[36:39], s[92:93]
	global_store_dwordx4 v171, v[52:55], s[92:93] offset:2048
	v_mov_b32_e32 v2, v173
	v_mbcnt_lo_u32_b32 v3, -1, 0
	v_mbcnt_hi_u32_b32 v3, -1, v3
	v_xor_b32_e32 v4, 16, v3
	v_xor_b32_e32 v5, 32, v3
	v_lshlrev_b32_e32 v4, 2, v4
	v_lshlrev_b32_e32 v5, 2, v5
	v_cmp_gt_u32_e64 s[34:35], 16, v3
	ds_bpermute_b32 v6, v4, v130
	ds_bpermute_b32 v7, v4, v114
	ds_bpermute_b32 v8, v4, v98
	ds_bpermute_b32 v9, v4, v82
	ds_bpermute_b32 v10, v4, v66
	ds_bpermute_b32 v11, v4, v34
	ds_bpermute_b32 v12, v4, v18
	ds_bpermute_b32 v13, v4, v2
	s_waitcnt lgkmcnt(0)
	v_add_f32_e32 v130, v130, v6
	v_add_f32_e32 v114, v114, v7
	v_add_f32_e32 v98, v98, v8
	v_add_f32_e32 v82, v82, v9
	v_add_f32_e32 v66, v66, v10
	v_add_f32_e32 v34, v34, v11
	v_add_f32_e32 v18, v18, v12
	v_add_f32_e32 v2, v2, v13
	ds_bpermute_b32 v6, v5, v130
	ds_bpermute_b32 v7, v5, v114
	ds_bpermute_b32 v8, v5, v98
	ds_bpermute_b32 v9, v5, v82
	ds_bpermute_b32 v10, v5, v66
	ds_bpermute_b32 v11, v5, v34
	ds_bpermute_b32 v12, v5, v18
	ds_bpermute_b32 v13, v5, v2
	s_waitcnt lgkmcnt(0)
	v_add_f32_e32 v130, v130, v6
	v_add_f32_e32 v114, v114, v7
	v_add_f32_e32 v98, v98, v8
	v_add_f32_e32 v82, v82, v9
	v_add_f32_e32 v66, v66, v10
	v_add_f32_e32 v34, v34, v11
	v_add_f32_e32 v18, v18, v12
	v_add_f32_e32 v2, v2, v13
	v_readlane_b32 s70, v244, 53
	v_readlane_b32 s71, v244, 54
	v_lshlrev_b32_e32 v3, 6, v194
	s_lshl_b32 s94, s54, 14
	s_lshl_b32 s95, s4, 4
	s_add_u32 s94, s94, s95
	s_lshl_b32 s95, s51, 2
	s_add_u32 s94, s94, s95
	s_add_u32 s94, s70, s94
	s_addc_u32 s95, s71, 0
	s_and_saveexec_b64 s[36:37], s[34:35]
	global_store_dword v3, v130, s[94:95]
	s_add_u32 s84, s94, 0x400
	s_addc_u32 s85, s95, 0
	global_store_dword v3, v114, s[84:85]
	s_add_u32 s84, s94, 0x800
	s_addc_u32 s85, s95, 0
	global_store_dword v3, v98, s[84:85]
	s_add_u32 s84, s94, 0xc00
	s_addc_u32 s85, s95, 0
	global_store_dword v3, v82, s[84:85]
	s_add_u32 s84, s94, 0x2000
	s_addc_u32 s85, s95, 0
	global_store_dword v3, v66, s[84:85]
	s_add_u32 s84, s94, 0x2400
	s_addc_u32 s85, s95, 0
	global_store_dword v3, v34, s[84:85]
	s_add_u32 s84, s94, 0x2800
	s_addc_u32 s85, s95, 0
	global_store_dword v3, v18, s[84:85]
	s_add_u32 s84, s94, 0x2c00
	s_addc_u32 s85, s95, 0
	global_store_dword v3, v2, s[84:85]
	s_or_b64 exec, exec, s[36:37]
	v_readlane_b32 s56, v246, 3
	v_readlane_b32 s57, v246, 4
	s_branch .LBB0_1568
